# k25: k20 + pass C gate-prefetch address arithmetic emitted once per shared address (about 420 fewer VALU per unit pair)
# baseline (speedup 1.0000x reference)
; template <bool GLA>
; __device__ __forceinline__ void chunk_tile(const ChunkRaw& raw, const bf16x8 (&wfr)[2], const f32x4 (&bfr)[2], int h, int it, int row, int kq, float lg, float (&carry)[8], float (&bq)[8], float (&qv)[8], float (&kv)[8]) {
;     ...
;     if (GLA) {
;         const u32x4 gsel = (kq == 0) ? raw.g0 : (kq == 1) ? raw.g1 : (u32x4){0u, 0u, 0u, 0u};
;         const bf16x8 gfr = __builtin_bit_cast(bf16x8, gsel);
;         const f32x4 z0 = __builtin_amdgcn_mfma_f32_16x16x32_bf16(wfr[0], gfr, bfr[0], 0, 0, 0), z1 = __builtin_amdgcn_mfma_f32_16x16x32_bf16(wfr[1], gfr, bfr[1], 0, 0, 0);
;         const float z[8] = {z0[0], z0[1], z0[2], z0[3], z1[0], z1[1], z1[2], z1[3]};
; #pragma unroll
;         for (int j = 0; j < 8; ++j) {
;             float la = (fminf(z[j], 0.f) - __logf(1.0f + __expf(-fabsf(z[j])))) * (1.0f / 16.0f);
;             la += __int_as_float(__builtin_amdgcn_update_dpp(0, __float_as_int(la), 0x111, 0xf, 0xf, false));
;             la += __int_as_float(__builtin_amdgcn_update_dpp(0, __float_as_int(la), 0x112, 0xf, 0xf, false));
;             la += __int_as_float(__builtin_amdgcn_update_dpp(0, __float_as_int(la), 0x114, 0xf, 0xf, false));
;             la += __int_as_float(__builtin_amdgcn_update_dpp(0, __float_as_int(la), 0x118, 0xf, 0xf, false));
;             bq[j] = la + carry[j];
;             carry[j] += __int_as_float(__builtin_amdgcn_ds_bpermute((16 * kq + 15) * 4, __float_as_int(la)));
;             qv[j] = q[j] * qs; kv[j] = k[j];
; template <bool GLA>
; __device__ __forceinline__ void chunk_pass_c(const ChunkIn& ci, const float* wgl, int unit, unsigned char* wl, int lane, const float* Sb, const float* ng, bf16_t* omix) {
;     ...
; #pragma unroll
;     for (int it = 0; it < 4; ++it) {
;         float bq[8], qv[8], kv[8];
;         chunk_tile<GLA>(raw[it], wfr, bfr, h, it, row, kq, lg, carry, bq, qv, kv);
;         float a[8], bneg[8], cpos[8], dneg[8];
; #pragma unroll
;         for (int j = 0; j < 8; ++j) { const float eb = __expf(bq[j]), enb = __expf(-bq[j]); a[j] = qv[j] * eb; bneg[j] = kv[j] * enb; cpos[j] = qv[j] * enb; dneg[j] = kv[j] * eb; }
;         qf[it] = __builtin_bit_cast(bf16x8, (u32x4){cvtpk(a[0], a[1]), cvtpk(a[2], a[3]), cvtpk(a[4], a[5]), cvtpk(a[6], a[7])});
;         kf[it] = __builtin_bit_cast(bf16x8, (u32x4){cvtpk(bneg[0], bneg[1]), cvtpk(bneg[2], bneg[3]), cvtpk(bneg[4], bneg[5]), cvtpk(bneg[6], bneg[7])});
.LBB0_213:
	s_andn2_saveexec_b64 s[6:7], s[6:7]
	s_or_b64 exec, exec, s[6:7]
	s_waitcnt vmcnt(1)
	v_mfma_f32_16x16x32_bf16 v[16:19], v[16:19], v[4:7], v[8:11]
	s_waitcnt vmcnt(0)
	v_lshlrev_b32_e32 v0, 16, v82
	v_and_b32_e32 v1, 0xffff0000, v82
	s_mov_b32 s8, 0x3e3504f3
	v_pk_mul_f32 v[138:139], v[0:1], s[8:9] op_sel_hi:[1,0]
	v_lshlrev_b32_e32 v0, 16, v83
	v_and_b32_e32 v1, 0xffff0000, v83
	s_mov_b32 s7, 0xbfb8aa3b
	v_pk_mul_f32 v[82:83], v[0:1], s[8:9] op_sel_hi:[1,0]
	v_lshlrev_b32_e32 v0, 16, v78
	v_and_b32_e32 v1, 0xffff0000, v78
	v_mfma_f32_16x16x32_bf16 v[10:13], v[20:23], v[4:7], v[12:15]
	v_mul_f32_e64 v5, |v16|, s7
	v_pk_mul_f32 v[126:127], v[0:1], s[8:9] op_sel_hi:[1,0]
	v_lshlrev_b32_e32 v0, 16, v79
	v_and_b32_e32 v1, 0xffff0000, v79
	v_exp_f32_e32 v5, v5
	v_pk_mul_f32 v[118:119], v[0:1], s[8:9] op_sel_hi:[1,0]
	v_lshlrev_b32_e32 v0, 16, v70
	v_and_b32_e32 v1, 0xffff0000, v70
	v_pk_mul_f32 v[140:141], v[0:1], s[8:9] op_sel_hi:[1,0]
	v_lshlrev_b32_e32 v0, 16, v71
	v_and_b32_e32 v1, 0xffff0000, v71
	v_lshlrev_b32_e32 v124, 16, v72
	v_and_b32_e32 v125, 0xffff0000, v72
	v_lshlrev_b32_e32 v26, 16, v73
	v_and_b32_e32 v27, 0xffff0000, v73
	v_pk_mul_f32 v[72:73], v[0:1], s[8:9] op_sel_hi:[1,0]
	v_lshlrev_b32_e32 v0, 16, v68
	v_and_b32_e32 v1, 0xffff0000, v68
	v_pk_mul_f32 v[70:71], v[0:1], s[8:9] op_sel_hi:[1,0]
	v_lshlrev_b32_e32 v0, 16, v69
	v_and_b32_e32 v1, 0xffff0000, v69
	v_add_f32_e32 v5, 1.0, v5
	v_pk_mul_f32 v[30:31], v[0:1], s[8:9] op_sel_hi:[1,0]
	v_add_f32_e32 v0, 0, v53
	v_cmp_gt_f32_e32 vcc, s96, v5
	v_mul_f32_e32 v1, 0x3fb8aa3b, v0
	v_exp_f32_e32 v68, v1
	v_cndmask_b32_e64 v6, 0, 32, vcc
	v_add_f32_e32 v1, 0, v55
	v_ldexp_f32 v5, v5, v6
	v_mul_f32_e32 v2, 0x3fb8aa3b, v1
	v_log_f32_e32 v5, v5
	v_exp_f32_e32 v69, v2
	v_add_f32_e32 v2, 0, v63
	v_mul_f32_e32 v3, 0x3fb8aa3b, v2
	v_lshlrev_b32_e32 v136, 16, v76
	v_and_b32_e32 v137, 0xffff0000, v76
	v_exp_f32_e32 v76, v3
	v_add_f32_e32 v3, 0, v75
	v_mul_f32_e32 v53, 0x3fb8aa3b, v3
	v_mul_f32_e32 v6, 0x3f317217, v5
	v_lshlrev_b32_e32 v78, 16, v77
	v_and_b32_e32 v79, 0xffff0000, v77
	v_exp_f32_e32 v77, v53
	v_add_f32_e32 v53, 0, v81
	v_fma_f32 v6, v5, s3, -v6
	v_mul_f32_e32 v55, 0x3fb8aa3b, v53
	v_fmac_f32_e32 v6, 0x3377d1cf, v5
	s_mov_b32 s6, 0x7f800000
	v_lshlrev_b32_e32 v122, 16, v84
	v_and_b32_e32 v123, 0xffff0000, v84
	v_exp_f32_e32 v84, v55
	v_add_f32_e32 v55, 0, v91
	v_fmac_f32_e32 v6, 0x3f317217, v5
	v_cmp_lt_f32_e64 s[42:43], |v5|, s6
	v_mul_f32_e32 v63, 0x3fb8aa3b, v55
	v_max_f32_e32 v4, v16, v16
	v_cndmask_b32_e64 v5, v5, v6, s[42:43]
	v_cndmask_b32_e32 v6, 0, v237, vcc
	v_lshlrev_b32_e32 v116, 16, v85
	v_and_b32_e32 v117, 0xffff0000, v85
	v_exp_f32_e32 v85, v63
	v_add_f32_e32 v63, 0, v93
	v_min_f32_e32 v4, 0, v4
	v_sub_f32_e32 v5, v5, v6
	v_mul_f32_e32 v75, 0x3fb8aa3b, v63
	v_sub_f32_e32 v4, v4, v5
	v_exp_f32_e32 v144, v75
	v_add_f32_e32 v75, 0, v99
	v_mul_f32_e32 v6, 0x3d800000, v4
	v_mov_b32_e32 v5, v211
	v_mul_f32_e32 v81, 0x3fb8aa3b, v75
	v_exp_f32_e32 v145, v81
	v_mov_b32_dpp v5, v6 row_shr:1 row_mask:0xf bank_mask:0xf
	v_fmac_f32_e32 v5, 0x3d800000, v4
	v_mov_b32_e32 v81, v211
	v_mov_b32_e32 v4, v211
	v_mov_b32_e32 v93, v211
	v_mov_b32_dpp v81, v5 row_shr:2 row_mask:0xf bank_mask:0xf
	s_waitcnt lgkmcnt(14)
	v_pk_add_f32 v[4:5], v[4:5], v[80:81]
	v_mov_b32_e32 v99, v211
	v_mul_f32_e32 v0, 0xbfb8aa3b, v0
	v_mov_b32_dpp v93, v5 row_shr:4 row_mask:0xf bank_mask:0xf
	v_pk_add_f32 v[6:7], v[4:5], v[92:93]
	v_add_f32_e32 v4, v4, v89
	v_add_f32_e32 v5, v6, v133
	v_mul_f32_e32 v8, 0x3fb8aa3b, v5
	v_mul_f32_e32 v5, 0xbfb8aa3b, v5
	v_exp_f32_e32 v16, v5
	v_mul_f32_e32 v5, 0x3fb8aa3b, v4
	v_mul_f32_e32 v4, 0xbfb8aa3b, v4
	v_mov_b32_dpp v99, v7 row_shr:8 row_mask:0xf bank_mask:0xf
	v_exp_f32_e32 v20, v5
	v_exp_f32_e32 v22, v4
	s_waitcnt lgkmcnt(7)
	v_pk_add_f32 v[4:5], v[6:7], v[98:99]
	v_exp_f32_e32 v102, v0
	v_add_f32_e32 v14, v4, v5
	v_mul_f32_e64 v5, |v17|, s7
	v_exp_f32_e32 v5, v5
	v_mul_f32_e32 v0, 0xbfb8aa3b, v1
	v_exp_f32_e32 v103, v0
	v_mul_f32_e32 v0, 0xbfb8aa3b, v2
	v_add_f32_e32 v5, 1.0, v5
	v_exp_f32_e32 v104, v0
	v_mul_f32_e32 v0, 0xbfb8aa3b, v3
	v_cmp_gt_f32_e32 vcc, s96, v5
	v_exp_f32_e32 v105, v0
	v_mul_f32_e32 v0, 0xbfb8aa3b, v53
	v_cndmask_b32_e64 v6, 0, 32, vcc
	v_exp_f32_e32 v112, v0
	v_mul_f32_e32 v0, 0xbfb8aa3b, v55
	v_ldexp_f32 v5, v5, v6
	v_exp_f32_e32 v113, v0
	v_mul_f32_e32 v0, 0xbfb8aa3b, v63
	v_log_f32_e32 v5, v5
	v_exp_f32_e32 v148, v0
	v_mul_f32_e32 v0, 0xbfb8aa3b, v75
	v_exp_f32_e32 v149, v0
	v_lshlrev_b32_e32 v0, 16, v66
	v_and_b32_e32 v1, 0xffff0000, v66
	v_pk_mul_f32 v[2:3], v[68:69], v[0:1]
	v_mul_f32_e32 v6, 0x3f317217, v5
	v_cvt_pk_bf16_f32 v106, v2, v3
	v_lshlrev_b32_e32 v2, 16, v67
	v_and_b32_e32 v3, 0xffff0000, v67
	v_pk_mul_f32 v[0:1], v[102:103], v[0:1]
	v_pk_mul_f32 v[66:67], v[76:77], v[2:3]
	v_pk_mul_f32 v[2:3], v[104:105], v[2:3]
	v_fma_f32 v6, v5, s3, -v6
	v_cvt_pk_bf16_f32 v0, v0, v1
	v_cvt_pk_bf16_f32 v1, v2, v3
	v_lshlrev_b32_e32 v2, 16, v64
	v_and_b32_e32 v3, 0xffff0000, v64
	v_fmac_f32_e32 v6, 0x3377d1cf, v5
	v_cvt_pk_bf16_f32 v107, v66, v67
	v_pk_mul_f32 v[66:67], v[84:85], v[2:3]
	v_lshlrev_b32_e32 v64, 16, v65
	v_and_b32_e32 v65, 0xffff0000, v65
	v_fmac_f32_e32 v6, 0x3f317217, v5
	v_cmp_lt_f32_e64 s[42:43], |v5|, s6
	v_cvt_pk_bf16_f32 v108, v66, v67
	v_pk_mul_f32 v[2:3], v[112:113], v[2:3]
	v_pk_mul_f32 v[66:67], v[144:145], v[64:65]
	v_pk_mul_f32 v[64:65], v[148:149], v[64:65]
	v_max_f32_e32 v4, v17, v17
	v_cndmask_b32_e64 v5, v5, v6, s[42:43]
	v_cndmask_b32_e32 v6, 0, v237, vcc
	v_cvt_pk_bf16_f32 v2, v2, v3
	v_cvt_pk_bf16_f32 v3, v64, v65
	v_lshlrev_b32_e32 v64, 16, v60
	v_and_b32_e32 v65, 0xffff0000, v60
; __device__ __forceinline__ unsigned cvtpk(float lo, float hi) { f32x2_t v = {lo, hi}; bf16x2_t b = __builtin_convertvector(v, bf16x2_t); return __builtin_bit_cast(unsigned, b); }
; template <int X> __device__ __forceinline__ float swz_xor(float v) { return __int_as_float(__builtin_amdgcn_ds_swizzle(__float_as_int(v), (X << 10) | 0x1F)); }
; template <bool GLA>
; __device__ __forceinline__ void chunk_pass_c(const ChunkIn& ci, const float* wgl, int unit, unsigned char* wl, int lane, const float* Sb, const float* ng, bf16_t* omix) {
;     ...
; #pragma unroll
;     for (int it = 0; it < 4; ++it) {
;         float bq[8], qv[8], kv[8];
;         chunk_tile<GLA>(raw[it], wfr, bfr, h, it, row, kq, lg, carry, bq, qv, kv);
;         float a[8], bneg[8], cpos[8], dneg[8];
; #pragma unroll
;         for (int j = 0; j < 8; ++j) { const float eb = __expf(bq[j]), enb = __expf(-bq[j]); a[j] = qv[j] * eb; bneg[j] = kv[j] * enb; cpos[j] = qv[j] * enb; dneg[j] = kv[j] * eb; }
;         qf[it] = __builtin_bit_cast(bf16x8, (u32x4){cvtpk(a[0], a[1]), cvtpk(a[2], a[3]), cvtpk(a[4], a[5]), cvtpk(a[6], a[7])});
;         kf[it] = __builtin_bit_cast(bf16x8, (u32x4){cvtpk(bneg[0], bneg[1]), cvtpk(bneg[2], bneg[3]), cvtpk(bneg[4], bneg[5]), cvtpk(bneg[6], bneg[7])});
;         qb[it] = __builtin_bit_cast(bf16x8, (u32x4){cvtpk(cpos[0], cpos[1]), cvtpk(cpos[2], cpos[3]), cvtpk(cpos[4], cpos[5]), cvtpk(cpos[6], cpos[7])});
;         kb[it] = __builtin_bit_cast(bf16x8, (u32x4){cvtpk(dneg[0], dneg[1]), cvtpk(dneg[2], dneg[3]), cvtpk(dneg[4], dneg[5]), cvtpk(dneg[6], dneg[7])});
;         asm volatile("" ::: "memory");
;     }
;     __builtin_amdgcn_s_waitcnt(0); asm volatile("" ::: "memory");
;     ...
;         for (int r = 0; r < 4; ++r) {
;             ss[r] += swz_xor<1>(ss[r]); ss[r] += swz_xor<2>(ss[r]); ss[r] += swz_xor<4>(ss[r]); ss[r] += swz_xor<8>(ss[r]);
;             const float rs = rsqrtf(ss[r] * (1.0f / 64.0f) + EPS);
;             const int t = t0 + 16 * it + 4 * kq + r;
; #pragma unroll
;             for (int et = 0; et < 4; ++et) {
;                 const int e = 16 * et + row;
;                 const float gt = __uint_as_float((unsigned)ci.proj[(size_t)t * DINP + gcol + e] << 16);
;                 const float val = o[et][r] * rs * gn[et] * pg8::silu_f(gt);
;                 omix[(size_t)t * 1024 + ocol + e] = (bf16_t)(cvtpk(val, 0.f) & 0xffffu);
	v_min_f32_e32 v4, 0, v4
	v_sub_f32_e32 v5, v5, v6
	v_pk_mul_f32 v[64:65], v[64:65], s[8:9] op_sel_hi:[1,0]
	v_lshlrev_b32_e32 v60, 16, v61
	v_and_b32_e32 v61, 0xffff0000, v61
	v_sub_f32_e32 v4, v4, v5
	v_cvt_pk_bf16_f32 v109, v66, v67
	v_pk_mul_f32 v[66:67], v[64:65], v[102:103]
	v_pk_mul_f32 v[64:65], v[64:65], v[68:69]
	v_pk_mul_f32 v[60:61], v[60:61], s[8:9] op_sel_hi:[1,0]
	v_mul_f32_e32 v6, 0x3d800000, v4
	v_mov_b32_e32 v5, v211
	v_cvt_pk_bf16_f32 v102, v64, v65
	v_pk_mul_f32 v[64:65], v[60:61], v[104:105]
	v_pk_mul_f32 v[60:61], v[60:61], v[76:77]
	v_mov_b32_dpp v5, v6 row_shr:1 row_mask:0xf bank_mask:0xf
	v_cvt_pk_bf16_f32 v103, v60, v61
	v_lshlrev_b32_e32 v60, 16, v58
	v_and_b32_e32 v61, 0xffff0000, v58
	v_fmac_f32_e32 v5, 0x3d800000, v4
	v_mov_b32_e32 v75, v211
	v_pk_mul_f32 v[60:61], v[60:61], s[8:9] op_sel_hi:[1,0]
	v_lshlrev_b32_e32 v58, 16, v59
	v_and_b32_e32 v59, 0xffff0000, v59
	v_mov_b32_dpp v75, v5 row_shr:2 row_mask:0xf bank_mask:0xf
	v_mov_b32_e32 v4, v211
	v_cvt_pk_bf16_f32 v111, v64, v65
	v_pk_mul_f32 v[64:65], v[60:61], v[112:113]
	v_pk_mul_f32 v[60:61], v[60:61], v[84:85]
	v_pk_mul_f32 v[58:59], v[58:59], s[8:9] op_sel_hi:[1,0]
	v_pk_add_f32 v[6:7], v[4:5], v[74:75]
	v_mov_b32_e32 v89, v211
	v_cvt_pk_bf16_f32 v104, v60, v61
	v_pk_mul_f32 v[60:61], v[58:59], v[148:149]
	v_pk_mul_f32 v[58:59], v[58:59], v[144:145]
	v_mov_b32_dpp v89, v7 row_shr:4 row_mask:0xf bank_mask:0xf
	v_cvt_pk_bf16_f32 v105, v58, v59
	v_pk_add_f32 v[58:59], v[6:7], v[88:89]
	v_exp_f32_e32 v8, v8
	v_add_f32_e32 v4, v58, v131
	v_mul_f32_e32 v5, 0x3fb8aa3b, v4
	v_exp_f32_e32 v9, v5
	v_mul_f32_e32 v4, 0xbfb8aa3b, v4
	v_exp_f32_e32 v17, v4
	v_lshlrev_b32_e32 v134, 16, v86
	v_and_b32_e32 v135, 0xffff0000, v86
	v_pk_mul_f32 v[4:5], v[8:9], v[134:135]
	v_pk_mul_f32 v[8:9], v[138:139], v[8:9]
	v_cvt_pk_bf16_f32 v84, v4, v5
	v_pk_mul_f32 v[4:5], v[16:17], v[134:135]
	v_cvt_pk_bf16_f32 v76, v8, v9
	v_cvt_pk_bf16_f32 v4, v4, v5
	v_add_f32_e32 v5, v6, v57
	v_mul_f32_e32 v6, 0x3fb8aa3b, v5
	v_exp_f32_e32 v21, v6
	v_mul_f32_e32 v5, 0xbfb8aa3b, v5
	v_exp_f32_e32 v23, v5
	v_mov_b32_e32 v133, v211
	v_pk_mul_f32 v[6:7], v[20:21], v[136:137]
	v_max_f32_e32 v5, v18, v18
	v_cvt_pk_bf16_f32 v98, v6, v7
	v_pk_mul_f32 v[6:7], v[22:23], v[136:137]
	v_mov_b32_dpp v133, v59 row_shr:8 row_mask:0xf bank_mask:0xf
	v_cvt_pk_bf16_f32 v8, v6, v7
	v_pk_mul_f32 v[6:7], v[140:141], v[22:23]
	v_min_f32_e32 v5, 0, v5
	v_cvt_pk_bf16_f32 v92, v6, v7
	v_pk_mul_f32 v[6:7], v[140:141], v[20:21]
	v_mov_b32_e32 v63, v211
	v_cvt_pk_bf16_f32 v88, v6, v7
	s_waitcnt lgkmcnt(6)
	v_pk_add_f32 v[6:7], v[58:59], v[132:133]
	v_mov_b32_e32 v95, v211
	v_add_f32_e32 v15, v6, v7
	v_mul_f32_e64 v6, |v18|, s7
	v_exp_f32_e32 v6, v6
	v_pk_mul_f32 v[16:17], v[138:139], v[16:17]
	v_mov_b32_e32 v131, v211
	v_cvt_pk_bf16_f32 v80, v16, v17
	v_add_f32_e32 v6, 1.0, v6
	v_cmp_gt_f32_e32 vcc, s96, v6
	v_mov_b32_e32 v57, v211
	v_mov_b32_e32 v91, v211
	v_cndmask_b32_e64 v7, 0, 32, vcc
	v_ldexp_f32 v6, v6, v7
	v_log_f32_e32 v6, v6
	v_mov_b32_e32 v55, v211
	v_lshlrev_b32_e32 v86, 16, v87
	v_and_b32_e32 v87, 0xffff0000, v87
	v_mul_f32_e32 v7, 0x3f317217, v6
	v_fma_f32 v7, v6, s3, -v7
	v_fmac_f32_e32 v7, 0x3377d1cf, v6
	v_fmac_f32_e32 v7, 0x3f317217, v6
	v_cmp_lt_f32_e64 s[42:43], |v6|, s6
	v_cvt_pk_bf16_f32 v113, v60, v61
	v_mov_b32_e32 v53, v211
	v_cndmask_b32_e64 v6, v6, v7, s[42:43]
	v_cndmask_b32_e32 v7, 0, v237, vcc
	v_sub_f32_e32 v6, v6, v7
	v_sub_f32_e32 v5, v5, v6
	v_mul_f32_e32 v6, 0x3d800000, v5
	v_mov_b32_e32 v7, v211
	s_waitcnt vmcnt(0) expcnt(0) lgkmcnt(0)
	v_lshlrev_b32_e32 v224, 1, v156
	v_mov_b32_e32 v225, v211
	v_or_b32_e32 v226, s5, v97
	v_ashrrev_i32_e32 v227, 31, v226
	v_lshlrev_b64 v[228:229], 12, v[226:227]
	v_lshl_add_u64 v[230:231], s[58:59], 0, v[228:229]
	v_lshl_add_u64 v[232:233], v[230:231], 0, v[224:225]
	global_load_ushort v157, v[232:233], off offset:1888
	global_load_ushort v158, v[232:233], off offset:1920
	global_load_ushort v159, v[232:233], off offset:1952
	v_or_b32_e32 v224, 48, v147
	v_or_b32_e32 v226, s5, v97
	v_ashrrev_i32_e32 v227, 31, v226
	v_lshlrev_b64 v[228:229], 12, v[226:227]
	v_lshl_add_u64 v[230:231], s[58:59], 0, v[228:229]
	v_lshlrev_b32_e32 v228, 1, v224
	v_mov_b32_e32 v229, v211
	v_lshl_add_u64 v[224:225], v[230:231], 0, v[228:229]
	global_load_ushort v160, v[224:225], off offset:1888
	v_lshlrev_b32_e32 v224, 1, v156
	v_mov_b32_e32 v225, v211
	v_or_b32_e32 v226, s5, v97
	v_or_b32_e32 v228, 1, v226
	v_ashrrev_i32_e32 v229, 31, v228
	v_lshlrev_b64 v[230:231], 12, v[228:229]
	v_lshl_add_u64 v[230:231], s[58:59], 0, v[230:231]
	v_lshl_add_u64 v[232:233], v[230:231], 0, v[224:225]
	global_load_ushort v161, v[232:233], off offset:1888
	global_load_ushort v162, v[232:233], off offset:1920
	global_load_ushort v163, v[232:233], off offset:1952
	v_or_b32_e32 v224, 48, v147
	v_or_b32_e32 v226, s5, v97
	v_lshlrev_b32_e32 v228, 1, v224
	v_mov_b32_e32 v229, v211
	v_or_b32_e32 v230, 1, v226
	v_ashrrev_i32_e32 v231, 31, v230
	v_lshlrev_b64 v[232:233], 12, v[230:231]
	v_lshl_add_u64 v[232:233], s[58:59], 0, v[232:233]
	v_lshl_add_u64 v[242:243], v[232:233], 0, v[228:229]
	global_load_ushort v164, v[242:243], off offset:1888
	v_lshlrev_b32_e32 v224, 1, v156
	v_mov_b32_e32 v225, v211
	v_or_b32_e32 v226, s5, v97
	v_or_b32_e32 v228, 2, v226
	v_ashrrev_i32_e32 v229, 31, v228
	v_lshlrev_b64 v[230:231], 12, v[228:229]
	v_lshl_add_u64 v[230:231], s[58:59], 0, v[230:231]
	v_lshl_add_u64 v[232:233], v[230:231], 0, v[224:225]
	global_load_ushort v165, v[232:233], off offset:1888
	global_load_ushort v166, v[232:233], off offset:1920
	global_load_ushort v167, v[232:233], off offset:1952
; __device__ __forceinline__ unsigned cvtpk(float lo, float hi) { f32x2_t v = {lo, hi}; bf16x2_t b = __builtin_convertvector(v, bf16x2_t); return __builtin_bit_cast(unsigned, b); }
; template <int X> __device__ __forceinline__ float swz_xor(float v) { return __int_as_float(__builtin_amdgcn_ds_swizzle(__float_as_int(v), (X << 10) | 0x1F)); }
; __device__ __forceinline__ float silu_f(float g) { return g * __builtin_amdgcn_rcpf(1.0f + __expf(-g)); }
; template <bool GLA>
; __device__ __forceinline__ void chunk_pass_c(const ChunkIn& ci, const float* wgl, int unit, unsigned char* wl, int lane, const float* Sb, const float* ng, bf16_t* omix) {
;     ...
;         for (int r = 0; r < 4; ++r) {
;             ss[r] += swz_xor<1>(ss[r]); ss[r] += swz_xor<2>(ss[r]); ss[r] += swz_xor<4>(ss[r]); ss[r] += swz_xor<8>(ss[r]);
;             const float rs = rsqrtf(ss[r] * (1.0f / 64.0f) + EPS);
;             const int t = t0 + 16 * it + 4 * kq + r;
; #pragma unroll
;             for (int et = 0; et < 4; ++et) {
;                 const int e = 16 * et + row;
;                 const float gt = __uint_as_float((unsigned)ci.proj[(size_t)t * DINP + gcol + e] << 16);
;                 const float val = o[et][r] * rs * gn[et] * pg8::silu_f(gt);
;                 omix[(size_t)t * 1024 + ocol + e] = (bf16_t)(cvtpk(val, 0.f) & 0xffffu);
	v_or_b32_e32 v224, 48, v147
	v_or_b32_e32 v226, s5, v97
	v_lshlrev_b32_e32 v228, 1, v224
	v_mov_b32_e32 v229, v211
	v_or_b32_e32 v230, 2, v226
	v_ashrrev_i32_e32 v231, 31, v230
	v_lshlrev_b64 v[232:233], 12, v[230:231]
	v_lshl_add_u64 v[232:233], s[58:59], 0, v[232:233]
	v_lshl_add_u64 v[232:233], v[232:233], 0, v[228:229]
	global_load_ushort v168, v[232:233], off offset:1888
	v_lshlrev_b32_e32 v224, 1, v156
	v_mov_b32_e32 v225, v211
	v_or_b32_e32 v226, s5, v97
	v_or_b32_e32 v228, 3, v226
	v_ashrrev_i32_e32 v229, 31, v228
	v_lshlrev_b64 v[230:231], 12, v[228:229]
	v_lshl_add_u64 v[230:231], s[58:59], 0, v[230:231]
	v_lshl_add_u64 v[232:233], v[230:231], 0, v[224:225]
	global_load_ushort v169, v[232:233], off offset:1888
	global_load_ushort v170, v[232:233], off offset:1920
	global_load_ushort v171, v[232:233], off offset:1952
	v_or_b32_e32 v224, 48, v147
	v_or_b32_e32 v226, s5, v97
	v_lshlrev_b32_e32 v228, 1, v224
	v_mov_b32_e32 v229, v211
	v_or_b32_e32 v230, 3, v226
	v_ashrrev_i32_e32 v231, 31, v230
	v_lshlrev_b64 v[232:233], 12, v[230:231]
	v_lshl_add_u64 v[232:233], s[58:59], 0, v[232:233]
	v_lshl_add_u64 v[232:233], v[232:233], 0, v[228:229]
	global_load_ushort v172, v[232:233], off offset:1888
	v_lshlrev_b32_e32 v224, 1, v156
	v_mov_b32_e32 v225, v211
	v_or_b32_e32 v226, s4, v97
	v_ashrrev_i32_e32 v227, 31, v226
	v_lshlrev_b64 v[228:229], 12, v[226:227]
	v_lshl_add_u64 v[230:231], s[58:59], 0, v[228:229]
	v_lshl_add_u64 v[228:229], v[230:231], 0, v[224:225]
	global_load_ushort v173, v[228:229], off offset:1888
	global_load_ushort v174, v[228:229], off offset:1920
	global_load_ushort v175, v[228:229], off offset:1952
	v_or_b32_e32 v224, 48, v147
	v_lshlrev_b32_e32 v226, 1, v224
	v_mov_b32_e32 v227, v211
	v_or_b32_e32 v228, s4, v97
	v_ashrrev_i32_e32 v229, 31, v228
	v_lshlrev_b64 v[230:231], 12, v[228:229]
	v_lshl_add_u64 v[232:233], s[58:59], 0, v[230:231]
	v_lshl_add_u64 v[242:243], v[232:233], 0, v[226:227]
	global_load_ushort v176, v[242:243], off offset:1888
	v_lshlrev_b32_e32 v224, 1, v156
	v_mov_b32_e32 v225, v211
	v_or_b32_e32 v226, s4, v97
	v_or_b32_e32 v228, 1, v226
	v_ashrrev_i32_e32 v229, 31, v228
	v_lshlrev_b64 v[230:231], 12, v[228:229]
	v_lshl_add_u64 v[230:231], s[58:59], 0, v[230:231]
	v_lshl_add_u64 v[232:233], v[230:231], 0, v[224:225]
	global_load_ushort v177, v[232:233], off offset:1888
	global_load_ushort v178, v[232:233], off offset:1920
	global_load_ushort v179, v[232:233], off offset:1952
	v_or_b32_e32 v224, 48, v147
	v_lshlrev_b32_e32 v226, 1, v224
	v_mov_b32_e32 v227, v211
	v_or_b32_e32 v228, s4, v97
	v_or_b32_e32 v230, 1, v228
	v_ashrrev_i32_e32 v231, 31, v230
	v_lshlrev_b64 v[232:233], 12, v[230:231]
	v_lshl_add_u64 v[232:233], s[58:59], 0, v[232:233]
	v_lshl_add_u64 v[242:243], v[232:233], 0, v[226:227]
	global_load_ushort v180, v[242:243], off offset:1888
	v_lshlrev_b32_e32 v224, 1, v156
	v_mov_b32_e32 v225, v211
	v_or_b32_e32 v226, s4, v97
	v_or_b32_e32 v228, 2, v226
	v_ashrrev_i32_e32 v229, 31, v228
	v_lshlrev_b64 v[230:231], 12, v[228:229]
	v_lshl_add_u64 v[230:231], s[58:59], 0, v[230:231]
	v_lshl_add_u64 v[232:233], v[230:231], 0, v[224:225]
	global_load_ushort v181, v[232:233], off offset:1888
	global_load_ushort v182, v[232:233], off offset:1920
	global_load_ushort v183, v[232:233], off offset:1952
	v_or_b32_e32 v224, 48, v147
	v_lshlrev_b32_e32 v226, 1, v224
	v_mov_b32_e32 v227, v211
	v_or_b32_e32 v228, s4, v97
	v_or_b32_e32 v230, 2, v228
	v_ashrrev_i32_e32 v231, 31, v230
	v_lshlrev_b64 v[232:233], 12, v[230:231]
	v_lshl_add_u64 v[232:233], s[58:59], 0, v[232:233]
	v_lshl_add_u64 v[232:233], v[232:233], 0, v[226:227]
	global_load_ushort v184, v[232:233], off offset:1888
	v_lshlrev_b32_e32 v224, 1, v156
	v_mov_b32_e32 v225, v211
	v_or_b32_e32 v226, s4, v97
	v_or_b32_e32 v228, 3, v226
	v_ashrrev_i32_e32 v229, 31, v228
	v_lshlrev_b64 v[230:231], 12, v[228:229]
	v_lshl_add_u64 v[230:231], s[58:59], 0, v[230:231]
	v_lshl_add_u64 v[232:233], v[230:231], 0, v[224:225]
	global_load_ushort v185, v[232:233], off offset:1888
	global_load_ushort v186, v[232:233], off offset:1920
	global_load_ushort v187, v[232:233], off offset:1952
	v_or_b32_e32 v224, 48, v147
	v_lshlrev_b32_e32 v226, 1, v224
	v_mov_b32_e32 v227, v211
	v_or_b32_e32 v228, s4, v97
	v_or_b32_e32 v230, 3, v228
	v_ashrrev_i32_e32 v231, 31, v230
	v_lshlrev_b64 v[232:233], 12, v[230:231]
	v_lshl_add_u64 v[232:233], s[58:59], 0, v[232:233]
	v_lshl_add_u64 v[232:233], v[232:233], 0, v[226:227]
	global_load_ushort v188, v[232:233], off offset:1888
	v_lshlrev_b32_e32 v224, 1, v156
	v_mov_b32_e32 v225, v211
	v_or_b32_e32 v226, s65, v97
	v_ashrrev_i32_e32 v227, 31, v226
	v_lshlrev_b64 v[228:229], 12, v[226:227]
	v_lshl_add_u64 v[230:231], s[58:59], 0, v[228:229]
	v_lshl_add_u64 v[228:229], v[230:231], 0, v[224:225]
	global_load_ushort v189, v[228:229], off offset:1888
	global_load_ushort v190, v[228:229], off offset:1920
	global_load_ushort v191, v[228:229], off offset:1952
	v_or_b32_e32 v224, 48, v147
	v_lshlrev_b32_e32 v226, 1, v224
	v_mov_b32_e32 v227, v211
	v_or_b32_e32 v228, s65, v97
	v_ashrrev_i32_e32 v229, 31, v228
	v_lshlrev_b64 v[230:231], 12, v[228:229]
	v_lshl_add_u64 v[232:233], s[58:59], 0, v[230:231]
	v_lshl_add_u64 v[242:243], v[232:233], 0, v[226:227]
	global_load_ushort v192, v[242:243], off offset:1888
	v_lshlrev_b32_e32 v224, 1, v156
	v_mov_b32_e32 v225, v211
	v_or_b32_e32 v226, s65, v97
	v_or_b32_e32 v228, 1, v226
	v_ashrrev_i32_e32 v229, 31, v228
	v_lshlrev_b64 v[230:231], 12, v[228:229]
	v_lshl_add_u64 v[230:231], s[58:59], 0, v[230:231]
	v_lshl_add_u64 v[232:233], v[230:231], 0, v[224:225]
	global_load_ushort v193, v[232:233], off offset:1888
; template <int X> __device__ __forceinline__ float swz_xor(float v) { return __int_as_float(__builtin_amdgcn_ds_swizzle(__float_as_int(v), (X << 10) | 0x1F)); }
; template <bool GLA>
; __device__ __forceinline__ void chunk_pass_c(const ChunkIn& ci, const float* wgl, int unit, unsigned char* wl, int lane, const float* Sb, const float* ng, bf16_t* omix) {
;     ...
;         for (int r = 0; r < 4; ++r) {
;             ss[r] += swz_xor<1>(ss[r]); ss[r] += swz_xor<2>(ss[r]); ss[r] += swz_xor<4>(ss[r]); ss[r] += swz_xor<8>(ss[r]);
;             const float rs = rsqrtf(ss[r] * (1.0f / 64.0f) + EPS);
;             const int t = t0 + 16 * it + 4 * kq + r;
; #pragma unroll
;             for (int et = 0; et < 4; ++et) {
;                 const int e = 16 * et + row;
;                 const float gt = __uint_as_float((unsigned)ci.proj[(size_t)t * DINP + gcol + e] << 16);
	global_load_ushort v194, v[232:233], off offset:1920
	global_load_ushort v195, v[232:233], off offset:1952
	v_or_b32_e32 v224, 48, v147
	v_lshlrev_b32_e32 v226, 1, v224
	v_mov_b32_e32 v227, v211
	v_or_b32_e32 v228, s65, v97
	v_or_b32_e32 v230, 1, v228
	v_ashrrev_i32_e32 v231, 31, v230
	v_lshlrev_b64 v[232:233], 12, v[230:231]
	v_lshl_add_u64 v[232:233], s[58:59], 0, v[232:233]
	v_lshl_add_u64 v[242:243], v[232:233], 0, v[226:227]
	global_load_ushort v196, v[242:243], off offset:1888
	v_lshlrev_b32_e32 v224, 1, v156
	v_mov_b32_e32 v225, v211
	v_or_b32_e32 v226, s65, v97
	v_or_b32_e32 v228, 2, v226
	v_ashrrev_i32_e32 v229, 31, v228
	v_lshlrev_b64 v[230:231], 12, v[228:229]
	v_lshl_add_u64 v[230:231], s[58:59], 0, v[230:231]
	v_lshl_add_u64 v[232:233], v[230:231], 0, v[224:225]
	global_load_ushort v197, v[232:233], off offset:1888
	global_load_ushort v198, v[232:233], off offset:1920
	global_load_ushort v199, v[232:233], off offset:1952
	v_or_b32_e32 v224, 48, v147
	v_lshlrev_b32_e32 v226, 1, v224
	v_mov_b32_e32 v227, v211
	v_or_b32_e32 v228, s65, v97
	v_or_b32_e32 v230, 2, v228
	v_ashrrev_i32_e32 v231, 31, v230
	v_lshlrev_b64 v[232:233], 12, v[230:231]
	v_lshl_add_u64 v[232:233], s[58:59], 0, v[232:233]
	v_lshl_add_u64 v[232:233], v[232:233], 0, v[226:227]
	global_load_ushort v200, v[232:233], off offset:1888
	v_lshlrev_b32_e32 v224, 1, v156
	v_mov_b32_e32 v225, v211
	v_or_b32_e32 v226, s65, v97
	v_or_b32_e32 v228, 3, v226
	v_ashrrev_i32_e32 v229, 31, v228
	v_lshlrev_b64 v[230:231], 12, v[228:229]
	v_lshl_add_u64 v[230:231], s[58:59], 0, v[230:231]
	v_lshl_add_u64 v[232:233], v[230:231], 0, v[224:225]
	global_load_ushort v201, v[232:233], off offset:1888
	global_load_ushort v202, v[232:233], off offset:1920
	global_load_ushort v203, v[232:233], off offset:1952
	v_or_b32_e32 v224, 48, v147
	v_lshlrev_b32_e32 v226, 1, v224
	v_mov_b32_e32 v227, v211
	v_or_b32_e32 v228, s65, v97
	v_or_b32_e32 v230, 3, v228
	v_ashrrev_i32_e32 v231, 31, v230
	v_lshlrev_b64 v[232:233], 12, v[230:231]
	v_lshl_add_u64 v[232:233], s[58:59], 0, v[232:233]
	v_lshl_add_u64 v[232:233], v[232:233], 0, v[226:227]
	global_load_ushort v204, v[232:233], off offset:1888
	v_lshlrev_b32_e32 v224, 1, v156
	v_mov_b32_e32 v225, v211
	v_or_b32_e32 v226, s27, v97
	v_ashrrev_i32_e32 v227, 31, v226
	v_lshlrev_b64 v[228:229], 12, v[226:227]
	v_lshl_add_u64 v[230:231], s[58:59], 0, v[228:229]
	v_lshl_add_u64 v[228:229], v[230:231], 0, v[224:225]
	global_load_ushort v205, v[228:229], off offset:1888
	global_load_ushort v206, v[228:229], off offset:1920
	global_load_ushort v207, v[228:229], off offset:1952
	v_or_b32_e32 v224, 48, v147
	v_lshlrev_b32_e32 v226, 1, v224
	v_mov_b32_e32 v227, v211
	v_or_b32_e32 v228, s27, v97
	v_ashrrev_i32_e32 v229, 31, v228
	v_lshlrev_b64 v[230:231], 12, v[228:229]
	v_lshl_add_u64 v[232:233], s[58:59], 0, v[230:231]
	v_lshl_add_u64 v[242:243], v[232:233], 0, v[226:227]
	global_load_ushort v208, v[242:243], off offset:1888
	v_lshlrev_b32_e32 v224, 1, v156
	v_mov_b32_e32 v225, v211
	v_or_b32_e32 v226, s27, v97
	v_or_b32_e32 v228, 1, v226
	v_ashrrev_i32_e32 v229, 31, v228
	v_lshlrev_b64 v[230:231], 12, v[228:229]
	v_lshl_add_u64 v[230:231], s[58:59], 0, v[230:231]
	v_lshl_add_u64 v[232:233], v[230:231], 0, v[224:225]
	global_load_ushort v209, v[232:233], off offset:1888
	global_load_ushort v212, v[232:233], off offset:1920
	global_load_ushort v213, v[232:233], off offset:1952
	v_or_b32_e32 v224, 48, v147
	v_lshlrev_b32_e32 v226, 1, v224
	v_mov_b32_e32 v227, v211
	v_or_b32_e32 v228, s27, v97
	v_or_b32_e32 v230, 1, v228
	v_ashrrev_i32_e32 v231, 31, v230
	v_lshlrev_b64 v[232:233], 12, v[230:231]
	v_lshl_add_u64 v[232:233], s[58:59], 0, v[232:233]
	v_lshl_add_u64 v[242:243], v[232:233], 0, v[226:227]
	global_load_ushort v214, v[242:243], off offset:1888
	v_lshlrev_b32_e32 v224, 1, v156
	v_mov_b32_e32 v225, v211
	v_or_b32_e32 v226, s27, v97
	v_or_b32_e32 v228, 2, v226
	v_ashrrev_i32_e32 v229, 31, v228
	v_lshlrev_b64 v[230:231], 12, v[228:229]
	v_lshl_add_u64 v[230:231], s[58:59], 0, v[230:231]
	v_lshl_add_u64 v[232:233], v[230:231], 0, v[224:225]
	global_load_ushort v215, v[232:233], off offset:1888
	global_load_ushort v216, v[232:233], off offset:1920
	global_load_ushort v217, v[232:233], off offset:1952
	v_or_b32_e32 v224, 48, v147
	v_lshlrev_b32_e32 v226, 1, v224
	v_mov_b32_e32 v227, v211
	v_or_b32_e32 v228, s27, v97
	v_or_b32_e32 v230, 2, v228
	v_ashrrev_i32_e32 v231, 31, v230
	v_lshlrev_b64 v[232:233], 12, v[230:231]
	v_lshl_add_u64 v[232:233], s[58:59], 0, v[232:233]
	v_lshl_add_u64 v[232:233], v[232:233], 0, v[226:227]
	global_load_ushort v218, v[232:233], off offset:1888
	v_lshlrev_b32_e32 v224, 1, v156
	v_mov_b32_e32 v225, v211
	v_or_b32_e32 v226, s27, v97
	v_or_b32_e32 v228, 3, v226
	v_ashrrev_i32_e32 v229, 31, v228
	v_lshlrev_b64 v[230:231], 12, v[228:229]
	v_lshl_add_u64 v[230:231], s[58:59], 0, v[230:231]
	v_lshl_add_u64 v[232:233], v[230:231], 0, v[224:225]
	global_load_ushort v219, v[232:233], off offset:1888
	global_load_ushort v220, v[232:233], off offset:1920
	global_load_ushort v221, v[232:233], off offset:1952
	v_or_b32_e32 v224, 48, v147
	v_lshlrev_b32_e32 v226, 1, v224
	v_mov_b32_e32 v227, v211
	v_or_b32_e32 v228, s27, v97
	v_or_b32_e32 v230, 3, v228
	v_ashrrev_i32_e32 v231, 31, v230
	v_lshlrev_b64 v[232:233], 12, v[230:231]
	v_lshl_add_u64 v[232:233], s[58:59], 0, v[232:233]
	v_lshl_add_u64 v[242:243], v[232:233], 0, v[226:227]
	global_load_ushort v222, v[242:243], off offset:1888
	v_cvt_pk_bf16_f32 v110, v66, v67
	v_mov_b32_dpp v7, v6 row_shr:1 row_mask:0xf bank_mask:0xf
	v_fmac_f32_e32 v7, 0x3d800000, v5
	v_mov_b32_e32 v6, v211
; __device__ __forceinline__ unsigned cvtpk(float lo, float hi) { f32x2_t v = {lo, hi}; bf16x2_t b = __builtin_convertvector(v, bf16x2_t); return __builtin_bit_cast(unsigned, b); }
; template <bool GLA>
; __device__ __forceinline__ void chunk_tile(const ChunkRaw& raw, const bf16x8 (&wfr)[2], const f32x4 (&bfr)[2], int h, int it, int row, int kq, float lg, float (&carry)[8], float (&bq)[8], float (&qv)[8], float (&kv)[8]) {
;     ...
;         for (int j = 0; j < 8; ++j) {
;             float la = (fminf(z[j], 0.f) - __logf(1.0f + __expf(-fabsf(z[j])))) * (1.0f / 16.0f);
;             la += __int_as_float(__builtin_amdgcn_update_dpp(0, __float_as_int(la), 0x111, 0xf, 0xf, false));
;             la += __int_as_float(__builtin_amdgcn_update_dpp(0, __float_as_int(la), 0x112, 0xf, 0xf, false));
;             la += __int_as_float(__builtin_amdgcn_update_dpp(0, __float_as_int(la), 0x114, 0xf, 0xf, false));
;             la += __int_as_float(__builtin_amdgcn_update_dpp(0, __float_as_int(la), 0x118, 0xf, 0xf, false));
;             bq[j] = la + carry[j];
;             carry[j] += __int_as_float(__builtin_amdgcn_ds_bpermute((16 * kq + 15) * 4, __float_as_int(la)));
;             qv[j] = q[j] * qs; kv[j] = k[j];
; template <bool GLA>
; __device__ __forceinline__ void chunk_pass_c(const ChunkIn& ci, const float* wgl, int unit, unsigned char* wl, int lane, const float* Sb, const float* ng, bf16_t* omix) {
;     ...
;         float a[8], bneg[8], cpos[8], dneg[8];
; #pragma unroll
;         for (int j = 0; j < 8; ++j) { const float eb = __expf(bq[j]), enb = __expf(-bq[j]); a[j] = qv[j] * eb; bneg[j] = kv[j] * enb; cpos[j] = qv[j] * enb; dneg[j] = kv[j] * eb; }
;         qf[it] = __builtin_bit_cast(bf16x8, (u32x4){cvtpk(a[0], a[1]), cvtpk(a[2], a[3]), cvtpk(a[4], a[5]), cvtpk(a[6], a[7])});
;         kf[it] = __builtin_bit_cast(bf16x8, (u32x4){cvtpk(bneg[0], bneg[1]), cvtpk(bneg[2], bneg[3]), cvtpk(bneg[4], bneg[5]), cvtpk(bneg[6], bneg[7])});
;         qb[it] = __builtin_bit_cast(bf16x8, (u32x4){cvtpk(cpos[0], cpos[1]), cvtpk(cpos[2], cpos[3]), cvtpk(cpos[4], cpos[5]), cvtpk(cpos[6], cpos[7])});
;         kb[it] = __builtin_bit_cast(bf16x8, (u32x4){cvtpk(dneg[0], dneg[1]), cvtpk(dneg[2], dneg[3]), cvtpk(dneg[4], dneg[5]), cvtpk(dneg[6], dneg[7])});
	v_cvt_pk_bf16_f32 v112, v64, v65
	v_mov_b32_dpp v63, v7 row_shr:2 row_mask:0xf bank_mask:0xf
	v_pk_add_f32 v[6:7], v[6:7], v[62:63]
	s_add_u32 s44, s44, s56
	s_addc_u32 s45, s45, s57
	v_mov_b32_dpp v95, v7 row_shr:4 row_mask:0xf bank_mask:0xf
	v_pk_add_f32 v[16:17], v[6:7], v[94:95]
	v_mfma_f32_16x16x32_bf16 v[106:109], v[106:109], v[110:113], 0
	v_add_f32_e32 v5, v16, v129
	v_mul_f32_e32 v7, 0x3fb8aa3b, v5
	v_exp_f32_e32 v18, v7
	v_mul_f32_e64 v7, |v19|, s7
	v_exp_f32_e32 v7, v7
	v_mul_f32_e32 v5, 0xbfb8aa3b, v5
	v_exp_f32_e32 v22, v5
	v_add_f32_e32 v5, v6, v43
	v_add_f32_e32 v7, 1.0, v7
	v_cmp_gt_f32_e32 vcc, s96, v7
	v_mul_f32_e32 v6, 0x3fb8aa3b, v5
	v_mul_f32_e32 v5, 0xbfb8aa3b, v5
	v_cndmask_b32_e64 v9, 0, 32, vcc
	v_ldexp_f32 v7, v7, v9
	v_log_f32_e32 v7, v7
	v_exp_f32_e32 v58, v5
	v_max_f32_e32 v5, v19, v19
	v_mov_b32_dpp v131, v17 row_shr:8 row_mask:0xf bank_mask:0xf
	v_mul_f32_e32 v9, 0x3f317217, v7
	v_fma_f32 v9, v7, s3, -v9
	v_fmac_f32_e32 v9, 0x3377d1cf, v7
	v_fmac_f32_e32 v9, 0x3f317217, v7
	v_cmp_lt_f32_e64 s[42:43], |v7|, s6
	v_min_f32_e32 v5, 0, v5
	v_pk_add_f32 v[16:17], v[16:17], v[130:131]
	v_cndmask_b32_e64 v7, v7, v9, s[42:43]
	v_cndmask_b32_e32 v9, 0, v237, vcc
	v_sub_f32_e32 v7, v7, v9
	v_sub_f32_e32 v5, v5, v7
	v_add_f32_e32 v20, v16, v17
	v_mul_f32_e32 v7, 0x3d800000, v5
	v_mov_b32_e32 v17, v211
	v_mov_b32_e32 v16, v211
	v_exp_f32_e32 v6, v6
	v_mov_b32_dpp v17, v7 row_shr:1 row_mask:0xf bank_mask:0xf
	v_fmac_f32_e32 v17, 0x3d800000, v5
	v_mov_b32_e32 v129, v211
	v_mov_b32_e32 v43, v211
	v_mov_b32_dpp v57, v17 row_shr:2 row_mask:0xf bank_mask:0xf
	v_pk_add_f32 v[16:17], v[16:17], v[56:57]
	v_lshlrev_b32_e32 v210, 1, v156
	v_add_f32_e32 v9, v16, v39
	v_mov_b32_dpp v91, v17 row_shr:4 row_mask:0xf bank_mask:0xf
	v_pk_add_f32 v[56:57], v[16:17], v[90:91]
	v_mov_b32_e32 v39, v211
	v_add_f32_e32 v5, v56, v121
	v_mul_f32_e32 v7, 0x3fb8aa3b, v5
	v_exp_f32_e32 v19, v7
	v_mul_f32_e32 v7, 0x3fb8aa3b, v9
	v_exp_f32_e32 v7, v7
	v_mov_b32_dpp v129, v57 row_shr:8 row_mask:0xf bank_mask:0xf
	v_mul_f32_e32 v9, 0xbfb8aa3b, v9
	v_exp_f32_e32 v59, v9
	v_pk_mul_f32 v[16:17], v[6:7], v[78:79]
	v_pk_mul_f32 v[6:7], v[72:73], v[6:7]
	v_cvt_pk_bf16_f32 v99, v16, v17
	v_cvt_pk_bf16_f32 v89, v6, v7
	v_pk_add_f32 v[6:7], v[56:57], v[128:129]
	v_pk_mul_f32 v[16:17], v[58:59], v[78:79]
	v_add_f32_e32 v21, v6, v7
	v_mul_f32_e64 v7, |v10|, s7
	v_exp_f32_e32 v7, v7
	v_max_f32_e32 v6, v10, v10
	v_min_f32_e32 v6, 0, v6
	v_mul_f32_e32 v5, 0xbfb8aa3b, v5
	v_add_f32_e32 v7, 1.0, v7
	v_cmp_gt_f32_e32 vcc, s96, v7
	v_cvt_pk_bf16_f32 v9, v16, v17
	v_pk_mul_f32 v[16:17], v[72:73], v[58:59]
	v_cndmask_b32_e64 v10, 0, 32, vcc
	v_ldexp_f32 v7, v7, v10
	v_log_f32_e32 v7, v7
	v_exp_f32_e32 v23, v5
	v_cvt_pk_bf16_f32 v93, v16, v17
	v_pk_mul_f32 v[60:61], v[18:19], v[86:87]
	v_mul_f32_e32 v10, 0x3f317217, v7
	v_fma_f32 v10, v7, s3, -v10
	v_fmac_f32_e32 v10, 0x3377d1cf, v7
	v_fmac_f32_e32 v10, 0x3f317217, v7
	v_cmp_lt_f32_e64 s[42:43], |v7|, s6
	v_pk_mul_f32 v[18:19], v[82:83], v[18:19]
	v_cvt_pk_bf16_f32 v85, v60, v61
	v_cndmask_b32_e64 v7, v7, v10, s[42:43]
	v_cndmask_b32_e32 v10, 0, v237, vcc
	v_sub_f32_e32 v7, v7, v10
	v_sub_f32_e32 v6, v6, v7
	v_mul_f32_e32 v10, 0x3d800000, v6
	v_mov_b32_e32 v7, v211
	v_cvt_pk_bf16_f32 v77, v18, v19
	v_pk_mul_f32 v[60:61], v[22:23], v[86:87]
	v_mov_b32_dpp v7, v10 row_shr:1 row_mask:0xf bank_mask:0xf
	v_fmac_f32_e32 v7, 0x3d800000, v6
	v_mov_b32_e32 v6, v211
	v_pk_mul_f32 v[22:23], v[82:83], v[22:23]
	v_mov_b32_dpp v55, v7 row_shr:2 row_mask:0xf bank_mask:0xf
	v_pk_add_f32 v[6:7], v[6:7], v[54:55]
	v_cvt_pk_bf16_f32 v81, v22, v23
	v_mov_b32_e32 v121, v211
	v_mov_b32_dpp v39, v7 row_shr:4 row_mask:0xf bank_mask:0xf
	v_pk_add_f32 v[16:17], v[6:7], v[38:39]
	v_add_f32_e32 v6, v6, v37
	v_add_f32_e32 v7, v16, v101
	v_mul_f32_e32 v10, 0x3fb8aa3b, v7
	v_mul_f32_e32 v7, 0xbfb8aa3b, v7
	v_mov_b32_e32 v101, v211
	v_exp_f32_e32 v18, v7
	v_mul_f32_e32 v7, 0x3fb8aa3b, v6
	v_mul_f32_e32 v6, 0xbfb8aa3b, v6
	v_mov_b32_dpp v101, v17 row_shr:8 row_mask:0xf bank_mask:0xf
	v_exp_f32_e32 v38, v7
	v_exp_f32_e32 v54, v6
	v_pk_add_f32 v[6:7], v[16:17], v[100:101]
	v_mov_b32_e32 v37, v211
	v_add_f32_e32 v22, v6, v7
	v_mul_f32_e64 v7, |v11|, s7
	v_exp_f32_e32 v7, v7
	v_max_f32_e32 v6, v11, v11
	v_min_f32_e32 v6, 0, v6
	v_exp_f32_e32 v10, v10
	v_add_f32_e32 v7, 1.0, v7
	v_cmp_gt_f32_e32 vcc, s96, v7
	v_cvt_pk_bf16_f32 v5, v60, v61
	s_nop 0
	v_cndmask_b32_e64 v11, 0, 32, vcc
	v_ldexp_f32 v7, v7, v11
	v_log_f32_e32 v7, v7
	s_nop 0
	v_mul_f32_e32 v11, 0x3f317217, v7
	v_fma_f32 v11, v7, s3, -v11
	v_fmac_f32_e32 v11, 0x3377d1cf, v7
	v_fmac_f32_e32 v11, 0x3f317217, v7
	v_cmp_lt_f32_e64 s[42:43], |v7|, s6
	s_nop 1
	v_cndmask_b32_e64 v7, v7, v11, s[42:43]
	v_cndmask_b32_e32 v11, 0, v237, vcc
	v_sub_f32_e32 v7, v7, v11
	v_sub_f32_e32 v6, v6, v7
	v_mul_f32_e32 v11, 0x3d800000, v6
	v_mov_b32_e32 v7, v211
	s_nop 1
	v_mov_b32_dpp v7, v11 row_shr:1 row_mask:0xf bank_mask:0xf
	v_fmac_f32_e32 v7, 0x3d800000, v6
	v_mov_b32_e32 v6, v211
	s_nop 0
	v_mov_b32_dpp v53, v7 row_shr:2 row_mask:0xf bank_mask:0xf
	v_pk_add_f32 v[16:17], v[6:7], v[52:53]
	s_nop 1
	v_mov_b32_dpp v37, v17 row_shr:4 row_mask:0xf bank_mask:0xf
	v_pk_add_f32 v[36:37], v[16:17], v[36:37]
	s_nop 0
	v_add_f32_e32 v6, v36, v35
	v_mul_f32_e32 v7, 0x3fb8aa3b, v6
	v_exp_f32_e32 v11, v7
	v_mul_f32_e32 v6, 0xbfb8aa3b, v6
	v_exp_f32_e32 v19, v6
	v_mov_b32_dpp v121, v37 row_shr:8 row_mask:0xf bank_mask:0xf
	v_pk_mul_f32 v[6:7], v[10:11], v[122:123]
	v_pk_mul_f32 v[10:11], v[126:127], v[10:11]
	v_cvt_pk_bf16_f32 v86, v6, v7
	v_pk_mul_f32 v[6:7], v[18:19], v[122:123]
	v_cvt_pk_bf16_f32 v78, v10, v11
; __device__ __forceinline__ unsigned cvtpk(float lo, float hi) { f32x2_t v = {lo, hi}; bf16x2_t b = __builtin_convertvector(v, bf16x2_t); return __builtin_bit_cast(unsigned, b); }
; template <bool GLA>
; __device__ __forceinline__ void chunk_tile(const ChunkRaw& raw, const bf16x8 (&wfr)[2], const f32x4 (&bfr)[2], int h, int it, int row, int kq, float lg, float (&carry)[8], float (&bq)[8], float (&qv)[8], float (&kv)[8]) {
;     ...
;         for (int j = 0; j < 8; ++j) {
;             float la = (fminf(z[j], 0.f) - __logf(1.0f + __expf(-fabsf(z[j])))) * (1.0f / 16.0f);
;             la += __int_as_float(__builtin_amdgcn_update_dpp(0, __float_as_int(la), 0x111, 0xf, 0xf, false));
;             la += __int_as_float(__builtin_amdgcn_update_dpp(0, __float_as_int(la), 0x112, 0xf, 0xf, false));
;             la += __int_as_float(__builtin_amdgcn_update_dpp(0, __float_as_int(la), 0x114, 0xf, 0xf, false));
;             la += __int_as_float(__builtin_amdgcn_update_dpp(0, __float_as_int(la), 0x118, 0xf, 0xf, false));
;             bq[j] = la + carry[j];
;             carry[j] += __int_as_float(__builtin_amdgcn_ds_bpermute((16 * kq + 15) * 4, __float_as_int(la)));
;             qv[j] = q[j] * qs; kv[j] = k[j];
; template <bool GLA>
; __device__ __forceinline__ void chunk_pass_c(const ChunkIn& ci, const float* wgl, int unit, unsigned char* wl, int lane, const float* Sb, const float* ng, bf16_t* omix) {
;     ...
;         float a[8], bneg[8], cpos[8], dneg[8];
; #pragma unroll
;         for (int j = 0; j < 8; ++j) { const float eb = __expf(bq[j]), enb = __expf(-bq[j]); a[j] = qv[j] * eb; bneg[j] = kv[j] * enb; cpos[j] = qv[j] * enb; dneg[j] = kv[j] * eb; }
;         qf[it] = __builtin_bit_cast(bf16x8, (u32x4){cvtpk(a[0], a[1]), cvtpk(a[2], a[3]), cvtpk(a[4], a[5]), cvtpk(a[6], a[7])});
;         kf[it] = __builtin_bit_cast(bf16x8, (u32x4){cvtpk(bneg[0], bneg[1]), cvtpk(bneg[2], bneg[3]), cvtpk(bneg[4], bneg[5]), cvtpk(bneg[6], bneg[7])});
;         qb[it] = __builtin_bit_cast(bf16x8, (u32x4){cvtpk(cpos[0], cpos[1]), cvtpk(cpos[2], cpos[3]), cvtpk(cpos[4], cpos[5]), cvtpk(cpos[6], cpos[7])});
;         kb[it] = __builtin_bit_cast(bf16x8, (u32x4){cvtpk(dneg[0], dneg[1]), cvtpk(dneg[2], dneg[3]), cvtpk(dneg[4], dneg[5]), cvtpk(dneg[6], dneg[7])});
	v_cvt_pk_bf16_f32 v6, v6, v7
	v_add_f32_e32 v7, v16, v41
	v_mul_f32_e32 v10, 0x3fb8aa3b, v7
	v_exp_f32_e32 v39, v10
	v_mul_f32_e32 v7, 0xbfb8aa3b, v7
	v_exp_f32_e32 v55, v7
	v_max_f32_e32 v7, v12, v12
	v_pk_mul_f32 v[10:11], v[38:39], v[124:125]
	v_min_f32_e32 v7, 0, v7
	v_cvt_pk_bf16_f32 v100, v10, v11
	v_pk_mul_f32 v[10:11], v[54:55], v[124:125]
	v_pk_mul_f32 v[16:17], v[70:71], v[54:55]
	v_cvt_pk_bf16_f32 v10, v10, v11
	v_mul_f32_e64 v11, |v12|, s7
	v_exp_f32_e32 v11, v11
	v_cvt_pk_bf16_f32 v94, v16, v17
	v_pk_mul_f32 v[16:17], v[70:71], v[38:39]
	v_mov_b32_e32 v35, v211
	v_add_f32_e32 v11, 1.0, v11
	v_cmp_gt_f32_e32 vcc, s96, v11
	v_cvt_pk_bf16_f32 v90, v16, v17
	v_pk_add_f32 v[16:17], v[36:37], v[120:121]
	v_cndmask_b32_e64 v12, 0, 32, vcc
	v_ldexp_f32 v11, v11, v12
	v_log_f32_e32 v11, v11
	v_add_f32_e32 v23, v16, v17
	v_mov_b32_e32 v17, v211
	v_mov_b32_e32 v16, v211
	v_mul_f32_e32 v12, 0x3f317217, v11
	v_fma_f32 v12, v11, s3, -v12
	v_fmac_f32_e32 v12, 0x3377d1cf, v11
	v_fmac_f32_e32 v12, 0x3f317217, v11
	v_cmp_lt_f32_e64 s[42:43], |v11|, s6
	v_pk_mul_f32 v[18:19], v[126:127], v[18:19]
	v_mov_b32_e32 v41, v211
	v_cndmask_b32_e64 v11, v11, v12, s[42:43]
	v_cndmask_b32_e32 v12, 0, v237, vcc
	v_sub_f32_e32 v11, v11, v12
	v_sub_f32_e32 v7, v7, v11
	v_mul_f32_e32 v11, 0x3d800000, v7
	v_cvt_pk_bf16_f32 v82, v18, v19
	s_nop 0
	v_mov_b32_dpp v17, v11 row_shr:1 row_mask:0xf bank_mask:0xf
	v_fmac_f32_e32 v17, 0x3d800000, v7
	s_nop 1
	v_mov_b32_dpp v43, v17 row_shr:2 row_mask:0xf bank_mask:0xf
	v_pk_add_f32 v[16:17], v[16:17], v[42:43]
	s_nop 1
	v_mov_b32_dpp v35, v17 row_shr:4 row_mask:0xf bank_mask:0xf
	v_pk_add_f32 v[18:19], v[16:17], v[34:35]
	s_nop 0
	v_add_f32_e32 v7, v18, v29
	v_mul_f32_e32 v11, 0x3fb8aa3b, v7
	v_mul_f32_e32 v7, 0xbfb8aa3b, v7
	v_exp_f32_e32 v34, v7
	v_add_f32_e32 v7, v16, v33
	v_exp_f32_e32 v12, v11
	v_mul_f32_e32 v11, 0x3fb8aa3b, v7
	v_exp_f32_e32 v16, v11
	v_mul_f32_e64 v11, |v13|, s7
	v_exp_f32_e32 v11, v11
	v_mul_f32_e32 v7, 0xbfb8aa3b, v7
	v_exp_f32_e32 v36, v7
	v_max_f32_e32 v7, v13, v13
	v_add_f32_e32 v11, 1.0, v11
	v_cmp_gt_f32_e32 vcc, s96, v11
	v_mov_b32_e32 v29, v211
	v_min_f32_e32 v7, 0, v7
	v_cndmask_b32_e64 v13, 0, 32, vcc
	v_ldexp_f32 v11, v11, v13
	v_log_f32_e32 v11, v11
	v_mov_b32_dpp v29, v19 row_shr:8 row_mask:0xf bank_mask:0xf
	v_pk_add_f32 v[18:19], v[18:19], v[28:29]
	v_mov_b32_e32 v33, v211
	v_mul_f32_e32 v13, 0x3f317217, v11
	v_fma_f32 v13, v11, s3, -v13
	v_fmac_f32_e32 v13, 0x3377d1cf, v11
	v_fmac_f32_e32 v13, 0x3f317217, v11
	v_cmp_lt_f32_e64 s[42:43], |v11|, s6
	v_add_f32_e32 v38, v18, v19
	v_mov_b32_e32 v19, v211
	v_cndmask_b32_e64 v11, v11, v13, s[42:43]
	v_cndmask_b32_e32 v13, 0, v237, vcc
	v_sub_f32_e32 v11, v11, v13
	v_sub_f32_e32 v7, v7, v11
	v_mul_f32_e32 v11, 0x3d800000, v7
	v_mov_b32_e32 v18, v211
	v_readlane_b32 s3, v254, 60
	v_mov_b32_dpp v19, v11 row_shr:1 row_mask:0xf bank_mask:0xf
	v_fmac_f32_e32 v19, 0x3d800000, v7
	v_cmp_gt_u32_e32 vcc, v97, v156
	v_cmp_lt_u32_e64 s[42:43], v97, v156
	v_mov_b32_dpp v41, v19 row_shr:2 row_mask:0xf bank_mask:0xf
	v_pk_add_f32 v[18:19], v[18:19], v[40:41]
	v_lshlrev_b32_e32 v40, 16, v47
	v_and_b32_e32 v41, 0xffff0000, v47
	v_mov_b32_dpp v33, v19 row_shr:4 row_mask:0xf bank_mask:0xf
	v_pk_add_f32 v[28:29], v[18:19], v[32:33]
	v_pk_mul_f32 v[40:41], v[40:41], s[8:9] op_sel_hi:[1,0]
	v_add_f32_e32 v7, v28, v25
	v_mul_f32_e32 v11, 0x3fb8aa3b, v7
	v_exp_f32_e32 v13, v11
	v_add_f32_e32 v11, v18, v143
	v_mov_b32_e32 v25, v211
	v_mul_f32_e32 v7, 0xbfb8aa3b, v7
	v_pk_mul_f32 v[32:33], v[12:13], v[116:117]
	v_pk_mul_f32 v[12:13], v[118:119], v[12:13]
	v_mov_b32_dpp v25, v29 row_shr:8 row_mask:0xf bank_mask:0xf
	v_cvt_pk_bf16_f32 v79, v12, v13
	v_mul_f32_e32 v12, 0x3fb8aa3b, v11
	v_exp_f32_e32 v17, v12
	v_mul_f32_e32 v11, 0xbfb8aa3b, v11
	v_exp_f32_e32 v37, v11
	v_exp_f32_e32 v35, v7
	v_pk_mul_f32 v[12:13], v[16:17], v[26:27]
	v_cvt_pk_bf16_f32 v87, v32, v33
	v_cvt_pk_bf16_f32 v101, v12, v13
	v_pk_mul_f32 v[12:13], v[36:37], v[26:27]
	v_pk_mul_f32 v[32:33], v[34:35], v[116:117]
	v_cvt_pk_bf16_f32 v11, v12, v13
	v_pk_mul_f32 v[12:13], v[30:31], v[36:37]
	v_cvt_pk_bf16_f32 v7, v32, v33
	v_cvt_pk_bf16_f32 v95, v12, v13
	v_pk_mul_f32 v[12:13], v[30:31], v[16:17]
	v_lshlrev_b32_e32 v30, 16, v49
	v_cvt_pk_bf16_f32 v91, v12, v13
	v_pk_add_f32 v[12:13], v[28:29], v[24:25]
	v_lshlrev_b32_e32 v24, 16, v48
	v_add_f32_e32 v39, v12, v13
	v_mul_f32_e32 v12, 0x3fb8aa3b, v14
	v_exp_f32_e32 v16, v12
	v_mul_f32_e32 v12, 0xbfb8aa3b, v14
	v_exp_f32_e32 v14, v12
	v_mul_f32_e32 v12, 0x3fb8aa3b, v15
	v_exp_f32_e32 v17, v12
	v_mul_f32_e32 v12, 0xbfb8aa3b, v15
	v_exp_f32_e32 v15, v12
	v_lshlrev_b32_e32 v12, 16, v50
	v_and_b32_e32 v13, 0xffff0000, v50
	v_pk_mul_f32 v[18:19], v[12:13], s[8:9] op_sel_hi:[1,0]
	v_and_b32_e32 v25, 0xffff0000, v48
	v_pk_mul_f32 v[12:13], v[18:19], v[16:17]
	v_pk_mul_f32 v[18:19], v[18:19], v[14:15]
	v_pk_mul_f32 v[26:27], v[14:15], v[24:25]
	v_mul_f32_e32 v15, 0xbfb8aa3b, v20
	v_mul_f32_e32 v14, 0x3fb8aa3b, v20
	v_exp_f32_e32 v20, v15
	v_mul_f32_e32 v15, 0x3fb8aa3b, v21
	v_mul_f32_e32 v21, 0xbfb8aa3b, v21
	v_exp_f32_e32 v14, v14
	v_exp_f32_e32 v15, v15
	v_exp_f32_e32 v21, v21
	v_pk_mul_f32 v[16:17], v[16:17], v[24:25]
	v_lshlrev_b32_e32 v24, 16, v51
	v_and_b32_e32 v25, 0xffff0000, v51
	v_pk_mul_f32 v[24:25], v[24:25], s[8:9] op_sel_hi:[1,0]
	v_and_b32_e32 v31, 0xffff0000, v49
	v_pk_mul_f32 v[28:29], v[24:25], v[14:15]
	v_pk_mul_f32 v[24:25], v[24:25], v[20:21]
	v_pk_mul_f32 v[20:21], v[20:21], v[30:31]
	v_pk_mul_f32 v[30:31], v[14:15], v[30:31]
	v_mul_f32_e32 v15, 0xbfb8aa3b, v22
	v_mul_f32_e32 v14, 0x3fb8aa3b, v22
	v_exp_f32_e32 v22, v15
; template <bool GLA>
; __device__ __forceinline__ void chunk_pass_c(const ChunkIn& ci, const float* wgl, int unit, unsigned char* wl, int lane, const float* Sb, const float* ng, bf16_t* omix) {
;     ...
;         float a[8], bneg[8], cpos[8], dneg[8];
; #pragma unroll
;         for (int j = 0; j < 8; ++j) { const float eb = __expf(bq[j]), enb = __expf(-bq[j]); a[j] = qv[j] * eb; bneg[j] = kv[j] * enb; cpos[j] = qv[j] * enb; dneg[j] = kv[j] * eb; }
;         qf[it] = __builtin_bit_cast(bf16x8, (u32x4){cvtpk(a[0], a[1]), cvtpk(a[2], a[3]), cvtpk(a[4], a[5]), cvtpk(a[6], a[7])});
;         kf[it] = __builtin_bit_cast(bf16x8, (u32x4){cvtpk(bneg[0], bneg[1]), cvtpk(bneg[2], bneg[3]), cvtpk(bneg[4], bneg[5]), cvtpk(bneg[6], bneg[7])});
;         qb[it] = __builtin_bit_cast(bf16x8, (u32x4){cvtpk(cpos[0], cpos[1]), cvtpk(cpos[2], cpos[3]), cvtpk(cpos[4], cpos[5]), cvtpk(cpos[6], cpos[7])});
;         kb[it] = __builtin_bit_cast(bf16x8, (u32x4){cvtpk(dneg[0], dneg[1]), cvtpk(dneg[2], dneg[3]), cvtpk(dneg[4], dneg[5]), cvtpk(dneg[6], dneg[7])});
;         asm volatile("" ::: "memory");
;     }
;     __builtin_amdgcn_s_waitcnt(0); asm volatile("" ::: "memory");
;     bf16x8 vfr[4][2], sfr[4];
; #pragma unroll
;     for (int et = 0; et < 4; ++et) {
; #pragma unroll
;         for (int p = 0; p < 2; ++p) {
;             const u32x2 lo = *(const u32x2*)(wl + (16 * et + row) * GP + (32 * p + 4 * kq) * 2), hh = *(const u32x2*)(wl + (16 * et + row) * GP + (32 * p + 16 + 4 * kq) * 2);
;             vfr[et][p] = __builtin_bit_cast(bf16x8, (u32x4){lo.x, lo.y, hh.x, hh.y});
;         }
;         sfr[et] = *(const bf16x8*)(sst + (16 * et + row) * 64 + kq * 16);
;     }
;     const int gcol = (GLA ? C_GR : C_RG) + h * 64, ocol = (GLA ? 512 : 768) + h * 64;
;     float gn[4];
; #pragma unroll
;     for (int et = 0; et < 4; ++et) gn[et] = ng[16 * et + row];
; #pragma unroll
;     for (int it = 0; it < 4; ++it) {
;         f32x4 st[4];
; #pragma unroll
;         for (int jt = 0; jt < 4; ++jt) {
;             const f32x4 z = {0.f, 0.f, 0.f, 0.f};
;             if (jt < it) st[jt] = __builtin_amdgcn_mfma_f32_16x16x32_bf16(kf[jt], qf[it], z, 0, 0, 0);
;             else if (jt > it) st[jt] = __builtin_amdgcn_mfma_f32_16x16x32_bf16(kb[jt], qb[it], z, 0, 0, 0);
;             else {
	v_mul_f32_e32 v15, 0x3fb8aa3b, v23
	v_mul_f32_e32 v23, 0xbfb8aa3b, v23
	v_exp_f32_e32 v14, v14
	v_exp_f32_e32 v15, v15
	v_exp_f32_e32 v23, v23
	v_pk_mul_f32 v[32:33], v[118:119], v[34:35]
	v_lshlrev_b32_e32 v36, 16, v44
	v_cvt_pk_bf16_f32 v83, v32, v33
	v_lshlrev_b32_e32 v32, 16, v46
	v_and_b32_e32 v33, 0xffff0000, v46
	v_pk_mul_f32 v[32:33], v[32:33], s[8:9] op_sel_hi:[1,0]
	v_and_b32_e32 v37, 0xffff0000, v44
	v_pk_mul_f32 v[34:35], v[32:33], v[14:15]
	v_pk_mul_f32 v[32:33], v[32:33], v[22:23]
	v_pk_mul_f32 v[22:23], v[22:23], v[36:37]
	v_pk_mul_f32 v[36:37], v[14:15], v[36:37]
	v_mul_f32_e32 v15, 0xbfb8aa3b, v38
	v_mul_f32_e32 v14, 0x3fb8aa3b, v38
	v_exp_f32_e32 v38, v15
	v_mul_f32_e32 v15, 0x3fb8aa3b, v39
	v_mul_f32_e32 v39, 0xbfb8aa3b, v39
	v_exp_f32_e32 v14, v14
	v_exp_f32_e32 v15, v15
	v_exp_f32_e32 v39, v39
	v_cvt_pk_bf16_f32 v72, v16, v17
	v_mul_u32_u24_e32 v17, 0x90, v156
	v_lshlrev_b32_e32 v44, 16, v45
	v_and_b32_e32 v45, 0xffff0000, v45
	v_lshlrev_b32_e32 v16, 6, v156
	v_add3_u32 v17, s3, v17, v114
	v_pk_mul_f32 v[42:43], v[40:41], v[14:15]
	v_pk_mul_f32 v[40:41], v[40:41], v[38:39]
	v_pk_mul_f32 v[38:39], v[38:39], v[44:45]
	v_pk_mul_f32 v[44:45], v[14:15], v[44:45]
	v_cvt_pk_bf16_f32 v52, v18, v19
	ds_read2_b64 v[64:67], v17 offset1:4
	ds_read2_b64 v[60:63], v17 offset0:8 offset1:12
	v_add3_u32 v16, s3, v142, v16
	v_add_u32_e32 v18, 0x800, v17
	v_add_u32_e32 v17, 0x1000, v17
	v_or_b32_e32 v142, 48, v147
	v_cvt_pk_bf16_f32 v12, v12, v13
	v_cvt_pk_bf16_f32 v13, v28, v29
	v_cvt_pk_bf16_f32 v14, v34, v35
	v_cvt_pk_bf16_f32 v15, v42, v43
	v_cvt_pk_bf16_f32 v59, v38, v39
	v_cvt_pk_bf16_f32 v54, v32, v33
	v_cvt_pk_bf16_f32 v55, v40, v41
	v_cvt_pk_bf16_f32 v73, v30, v31
	v_cvt_pk_bf16_f32 v74, v36, v37
	v_cvt_pk_bf16_f32 v75, v44, v45
	ds_read_b128 v[68:71], v16 offset:9216
	ds_read2_b64 v[48:51], v18 offset0:32 offset1:36
	ds_read2_b64 v[44:47], v18 offset0:40 offset1:44
	ds_read_b128 v[40:43], v16 offset:10240
	ds_read2_b64 v[36:39], v17 offset0:64 offset1:68
	ds_read2_b64 v[32:35], v17 offset0:72 offset1:76
	ds_read_b128 v[28:31], v16 offset:11264
	v_mul_u32_u24_e32 v17, 0x90, v142
	v_add3_u32 v17, s3, v17, v114
	v_lshlrev_b32_e32 v114, 2, v142
	v_cvt_pk_bf16_f32 v56, v26, v27
	v_cvt_pk_bf16_f32 v57, v20, v21
	v_cvt_pk_bf16_f32 v58, v22, v23
	v_cvt_pk_bf16_f32 v53, v24, v25
	ds_read2_b64 v[24:27], v17 offset1:4
	ds_read2_b64 v[20:23], v17 offset0:8 offset1:12
	ds_read_b128 v[16:19], v16 offset:12288
	global_load_dword v149, v115, s[44:45]
	global_load_dword v148, v115, s[44:45] offset:64
	global_load_dword v147, v115, s[44:45] offset:128
	global_load_dword v146, v114, s[44:45]
	v_mfma_f32_16x16x32_bf16 v[114:117], v[0:3], v[102:105], 0
	s_mov_b32 s6, 0x358637bd
	v_mfma_f32_16x16x32_bf16 v[56:59], v[56:59], v[12:15], 0
	v_mfma_f32_16x16x32_bf16 v[52:55], v[72:75], v[52:55], 0
	s_nop 4
	v_cndmask_b32_e32 v118, v114, v106, vcc
	v_or_b32_e32 v106, 2, v97
	v_cmp_gt_u32_e64 s[44:45], v106, v156
	v_or_b32_e32 v106, 3, v97
	v_cmp_gt_u32_e64 s[46:47], v106, v156
	v_cndmask_b32_e64 v119, v107, v115, s[42:43]
	v_cndmask_b32_e64 v120, v116, v108, s[44:45]
	v_cndmask_b32_e64 v121, v117, v109, s[46:47]
	v_mfma_f32_16x16x32_bf16 v[106:109], v[98:101], v[110:113], 0
	v_cvt_pk_bf16_f32 v122, v118, v119
	v_cvt_pk_bf16_f32 v123, v120, v121
	v_cndmask_b32_e64 v59, v59, v55, s[46:47]
	v_mfma_f32_16x16x32_bf16 v[114:117], v[84:87], v[110:113], 0
	v_cndmask_b32_e32 v56, v56, v52, vcc
	s_nop 2
	v_cvt_pk_bf16_f32 v124, v106, v107
	v_cvt_pk_bf16_f32 v125, v108, v109
	v_mfma_f32_16x16x32_bf16 v[110:113], v[72:75], v[110:113], 0
	v_cndmask_b32_e64 v57, v53, v57, s[42:43]
	v_cvt_pk_bf16_f32 v130, v114, v115
	v_cvt_pk_bf16_f32 v131, v116, v117
	s_waitcnt lgkmcnt(11)
	v_mfma_f32_16x16x32_bf16 v[106:109], v[122:125], v[64:67], 0
	v_cndmask_b32_e64 v58, v58, v54, s[44:45]
	s_nop 1
	v_cvt_pk_bf16_f32 v132, v110, v111
	v_cvt_pk_bf16_f32 v133, v112, v113
	v_mfma_f32_16x16x32_bf16 v[98:101], v[98:101], v[92:95], 0
	s_waitcnt lgkmcnt(10)
	v_mfma_f32_16x16x32_bf16 v[106:109], v[130:133], v[60:63], v[106:109]
	s_waitcnt lgkmcnt(9)
	v_mfma_f32_16x16x32_bf16 v[114:117], v[102:105], v[68:71], v[106:109]
	s_waitcnt lgkmcnt(8)
	v_mfma_f32_16x16x32_bf16 v[106:109], v[122:125], v[48:51], 0
	s_waitcnt lgkmcnt(7)
	v_mfma_f32_16x16x32_bf16 v[106:109], v[130:133], v[44:47], v[106:109]
	s_nop 3
	v_mov_b32_e32 v110, v114
	s_waitcnt lgkmcnt(6)
	v_mfma_f32_16x16x32_bf16 v[106:109], v[102:105], v[40:43], v[106:109]
	s_nop 7
	v_mov_b32_e32 v111, v106
	v_pk_mul_f32 v[120:121], v[110:111], v[110:111]
	v_mov_b32_e32 v110, v115
	v_mov_b32_e32 v111, v107
	v_pk_mul_f32 v[134:135], v[110:111], v[110:111]
	v_mov_b32_e32 v110, v116
	v_mov_b32_e32 v111, v108
	v_pk_mul_f32 v[126:127], v[110:111], v[110:111]
	v_mov_b32_e32 v110, v117
	v_mov_b32_e32 v111, v109
	v_pk_mul_f32 v[128:129], v[110:111], v[110:111]
	s_waitcnt lgkmcnt(5)
	v_mfma_f32_16x16x32_bf16 v[110:113], v[122:125], v[36:39], 0
	s_waitcnt lgkmcnt(2)
	v_mfma_f32_16x16x32_bf16 v[122:125], v[122:125], v[24:27], 0
	v_mfma_f32_16x16x32_bf16 v[110:113], v[130:133], v[32:35], v[110:113]
	s_waitcnt lgkmcnt(1)
	v_mfma_f32_16x16x32_bf16 v[122:125], v[130:133], v[20:23], v[122:125]
	v_mfma_f32_16x16x32_bf16 v[110:113], v[102:105], v[28:31], v[110:113]
	s_waitcnt lgkmcnt(0)
; __device__ __forceinline__ unsigned cvtpk(float lo, float hi) { f32x2_t v = {lo, hi}; bf16x2_t b = __builtin_convertvector(v, bf16x2_t); return __builtin_bit_cast(unsigned, b); }
; template <int X> __device__ __forceinline__ float swz_xor(float v) { return __int_as_float(__builtin_amdgcn_ds_swizzle(__float_as_int(v), (X << 10) | 0x1F)); }
; __device__ __forceinline__ float silu_f(float g) { return g * __builtin_amdgcn_rcpf(1.0f + __expf(-g)); }
; template <bool GLA>
; __device__ __forceinline__ void chunk_pass_c(const ChunkIn& ci, const float* wgl, int unit, unsigned char* wl, int lane, const float* Sb, const float* ng, bf16_t* omix) {
;     ...
;         f32x4 o[4]; float ss[4] = {0.f, 0.f, 0.f, 0.f};
; #pragma unroll
;         for (int et = 0; et < 4; ++et) {
;             f32x4 acc = {0.f, 0.f, 0.f, 0.f};
;             acc = __builtin_amdgcn_mfma_f32_16x16x32_bf16(af[0], vfr[et][0], acc, 0, 0, 0);
;             acc = __builtin_amdgcn_mfma_f32_16x16x32_bf16(af[1], vfr[et][1], acc, 0, 0, 0);
;             acc = __builtin_amdgcn_mfma_f32_16x16x32_bf16(qf[it], sfr[et], acc, 0, 0, 0);
;             o[et] = acc;
; #pragma unroll
;             for (int r = 0; r < 4; ++r) ss[r] += acc[r] * acc[r];
;         }
; #pragma unroll
;         for (int r = 0; r < 4; ++r) {
;             ss[r] += swz_xor<1>(ss[r]); ss[r] += swz_xor<2>(ss[r]); ss[r] += swz_xor<4>(ss[r]); ss[r] += swz_xor<8>(ss[r]);
;             const float rs = rsqrtf(ss[r] * (1.0f / 64.0f) + EPS);
;             const int t = t0 + 16 * it + 4 * kq + r;
; #pragma unroll
;             for (int et = 0; et < 4; ++et) {
;                 const int e = 16 * et + row;
;                 const float gt = __uint_as_float((unsigned)ci.proj[(size_t)t * DINP + gcol + e] << 16);
;                 const float val = o[et][r] * rs * gn[et] * pg8::silu_f(gt);
;                 omix[(size_t)t * 1024 + ocol + e] = (bf16_t)(cvtpk(val, 0.f) & 0xffffu);
;             }
;         }
	v_mfma_f32_16x16x32_bf16 v[102:105], v[102:105], v[16:19], v[122:125]
	s_nop 4
	v_or_b32_e32 v122, s5, v97
	v_mov_b32_e32 v118, v110
	s_nop 0
	v_mov_b32_e32 v119, v102
	v_pk_mul_f32 v[136:137], v[118:119], v[118:119]
	v_mov_b32_e32 v118, v111
	v_mov_b32_e32 v119, v103
	v_pk_mul_f32 v[138:139], v[118:119], v[118:119]
	v_mov_b32_e32 v118, v112
	v_mov_b32_e32 v119, v104
	v_pk_mul_f32 v[124:125], v[118:119], v[118:119]
	v_mov_b32_e32 v118, v113
	v_mov_b32_e32 v119, v105
	v_ashrrev_i32_e32 v123, 31, v122
	v_pk_mul_f32 v[130:131], v[118:119], v[118:119]
	v_lshlrev_b64 v[118:119], 12, v[122:123]
	v_lshl_add_u64 v[132:133], s[58:59], 0, v[118:119]
	v_lshlrev_b64 v[118:119], 11, v[122:123]
	v_lshl_add_u64 v[144:145], v[132:133], 0, v[210:211]
	v_lshl_add_u64 v[150:151], s[60:61], 0, v[118:119]
	v_lshl_add_u64 v[140:141], v[150:151], 0, v[210:211]
	s_waitcnt vmcnt(0)
	v_mov_b32_e32 v118, v157
	v_lshlrev_b32_e32 v118, 16, v118
	v_mul_f32_e32 v119, 0xbfb8aa3b, v118
	v_exp_f32_e32 v119, v119
	s_nop 0
	v_add_f32_e32 v119, 1.0, v119
	v_rcp_f32_e32 v119, v119
	s_nop 0
	v_mul_f32_e32 v123, v119, v118
	v_lshlrev_b32_e32 v118, 1, v142
	v_mov_b32_e32 v119, v211
	v_lshl_add_u64 v[142:143], v[132:133], 0, v[118:119]
	v_lshl_add_u64 v[132:133], v[150:151], 0, v[118:119]
	v_mov_b32_e32 v150, v134
	v_mov_b32_e32 v151, v120
	v_mov_b32_e32 v120, v135
	v_pk_add_f32 v[120:121], v[150:151], v[120:121]
	v_mov_b32_e32 v134, v138
	v_mov_b32_e32 v135, v136
	v_pk_add_f32 v[120:121], v[120:121], v[134:135]
	v_mov_b32_e32 v136, v139
	v_pk_add_f32 v[120:121], v[120:121], v[136:137]
	ds_swizzle_b32 v135, v121 offset:swizzle(SWAP,1)
	ds_swizzle_b32 v134, v120 offset:swizzle(SWAP,1)
	s_waitcnt lgkmcnt(0)
	v_pk_add_f32 v[120:121], v[120:121], v[134:135]
	ds_swizzle_b32 v135, v121 offset:swizzle(SWAP,2)
	ds_swizzle_b32 v134, v120 offset:swizzle(SWAP,2)
	s_waitcnt lgkmcnt(0)
	v_pk_add_f32 v[120:121], v[120:121], v[134:135]
	ds_swizzle_b32 v135, v121 offset:swizzle(SWAP,4)
	ds_swizzle_b32 v134, v120 offset:swizzle(SWAP,4)
	s_waitcnt lgkmcnt(0)
	v_pk_add_f32 v[120:121], v[120:121], v[134:135]
	ds_swizzle_b32 v135, v121 offset:swizzle(SWAP,8)
	ds_swizzle_b32 v134, v120 offset:swizzle(SWAP,8)
	s_waitcnt lgkmcnt(0)
	v_pk_add_f32 v[134:135], v[120:121], v[134:135]
	v_mov_b64_e32 v[120:121], s[6:7]
	s_mov_b32 s6, 0x3c800000
	v_pk_fma_f32 v[134:135], v[134:135], s[6:7], v[120:121] op_sel_hi:[1,0,0]
	s_nop 0
	v_mul_f32_e32 v136, 0x4b800000, v135
	v_cmp_gt_f32_e64 s[50:51], s96, v135
	v_cmp_gt_f32_e64 s[48:49], s96, v134
	s_nop 0
	v_cndmask_b32_e64 v135, v135, v136, s[50:51]
	v_rsq_f32_e32 v135, v135
	s_nop 0
	v_mul_f32_e32 v136, 0x45800000, v135
	v_cndmask_b32_e64 v135, v135, v136, s[50:51]
	v_mul_f32_e32 v114, v114, v135
	v_mul_f32_e32 v114, v149, v114
	v_mul_f32_e32 v114, v123, v114
	v_cvt_pk_bf16_f32 v114, v114, s0
	global_store_short v[140:141], v114, off offset:1024
	v_mul_f32_e32 v106, v106, v135
	v_mul_f32_e32 v106, v148, v106
	v_mul_f32_e32 v110, v110, v135
	v_mul_f32_e32 v110, v147, v110
	v_mul_f32_e32 v102, v102, v135
	v_mul_f32_e32 v102, v146, v102
	s_waitcnt vmcnt(63)
	v_mov_b32_e32 v114, v158
	v_lshlrev_b32_e32 v114, 16, v114
	v_mul_f32_e32 v123, 0xbfb8aa3b, v114
	v_exp_f32_e32 v123, v123
	s_nop 0
	v_add_f32_e32 v123, 1.0, v123
	v_rcp_f32_e32 v123, v123
	s_nop 0
	v_mul_f32_e32 v114, v123, v114
	v_mul_f32_e32 v106, v114, v106
	v_cvt_pk_bf16_f32 v106, v106, s0
	global_store_short v[140:141], v106, off offset:1056
	s_waitcnt vmcnt(63)
	v_mov_b32_e32 v106, v159
	v_lshlrev_b32_e32 v106, 16, v106
	v_mul_f32_e32 v114, 0xbfb8aa3b, v106
	v_exp_f32_e32 v114, v114
	s_nop 0
	v_add_f32_e32 v114, 1.0, v114
	v_rcp_f32_e32 v114, v114
	s_nop 0
	v_mul_f32_e32 v106, v114, v106
	v_mul_f32_e32 v106, v110, v106
	v_cvt_pk_bf16_f32 v106, v106, s0
	global_store_short v[140:141], v106, off offset:1088
	s_waitcnt vmcnt(63)
	v_mov_b32_e32 v106, v160
	v_lshlrev_b32_e32 v106, 16, v106
	v_mul_f32_e32 v110, 0xbfb8aa3b, v106
	v_exp_f32_e32 v110, v110
	s_nop 0
	v_add_f32_e32 v110, 1.0, v110
	v_rcp_f32_e32 v110, v110
	s_nop 0
	v_mul_f32_e32 v106, v110, v106
	v_mul_f32_e32 v102, v102, v106
	v_cvt_pk_bf16_f32 v102, v102, s0
	global_store_short v[132:133], v102, off offset:1024
	v_mul_f32_e32 v102, 0x4b800000, v134
	v_cndmask_b32_e64 v102, v134, v102, s[48:49]
	v_rsq_f32_e32 v102, v102
	v_or_b32_e32 v132, 1, v122
	v_ashrrev_i32_e32 v133, 31, v132
	v_lshlrev_b64 v[134:135], 12, v[132:133]
	v_lshl_add_u64 v[134:135], s[58:59], 0, v[134:135]
	v_mul_f32_e32 v106, 0x45800000, v102
	v_lshl_add_u64 v[136:137], v[134:135], 0, v[210:211]
	v_cndmask_b32_e64 v102, v102, v106, s[48:49]
	v_mul_f32_e32 v110, v115, v102
	v_lshlrev_b64 v[132:133], 11, v[132:133]
	v_mul_f32_e32 v110, v149, v110
	v_lshl_add_u64 v[132:133], s[60:61], 0, v[132:133]
	v_mul_f32_e32 v107, v107, v102
	v_mul_f32_e32 v107, v148, v107
	s_waitcnt vmcnt(63)
	v_mov_b32_e32 v106, v161
	v_lshlrev_b32_e32 v106, 16, v106
	v_mul_f32_e32 v114, 0xbfb8aa3b, v106
	v_exp_f32_e32 v114, v114
	s_nop 0
	v_add_f32_e32 v114, 1.0, v114
	v_rcp_f32_e32 v114, v114
	s_nop 0
	v_mul_f32_e32 v106, v114, v106
	v_mul_f32_e32 v106, v106, v110
	v_cvt_pk_bf16_f32 v106, v106, s0
	v_lshl_add_u64 v[114:115], v[132:133], 0, v[210:211]
	global_store_short v[114:115], v106, off offset:1024
	s_waitcnt vmcnt(63)
	v_mov_b32_e32 v106, v162
	v_lshlrev_b32_e32 v106, 16, v106
	v_mul_f32_e32 v110, 0xbfb8aa3b, v106
	v_exp_f32_e32 v110, v110
	s_nop 0
	v_add_f32_e32 v110, 1.0, v110
	v_rcp_f32_e32 v110, v110
	s_nop 0
	v_mul_f32_e32 v106, v110, v106
	v_mul_f32_e32 v106, v107, v106
	v_cvt_pk_bf16_f32 v106, v106, s0
	global_store_short v[114:115], v106, off offset:1056
	v_mul_f32_e32 v107, v111, v102
	v_mul_f32_e32 v107, v147, v107
	v_mul_f32_e32 v102, v103, v102
	v_mul_f32_e32 v102, v146, v102
	s_waitcnt vmcnt(63)
; __device__ __forceinline__ unsigned cvtpk(float lo, float hi) { f32x2_t v = {lo, hi}; bf16x2_t b = __builtin_convertvector(v, bf16x2_t); return __builtin_bit_cast(unsigned, b); }
; template <int X> __device__ __forceinline__ float swz_xor(float v) { return __int_as_float(__builtin_amdgcn_ds_swizzle(__float_as_int(v), (X << 10) | 0x1F)); }
; __device__ __forceinline__ float silu_f(float g) { return g * __builtin_amdgcn_rcpf(1.0f + __expf(-g)); }
; template <bool GLA>
; __device__ __forceinline__ void chunk_pass_c(const ChunkIn& ci, const float* wgl, int unit, unsigned char* wl, int lane, const float* Sb, const float* ng, bf16_t* omix) {
;     ...
;         for (int r = 0; r < 4; ++r) {
;             ss[r] += swz_xor<1>(ss[r]); ss[r] += swz_xor<2>(ss[r]); ss[r] += swz_xor<4>(ss[r]); ss[r] += swz_xor<8>(ss[r]);
;             const float rs = rsqrtf(ss[r] * (1.0f / 64.0f) + EPS);
;             const int t = t0 + 16 * it + 4 * kq + r;
; #pragma unroll
;             for (int et = 0; et < 4; ++et) {
;                 const int e = 16 * et + row;
;                 const float gt = __uint_as_float((unsigned)ci.proj[(size_t)t * DINP + gcol + e] << 16);
;                 const float val = o[et][r] * rs * gn[et] * pg8::silu_f(gt);
;                 omix[(size_t)t * 1024 + ocol + e] = (bf16_t)(cvtpk(val, 0.f) & 0xffffu);
;             }
;         }
	v_mov_b32_e32 v106, v163
	v_lshlrev_b32_e32 v106, 16, v106
	v_mul_f32_e32 v110, 0xbfb8aa3b, v106
	v_exp_f32_e32 v110, v110
	s_nop 0
	v_add_f32_e32 v110, 1.0, v110
	v_rcp_f32_e32 v110, v110
	s_nop 0
	v_mul_f32_e32 v106, v110, v106
	v_mul_f32_e32 v106, v107, v106
	v_cvt_pk_bf16_f32 v106, v106, s0
	global_store_short v[114:115], v106, off offset:1088
	v_lshl_add_u64 v[106:107], v[134:135], 0, v[118:119]
	s_waitcnt vmcnt(63)
	v_mov_b32_e32 v106, v164
	v_lshlrev_b32_e32 v106, 16, v106
	v_mul_f32_e32 v103, 0xbfb8aa3b, v106
	v_exp_f32_e32 v103, v103
	s_nop 0
	v_add_f32_e32 v103, 1.0, v103
	v_rcp_f32_e32 v103, v103
	s_nop 0
	v_mul_f32_e32 v103, v103, v106
	v_mul_f32_e32 v102, v102, v103
	v_cvt_pk_bf16_f32 v106, v102, s0
	v_lshl_add_u64 v[102:103], v[132:133], 0, v[118:119]
	global_store_short v[102:103], v106, off offset:1024
	v_or_b32_e32 v102, 2, v122
	v_ashrrev_i32_e32 v103, 31, v102
	v_lshlrev_b64 v[106:107], 12, v[102:103]
	v_lshl_add_u64 v[106:107], s[58:59], 0, v[106:107]
	v_lshl_add_u64 v[110:111], v[106:107], 0, v[210:211]
	v_mov_b32_e32 v132, v128
	v_mov_b32_e32 v133, v126
	v_mov_b32_e32 v126, v129
	v_pk_add_f32 v[126:127], v[132:133], v[126:127]
	v_mov_b32_e32 v128, v130
	v_mov_b32_e32 v129, v124
	v_pk_add_f32 v[126:127], v[126:127], v[128:129]
	v_mov_b32_e32 v124, v131
	v_pk_add_f32 v[124:125], v[126:127], v[124:125]
	ds_swizzle_b32 v127, v125 offset:swizzle(SWAP,1)
	ds_swizzle_b32 v126, v124 offset:swizzle(SWAP,1)
	v_lshlrev_b64 v[102:103], 11, v[102:103]
	v_lshl_add_u64 v[102:103], s[60:61], 0, v[102:103]
	v_lshl_add_u64 v[106:107], v[106:107], 0, v[118:119]
	s_waitcnt lgkmcnt(0)
	v_pk_add_f32 v[124:125], v[124:125], v[126:127]
	ds_swizzle_b32 v127, v125 offset:swizzle(SWAP,2)
	ds_swizzle_b32 v126, v124 offset:swizzle(SWAP,2)
	s_waitcnt lgkmcnt(0)
	v_pk_add_f32 v[124:125], v[124:125], v[126:127]
	ds_swizzle_b32 v127, v125 offset:swizzle(SWAP,4)
	ds_swizzle_b32 v126, v124 offset:swizzle(SWAP,4)
	s_waitcnt lgkmcnt(0)
	v_pk_add_f32 v[124:125], v[124:125], v[126:127]
	ds_swizzle_b32 v127, v125 offset:swizzle(SWAP,8)
	ds_swizzle_b32 v126, v124 offset:swizzle(SWAP,8)
	s_waitcnt lgkmcnt(0)
	v_pk_add_f32 v[124:125], v[124:125], v[126:127]
	s_nop 0
	v_pk_fma_f32 v[124:125], v[124:125], s[6:7], v[120:121] op_sel_hi:[1,0,0]
	s_waitcnt vmcnt(63)
	v_mov_b32_e32 v114, v165
	v_lshlrev_b32_e32 v114, 16, v114
	v_mul_f32_e32 v115, 0xbfb8aa3b, v114
	v_exp_f32_e32 v115, v115
	v_mul_f32_e32 v126, 0x4b800000, v125
	v_cmp_gt_f32_e64 s[50:51], s96, v125
	v_cmp_gt_f32_e64 s[48:49], s96, v124
	v_add_f32_e32 v115, 1.0, v115
	v_cndmask_b32_e64 v125, v125, v126, s[50:51]
	v_rsq_f32_e32 v125, v125
	v_rcp_f32_e32 v115, v115
	v_mul_f32_e32 v126, 0x45800000, v125
	v_cndmask_b32_e64 v125, v125, v126, s[50:51]
	v_mul_f32_e32 v116, v116, v125
	v_mul_f32_e32 v123, v115, v114
	v_mul_f32_e32 v116, v149, v116
	v_mul_f32_e32 v116, v123, v116
	v_lshl_add_u64 v[114:115], v[102:103], 0, v[210:211]
	v_cvt_pk_bf16_f32 v116, v116, s0
	global_store_short v[114:115], v116, off offset:1024
	v_mul_f32_e32 v108, v108, v125
	v_mul_f32_e32 v108, v148, v108
	v_mul_f32_e32 v104, v104, v125
	v_mul_f32_e32 v104, v146, v104
	v_lshl_add_u64 v[102:103], v[102:103], 0, v[118:119]
	s_waitcnt vmcnt(63)
	v_mov_b32_e32 v116, v166
	v_lshlrev_b32_e32 v116, 16, v116
	v_mul_f32_e32 v123, 0xbfb8aa3b, v116
	v_exp_f32_e32 v123, v123
	s_nop 0
	v_add_f32_e32 v123, 1.0, v123
	v_rcp_f32_e32 v123, v123
	s_nop 0
	v_mul_f32_e32 v116, v123, v116
	v_mul_f32_e32 v108, v108, v116
	v_cvt_pk_bf16_f32 v108, v108, s0
	global_store_short v[114:115], v108, off offset:1056
	v_mul_f32_e32 v110, v112, v125
	v_mul_f32_e32 v110, v147, v110
	s_waitcnt vmcnt(63)
	v_mov_b32_e32 v108, v167
	v_lshlrev_b32_e32 v108, 16, v108
	v_mul_f32_e32 v111, 0xbfb8aa3b, v108
	v_exp_f32_e32 v111, v111
	s_nop 0
	v_add_f32_e32 v111, 1.0, v111
	v_rcp_f32_e32 v111, v111
	s_nop 0
	v_mul_f32_e32 v108, v111, v108
	v_mul_f32_e32 v108, v110, v108
	v_cvt_pk_bf16_f32 v108, v108, s0
	global_store_short v[114:115], v108, off offset:1088
	s_waitcnt vmcnt(63)
	v_mov_b32_e32 v106, v168
	v_lshlrev_b32_e32 v106, 16, v106
	v_mul_f32_e32 v107, 0xbfb8aa3b, v106
	v_exp_f32_e32 v107, v107
	s_nop 0
	v_add_f32_e32 v107, 1.0, v107
	v_rcp_f32_e32 v107, v107
	s_nop 0
	v_mul_f32_e32 v106, v107, v106
	v_mul_f32_e32 v104, v104, v106
	v_cvt_pk_bf16_f32 v104, v104, s0
	global_store_short v[102:103], v104, off offset:1024
	v_mul_f32_e32 v102, 0x4b800000, v124
	v_cndmask_b32_e64 v102, v124, v102, s[48:49]
	v_rsq_f32_e32 v102, v102
	s_nop 0
	v_mul_f32_e32 v103, 0x45800000, v102
	v_cndmask_b32_e64 v104, v102, v103, s[48:49]
	v_or_b32_e32 v102, 3, v122
	v_ashrrev_i32_e32 v103, 31, v102
	v_lshlrev_b64 v[106:107], 12, v[102:103]
	v_lshl_add_u64 v[106:107], s[58:59], 0, v[106:107]
	v_lshl_add_u64 v[110:111], v[106:107], 0, v[210:211]
	v_mul_f32_e32 v112, v117, v104
	v_lshlrev_b64 v[102:103], 11, v[102:103]
	v_mul_f32_e32 v112, v149, v112
	v_lshl_add_u64 v[102:103], s[60:61], 0, v[102:103]
	v_mul_f32_e32 v109, v109, v104
	v_mul_f32_e32 v109, v148, v109
	v_lshl_add_u64 v[106:107], v[106:107], 0, v[118:119]
	s_waitcnt vmcnt(63)
	v_mov_b32_e32 v108, v169
	v_lshlrev_b32_e32 v108, 16, v108
	v_mul_f32_e32 v114, 0xbfb8aa3b, v108
	v_exp_f32_e32 v114, v114
	s_nop 0
	v_add_f32_e32 v114, 1.0, v114
	v_rcp_f32_e32 v114, v114
	s_nop 0
	v_mul_f32_e32 v108, v114, v108
	v_mul_f32_e32 v108, v108, v112
	v_cvt_pk_bf16_f32 v108, v108, s0
	v_lshl_add_u64 v[114:115], v[102:103], 0, v[210:211]
	global_store_short v[114:115], v108, off offset:1024
	v_lshl_add_u64 v[102:103], v[102:103], 0, v[118:119]
	s_waitcnt vmcnt(63)
; template <bool GLA>
; __device__ __forceinline__ void chunk_pass_c(const ChunkIn& ci, const float* wgl, int unit, unsigned char* wl, int lane, const float* Sb, const float* ng, bf16_t* omix) {
;     ...
;         for (int jt = 0; jt < 4; ++jt) {
;             const f32x4 z = {0.f, 0.f, 0.f, 0.f};
;             if (jt < it) st[jt] = __builtin_amdgcn_mfma_f32_16x16x32_bf16(kf[jt], qf[it], z, 0, 0, 0);
;             else if (jt > it) st[jt] = __builtin_amdgcn_mfma_f32_16x16x32_bf16(kb[jt], qb[it], z, 0, 0, 0);
;             else {
;                 const f32x4 lo = __builtin_amdgcn_mfma_f32_16x16x32_bf16(kf[jt], qf[it], z, 0, 0, 0), up = __builtin_amdgcn_mfma_f32_16x16x32_bf16(kb[jt], qb[it], z, 0, 0, 0);
; #pragma unroll
;                 for (int r = 0; r < 4; ++r) st[jt][r] = (4 * kq + r <= row) ? lo[r] : up[r];
;             }
;         }
;         bf16x8 af[2];
; #pragma unroll
;         for (int p = 0; p < 2; ++p)
;             af[p] = __builtin_bit_cast(bf16x8, (u32x4){cvtpk(st[2 * p][0], st[2 * p][1]), cvtpk(st[2 * p][2], st[2 * p][3]), cvtpk(st[2 * p + 1][0], st[2 * p + 1][1]), cvtpk(st[2 * p + 1][2], st[2 * p + 1][3])});
;         f32x4 o[4]; float ss[4] = {0.f, 0.f, 0.f, 0.f};
; #pragma unroll
;         for (int et = 0; et < 4; ++et) {
;             f32x4 acc = {0.f, 0.f, 0.f, 0.f};
;             acc = __builtin_amdgcn_mfma_f32_16x16x32_bf16(af[0], vfr[et][0], acc, 0, 0, 0);
;             acc = __builtin_amdgcn_mfma_f32_16x16x32_bf16(af[1], vfr[et][1], acc, 0, 0, 0);
;             acc = __builtin_amdgcn_mfma_f32_16x16x32_bf16(qf[it], sfr[et], acc, 0, 0, 0);
;             o[et] = acc;
; #pragma unroll
;             for (int r = 0; r < 4; ++r) ss[r] += acc[r] * acc[r];
;         }
; #pragma unroll
;         for (int r = 0; r < 4; ++r) {
;             ss[r] += swz_xor<1>(ss[r]); ss[r] += swz_xor<2>(ss[r]); ss[r] += swz_xor<4>(ss[r]); ss[r] += swz_xor<8>(ss[r]);
;             const float rs = rsqrtf(ss[r] * (1.0f / 64.0f) + EPS);
;             const int t = t0 + 16 * it + 4 * kq + r;
; #pragma unroll
;             for (int et = 0; et < 4; ++et) {
;                 const int e = 16 * et + row;
;                 const float gt = __uint_as_float((unsigned)ci.proj[(size_t)t * DINP + gcol + e] << 16);
;                 const float val = o[et][r] * rs * gn[et] * pg8::silu_f(gt);
	v_mov_b32_e32 v108, v170
	v_lshlrev_b32_e32 v108, 16, v108
	v_mul_f32_e32 v112, 0xbfb8aa3b, v108
	v_exp_f32_e32 v112, v112
	s_nop 0
	v_add_f32_e32 v112, 1.0, v112
	v_rcp_f32_e32 v112, v112
	s_nop 0
	v_mul_f32_e32 v108, v112, v108
	v_mul_f32_e32 v108, v109, v108
	v_cvt_pk_bf16_f32 v108, v108, s0
	global_store_short v[114:115], v108, off offset:1056
	v_mul_f32_e32 v109, v113, v104
	v_mul_f32_e32 v109, v147, v109
	v_mul_f32_e32 v104, v105, v104
	v_mul_f32_e32 v104, v146, v104
	s_waitcnt vmcnt(63)
	v_mov_b32_e32 v108, v171
	v_lshlrev_b32_e32 v108, 16, v108
	v_mul_f32_e32 v110, 0xbfb8aa3b, v108
	v_exp_f32_e32 v110, v110
	s_nop 0
	v_add_f32_e32 v110, 1.0, v110
	v_rcp_f32_e32 v110, v110
	s_nop 0
	v_mul_f32_e32 v108, v110, v108
	v_mul_f32_e32 v108, v109, v108
	v_cvt_pk_bf16_f32 v108, v108, s0
	global_store_short v[114:115], v108, off offset:1088
	s_waitcnt vmcnt(63)
	v_mov_b32_e32 v106, v172
	v_lshlrev_b32_e32 v106, 16, v106
	v_mul_f32_e32 v105, 0xbfb8aa3b, v106
	v_exp_f32_e32 v105, v105
	s_nop 0
	v_add_f32_e32 v105, 1.0, v105
	v_rcp_f32_e32 v105, v105
	s_nop 0
	v_mul_f32_e32 v105, v105, v106
	v_mul_f32_e32 v104, v104, v105
	v_cvt_pk_bf16_f32 v104, v104, s0
	v_mfma_f32_16x16x32_bf16 v[106:109], v[8:11], v[88:91], 0
	global_store_short v[102:103], v104, off offset:1024
	v_mfma_f32_16x16x32_bf16 v[102:105], v[0:3], v[88:91], 0
	s_nop 5
	v_cndmask_b32_e32 v106, v106, v98, vcc
	v_cndmask_b32_e64 v107, v99, v107, s[42:43]
	v_cndmask_b32_e64 v108, v108, v100, s[44:45]
	v_cndmask_b32_e64 v109, v109, v101, s[46:47]
	v_mfma_f32_16x16x32_bf16 v[98:101], v[84:87], v[92:95], 0
	v_cvt_pk_bf16_f32 v110, v102, v103
	v_cvt_pk_bf16_f32 v111, v104, v105
	v_cvt_pk_bf16_f32 v112, v106, v107
	v_mfma_f32_16x16x32_bf16 v[92:95], v[72:75], v[92:95], 0
	v_cvt_pk_bf16_f32 v113, v108, v109
	s_nop 2
	v_cvt_pk_bf16_f32 v124, v98, v99
	v_cvt_pk_bf16_f32 v125, v100, v101
	v_mfma_f32_16x16x32_bf16 v[84:87], v[84:87], v[80:83], 0
	v_mfma_f32_16x16x32_bf16 v[80:83], v[72:75], v[80:83], 0
	v_cvt_pk_bf16_f32 v126, v92, v93
	v_cvt_pk_bf16_f32 v127, v94, v95
	v_mfma_f32_16x16x32_bf16 v[92:95], v[110:113], v[64:67], 0
	s_nop 0
	v_mfma_f32_16x16x32_bf16 v[92:95], v[124:127], v[60:63], v[92:95]
	v_mfma_f32_16x16x32_bf16 v[98:101], v[88:91], v[68:71], v[92:95]
	v_mfma_f32_16x16x32_bf16 v[92:95], v[110:113], v[48:51], 0
	v_mfma_f32_16x16x32_bf16 v[92:95], v[124:127], v[44:47], v[92:95]
	s_nop 5
	v_mov_b32_e32 v102, v98
	v_mfma_f32_16x16x32_bf16 v[92:95], v[88:91], v[40:43], v[92:95]
	s_nop 7
	v_mov_b32_e32 v103, v92
	v_pk_mul_f32 v[116:117], v[102:103], v[102:103]
	v_mov_b32_e32 v102, v99
	v_mov_b32_e32 v103, v93
	v_pk_mul_f32 v[122:123], v[102:103], v[102:103]
	v_mov_b32_e32 v102, v100
	v_mov_b32_e32 v103, v94
	v_pk_mul_f32 v[106:107], v[102:103], v[102:103]
	v_mov_b32_e32 v102, v101
	v_mov_b32_e32 v103, v95
	v_pk_mul_f32 v[108:109], v[102:103], v[102:103]
	v_mfma_f32_16x16x32_bf16 v[102:105], v[110:113], v[36:39], 0
	v_mfma_f32_16x16x32_bf16 v[110:113], v[110:113], v[24:27], 0
	v_mfma_f32_16x16x32_bf16 v[102:105], v[124:127], v[32:35], v[102:105]
	v_mfma_f32_16x16x32_bf16 v[110:113], v[124:127], v[20:23], v[110:113]
	v_mfma_f32_16x16x32_bf16 v[102:105], v[88:91], v[28:31], v[102:105]
	v_mfma_f32_16x16x32_bf16 v[88:91], v[88:91], v[16:19], v[110:113]
	s_nop 6
	v_mov_b32_e32 v110, v102
	v_mov_b32_e32 v111, v88
	v_pk_mul_f32 v[124:125], v[110:111], v[110:111]
	v_mov_b32_e32 v110, v103
	v_mov_b32_e32 v111, v89
	v_pk_mul_f32 v[126:127], v[110:111], v[110:111]
	v_mov_b32_e32 v110, v104
	v_mov_b32_e32 v111, v90
	v_pk_mul_f32 v[112:113], v[110:111], v[110:111]
	v_mov_b32_e32 v110, v105
	v_mov_b32_e32 v111, v91
	v_pk_mul_f32 v[114:115], v[110:111], v[110:111]
	v_or_b32_e32 v110, s4, v97
	v_ashrrev_i32_e32 v111, 31, v110
	v_lshlrev_b64 v[128:129], 12, v[110:111]
	v_lshl_add_u64 v[130:131], s[58:59], 0, v[128:129]
	v_lshlrev_b64 v[128:129], 11, v[110:111]
	v_lshl_add_u64 v[132:133], s[60:61], 0, v[128:129]
	v_lshl_add_u64 v[128:129], v[130:131], 0, v[210:211]
	v_lshl_add_u64 v[136:137], v[130:131], 0, v[118:119]
	v_lshl_add_u64 v[130:131], v[132:133], 0, v[118:119]
	s_waitcnt vmcnt(63)
	v_mov_b32_e32 v111, v173
	v_lshlrev_b32_e32 v111, 16, v111
	v_mul_f32_e32 v134, 0xbfb8aa3b, v111
	v_exp_f32_e32 v134, v134
	s_nop 0
	v_add_f32_e32 v134, 1.0, v134
	v_rcp_f32_e32 v134, v134
	s_nop 0
	v_mul_f32_e32 v111, v134, v111
	v_lshl_add_u64 v[134:135], v[132:133], 0, v[210:211]
	v_mov_b32_e32 v132, v122
	v_mov_b32_e32 v133, v116
	v_mov_b32_e32 v116, v123
	v_pk_add_f32 v[116:117], v[132:133], v[116:117]
	v_mov_b32_e32 v122, v126
	v_mov_b32_e32 v123, v124
	v_pk_add_f32 v[116:117], v[116:117], v[122:123]
	v_mov_b32_e32 v124, v127
	v_pk_add_f32 v[116:117], v[116:117], v[124:125]
	ds_swizzle_b32 v123, v117 offset:swizzle(SWAP,1)
	ds_swizzle_b32 v122, v116 offset:swizzle(SWAP,1)
	s_waitcnt lgkmcnt(0)
	v_pk_add_f32 v[116:117], v[116:117], v[122:123]
	ds_swizzle_b32 v123, v117 offset:swizzle(SWAP,2)
	ds_swizzle_b32 v122, v116 offset:swizzle(SWAP,2)
	s_waitcnt lgkmcnt(0)
	v_pk_add_f32 v[116:117], v[116:117], v[122:123]
	ds_swizzle_b32 v123, v117 offset:swizzle(SWAP,4)
	ds_swizzle_b32 v122, v116 offset:swizzle(SWAP,4)
	s_waitcnt lgkmcnt(0)
	v_pk_add_f32 v[116:117], v[116:117], v[122:123]
	ds_swizzle_b32 v123, v117 offset:swizzle(SWAP,8)
	ds_swizzle_b32 v122, v116 offset:swizzle(SWAP,8)
	s_waitcnt lgkmcnt(0)
; __device__ __forceinline__ unsigned cvtpk(float lo, float hi) { f32x2_t v = {lo, hi}; bf16x2_t b = __builtin_convertvector(v, bf16x2_t); return __builtin_bit_cast(unsigned, b); }
; template <int X> __device__ __forceinline__ float swz_xor(float v) { return __int_as_float(__builtin_amdgcn_ds_swizzle(__float_as_int(v), (X << 10) | 0x1F)); }
; __device__ __forceinline__ float silu_f(float g) { return g * __builtin_amdgcn_rcpf(1.0f + __expf(-g)); }
; template <bool GLA>
; __device__ __forceinline__ void chunk_pass_c(const ChunkIn& ci, const float* wgl, int unit, unsigned char* wl, int lane, const float* Sb, const float* ng, bf16_t* omix) {
;     ...
;         for (int r = 0; r < 4; ++r) {
;             ss[r] += swz_xor<1>(ss[r]); ss[r] += swz_xor<2>(ss[r]); ss[r] += swz_xor<4>(ss[r]); ss[r] += swz_xor<8>(ss[r]);
;             const float rs = rsqrtf(ss[r] * (1.0f / 64.0f) + EPS);
;             const int t = t0 + 16 * it + 4 * kq + r;
; #pragma unroll
;             for (int et = 0; et < 4; ++et) {
;                 const int e = 16 * et + row;
;                 const float gt = __uint_as_float((unsigned)ci.proj[(size_t)t * DINP + gcol + e] << 16);
;                 const float val = o[et][r] * rs * gn[et] * pg8::silu_f(gt);
;                 omix[(size_t)t * 1024 + ocol + e] = (bf16_t)(cvtpk(val, 0.f) & 0xffffu);
;             }
;         }
	v_pk_add_f32 v[116:117], v[116:117], v[122:123]
	s_nop 0
	v_pk_fma_f32 v[116:117], v[116:117], s[6:7], v[120:121] op_sel_hi:[1,0,0]
	s_nop 0
	v_mul_f32_e32 v122, 0x4b800000, v117
	v_cmp_gt_f32_e64 s[50:51], s96, v117
	v_cmp_gt_f32_e64 s[48:49], s96, v116
	s_nop 0
	v_cndmask_b32_e64 v117, v117, v122, s[50:51]
	v_rsq_f32_e32 v117, v117
	s_nop 0
	v_mul_f32_e32 v122, 0x45800000, v117
	v_cndmask_b32_e64 v117, v117, v122, s[50:51]
	v_mul_f32_e32 v98, v98, v117
	v_mul_f32_e32 v98, v149, v98
	v_mul_f32_e32 v98, v111, v98
	v_cvt_pk_bf16_f32 v98, v98, s0
	global_store_short v[134:135], v98, off offset:1024
	v_mul_f32_e32 v92, v92, v117
	v_mul_f32_e32 v92, v148, v92
	v_mul_f32_e32 v88, v88, v117
	v_mul_f32_e32 v88, v146, v88
	s_waitcnt vmcnt(63)
	v_mov_b32_e32 v98, v174
	v_lshlrev_b32_e32 v98, 16, v98
	v_mul_f32_e32 v111, 0xbfb8aa3b, v98
	v_exp_f32_e32 v111, v111
	s_nop 0
	v_add_f32_e32 v111, 1.0, v111
	v_rcp_f32_e32 v111, v111
	s_nop 0
	v_mul_f32_e32 v98, v111, v98
	v_mul_f32_e32 v92, v98, v92
	v_cvt_pk_bf16_f32 v92, v92, s0
	global_store_short v[134:135], v92, off offset:1056
	v_mul_f32_e32 v98, v102, v117
	v_mul_f32_e32 v98, v147, v98
	s_waitcnt vmcnt(63)
	v_mov_b32_e32 v92, v175
	v_lshlrev_b32_e32 v92, 16, v92
	v_mul_f32_e32 v102, 0xbfb8aa3b, v92
	v_exp_f32_e32 v102, v102
	s_nop 0
	v_add_f32_e32 v102, 1.0, v102
	v_rcp_f32_e32 v102, v102
	s_nop 0
	v_mul_f32_e32 v92, v102, v92
	v_mul_f32_e32 v92, v98, v92
	v_cvt_pk_bf16_f32 v92, v92, s0
	global_store_short v[134:135], v92, off offset:1088
	s_waitcnt vmcnt(63)
	v_mov_b32_e32 v92, v176
	v_lshlrev_b32_e32 v92, 16, v92
	v_mul_f32_e32 v98, 0xbfb8aa3b, v92
	v_exp_f32_e32 v98, v98
	s_nop 0
	v_add_f32_e32 v98, 1.0, v98
	v_rcp_f32_e32 v98, v98
	s_nop 0
	v_mul_f32_e32 v92, v98, v92
	v_mul_f32_e32 v88, v88, v92
	v_cvt_pk_bf16_f32 v88, v88, s0
	global_store_short v[130:131], v88, off offset:1024
	v_mul_f32_e32 v88, 0x4b800000, v116
	v_cndmask_b32_e64 v88, v116, v88, s[48:49]
	v_rsq_f32_e32 v88, v88
	v_or_b32_e32 v116, 1, v110
	v_ashrrev_i32_e32 v117, 31, v116
	v_lshlrev_b64 v[122:123], 12, v[116:117]
	v_lshl_add_u64 v[122:123], s[58:59], 0, v[122:123]
	v_mul_f32_e32 v92, 0x45800000, v88
	v_lshl_add_u64 v[124:125], v[122:123], 0, v[210:211]
	v_cndmask_b32_e64 v88, v88, v92, s[48:49]
	v_mul_f32_e32 v98, v99, v88
	v_lshlrev_b64 v[116:117], 11, v[116:117]
	v_mul_f32_e32 v98, v149, v98
	v_lshl_add_u64 v[116:117], s[60:61], 0, v[116:117]
	v_mul_f32_e32 v93, v93, v88
	v_mul_f32_e32 v93, v148, v93
	s_waitcnt vmcnt(63)
	v_mov_b32_e32 v92, v177
	v_lshlrev_b32_e32 v92, 16, v92
	v_mul_f32_e32 v99, 0xbfb8aa3b, v92
	v_exp_f32_e32 v99, v99
	s_nop 0
	v_add_f32_e32 v99, 1.0, v99
	v_rcp_f32_e32 v99, v99
	s_nop 0
	v_mul_f32_e32 v92, v99, v92
	v_mul_f32_e32 v92, v92, v98
	v_cvt_pk_bf16_f32 v92, v92, s0
	v_lshl_add_u64 v[98:99], v[116:117], 0, v[210:211]
	global_store_short v[98:99], v92, off offset:1024
	s_waitcnt vmcnt(63)
	v_mov_b32_e32 v92, v178
	v_lshlrev_b32_e32 v92, 16, v92
	v_mul_f32_e32 v102, 0xbfb8aa3b, v92
	v_exp_f32_e32 v102, v102
	s_nop 0
	v_add_f32_e32 v102, 1.0, v102
	v_rcp_f32_e32 v102, v102
	s_nop 0
	v_mul_f32_e32 v92, v102, v92
	v_mul_f32_e32 v92, v93, v92
	v_cvt_pk_bf16_f32 v92, v92, s0
	global_store_short v[98:99], v92, off offset:1056
	v_mul_f32_e32 v93, v103, v88
	v_mul_f32_e32 v93, v147, v93
	v_mul_f32_e32 v88, v89, v88
	v_mul_f32_e32 v88, v146, v88
	s_waitcnt vmcnt(63)
	v_mov_b32_e32 v92, v179
	v_lshlrev_b32_e32 v92, 16, v92
	v_mul_f32_e32 v102, 0xbfb8aa3b, v92
	v_exp_f32_e32 v102, v102
	s_nop 0
	v_add_f32_e32 v102, 1.0, v102
	v_rcp_f32_e32 v102, v102
	s_nop 0
	v_mul_f32_e32 v92, v102, v92
	v_mul_f32_e32 v92, v93, v92
	v_cvt_pk_bf16_f32 v92, v92, s0
	global_store_short v[98:99], v92, off offset:1088
	v_lshl_add_u64 v[92:93], v[122:123], 0, v[118:119]
	s_waitcnt vmcnt(63)
	v_mov_b32_e32 v92, v180
	v_lshlrev_b32_e32 v92, 16, v92
	v_mul_f32_e32 v89, 0xbfb8aa3b, v92
	v_exp_f32_e32 v89, v89
	s_nop 0
	v_add_f32_e32 v89, 1.0, v89
	v_rcp_f32_e32 v89, v89
	s_nop 0
	v_mul_f32_e32 v89, v89, v92
	v_mul_f32_e32 v88, v88, v89
	v_cvt_pk_bf16_f32 v92, v88, s0
	v_lshl_add_u64 v[88:89], v[116:117], 0, v[118:119]
	global_store_short v[88:89], v92, off offset:1024
	v_or_b32_e32 v88, 2, v110
	v_ashrrev_i32_e32 v89, 31, v88
	v_lshlrev_b64 v[92:93], 12, v[88:89]
	v_lshl_add_u64 v[92:93], s[58:59], 0, v[92:93]
	v_lshl_add_u64 v[98:99], v[92:93], 0, v[210:211]
	v_mov_b32_e32 v116, v108
	v_mov_b32_e32 v117, v106
	v_mov_b32_e32 v106, v109
	v_pk_add_f32 v[106:107], v[116:117], v[106:107]
	v_mov_b32_e32 v108, v114
	v_mov_b32_e32 v109, v112
	v_pk_add_f32 v[106:107], v[106:107], v[108:109]
	v_mov_b32_e32 v112, v115
	v_pk_add_f32 v[106:107], v[106:107], v[112:113]
	ds_swizzle_b32 v109, v107 offset:swizzle(SWAP,1)
	ds_swizzle_b32 v108, v106 offset:swizzle(SWAP,1)
	v_lshlrev_b64 v[88:89], 11, v[88:89]
	v_lshl_add_u64 v[88:89], s[60:61], 0, v[88:89]
	v_lshl_add_u64 v[92:93], v[92:93], 0, v[118:119]
	s_waitcnt lgkmcnt(0)
	v_pk_add_f32 v[106:107], v[106:107], v[108:109]
	ds_swizzle_b32 v109, v107 offset:swizzle(SWAP,2)
	ds_swizzle_b32 v108, v106 offset:swizzle(SWAP,2)
	s_waitcnt lgkmcnt(0)
	v_pk_add_f32 v[106:107], v[106:107], v[108:109]
	ds_swizzle_b32 v109, v107 offset:swizzle(SWAP,4)
	ds_swizzle_b32 v108, v106 offset:swizzle(SWAP,4)
	s_waitcnt lgkmcnt(0)
	v_pk_add_f32 v[106:107], v[106:107], v[108:109]
	ds_swizzle_b32 v109, v107 offset:swizzle(SWAP,8)
	ds_swizzle_b32 v108, v106 offset:swizzle(SWAP,8)
	s_waitcnt lgkmcnt(0)
	v_pk_add_f32 v[106:107], v[106:107], v[108:109]
	s_nop 0
	v_pk_fma_f32 v[106:107], v[106:107], s[6:7], v[120:121] op_sel_hi:[1,0,0]
	s_waitcnt vmcnt(63)
; template <bool GLA>
; __device__ __forceinline__ void chunk_pass_c(const ChunkIn& ci, const float* wgl, int unit, unsigned char* wl, int lane, const float* Sb, const float* ng, bf16_t* omix) {
;     ...
;         for (int jt = 0; jt < 4; ++jt) {
;             const f32x4 z = {0.f, 0.f, 0.f, 0.f};
;             if (jt < it) st[jt] = __builtin_amdgcn_mfma_f32_16x16x32_bf16(kf[jt], qf[it], z, 0, 0, 0);
;             else if (jt > it) st[jt] = __builtin_amdgcn_mfma_f32_16x16x32_bf16(kb[jt], qb[it], z, 0, 0, 0);
;             else {
;                 const f32x4 lo = __builtin_amdgcn_mfma_f32_16x16x32_bf16(kf[jt], qf[it], z, 0, 0, 0), up = __builtin_amdgcn_mfma_f32_16x16x32_bf16(kb[jt], qb[it], z, 0, 0, 0);
; #pragma unroll
;                 for (int r = 0; r < 4; ++r) st[jt][r] = (4 * kq + r <= row) ? lo[r] : up[r];
;             }
;         }
;         bf16x8 af[2];
; #pragma unroll
;         for (int p = 0; p < 2; ++p)
;             af[p] = __builtin_bit_cast(bf16x8, (u32x4){cvtpk(st[2 * p][0], st[2 * p][1]), cvtpk(st[2 * p][2], st[2 * p][3]), cvtpk(st[2 * p + 1][0], st[2 * p + 1][1]), cvtpk(st[2 * p + 1][2], st[2 * p + 1][3])});
;         f32x4 o[4]; float ss[4] = {0.f, 0.f, 0.f, 0.f};
; #pragma unroll
;         for (int et = 0; et < 4; ++et) {
;             f32x4 acc = {0.f, 0.f, 0.f, 0.f};
;             acc = __builtin_amdgcn_mfma_f32_16x16x32_bf16(af[0], vfr[et][0], acc, 0, 0, 0);
;             acc = __builtin_amdgcn_mfma_f32_16x16x32_bf16(af[1], vfr[et][1], acc, 0, 0, 0);
;             acc = __builtin_amdgcn_mfma_f32_16x16x32_bf16(qf[it], sfr[et], acc, 0, 0, 0);
;             o[et] = acc;
; #pragma unroll
;             for (int r = 0; r < 4; ++r) ss[r] += acc[r] * acc[r];
;         }
; #pragma unroll
;         for (int r = 0; r < 4; ++r) {
;             ss[r] += swz_xor<1>(ss[r]); ss[r] += swz_xor<2>(ss[r]); ss[r] += swz_xor<4>(ss[r]); ss[r] += swz_xor<8>(ss[r]);
;             const float rs = rsqrtf(ss[r] * (1.0f / 64.0f) + EPS);
;             const int t = t0 + 16 * it + 4 * kq + r;
; #pragma unroll
;             for (int et = 0; et < 4; ++et) {
;                 const int e = 16 * et + row;
;                 const float gt = __uint_as_float((unsigned)ci.proj[(size_t)t * DINP + gcol + e] << 16);
;                 const float val = o[et][r] * rs * gn[et] * pg8::silu_f(gt);
	v_mov_b32_e32 v102, v181
	v_lshlrev_b32_e32 v102, 16, v102
	v_mul_f32_e32 v103, 0xbfb8aa3b, v102
	v_exp_f32_e32 v103, v103
	v_mul_f32_e32 v108, 0x4b800000, v107
	v_cmp_gt_f32_e64 s[50:51], s96, v107
	v_cmp_gt_f32_e64 s[48:49], s96, v106
	v_add_f32_e32 v103, 1.0, v103
	v_cndmask_b32_e64 v107, v107, v108, s[50:51]
	v_rsq_f32_e32 v107, v107
	v_rcp_f32_e32 v103, v103
	v_mul_f32_e32 v108, 0x45800000, v107
	v_cndmask_b32_e64 v107, v107, v108, s[50:51]
	v_mul_f32_e32 v100, v100, v107
	v_mul_f32_e32 v111, v103, v102
	v_mul_f32_e32 v100, v149, v100
	v_mul_f32_e32 v100, v111, v100
	v_lshl_add_u64 v[102:103], v[88:89], 0, v[210:211]
	v_cvt_pk_bf16_f32 v100, v100, s0
	global_store_short v[102:103], v100, off offset:1024
	v_mul_f32_e32 v94, v94, v107
	v_mul_f32_e32 v94, v148, v94
	v_mul_f32_e32 v90, v90, v107
	v_mul_f32_e32 v90, v146, v90
	v_lshl_add_u64 v[88:89], v[88:89], 0, v[118:119]
	v_cvt_pk_bf16_f32 v111, v82, v83
	s_waitcnt vmcnt(63)
	v_mov_b32_e32 v100, v182
	v_lshlrev_b32_e32 v100, 16, v100
	v_mul_f32_e32 v108, 0xbfb8aa3b, v100
	v_exp_f32_e32 v108, v108
	s_nop 0
	v_add_f32_e32 v108, 1.0, v108
	v_rcp_f32_e32 v108, v108
	s_nop 0
	v_mul_f32_e32 v100, v108, v100
	v_mul_f32_e32 v94, v94, v100
	v_cvt_pk_bf16_f32 v94, v94, s0
	global_store_short v[102:103], v94, off offset:1056
	v_mul_f32_e32 v98, v104, v107
	v_mul_f32_e32 v98, v147, v98
	s_waitcnt vmcnt(63)
	v_mov_b32_e32 v94, v183
	v_lshlrev_b32_e32 v94, 16, v94
	v_mul_f32_e32 v99, 0xbfb8aa3b, v94
	v_exp_f32_e32 v99, v99
	s_nop 0
	v_add_f32_e32 v99, 1.0, v99
	v_rcp_f32_e32 v99, v99
	s_nop 0
	v_mul_f32_e32 v94, v99, v94
	v_mul_f32_e32 v94, v98, v94
	v_cvt_pk_bf16_f32 v94, v94, s0
	global_store_short v[102:103], v94, off offset:1088
	s_waitcnt vmcnt(63)
	v_mov_b32_e32 v92, v184
	v_lshlrev_b32_e32 v92, 16, v92
	v_mul_f32_e32 v93, 0xbfb8aa3b, v92
	v_exp_f32_e32 v93, v93
	s_nop 0
	v_add_f32_e32 v93, 1.0, v93
	v_rcp_f32_e32 v93, v93
	s_nop 0
	v_mul_f32_e32 v92, v93, v92
	v_mul_f32_e32 v90, v90, v92
	v_cvt_pk_bf16_f32 v90, v90, s0
	global_store_short v[88:89], v90, off offset:1024
	v_mul_f32_e32 v88, 0x4b800000, v106
	v_cndmask_b32_e64 v88, v106, v88, s[48:49]
	v_rsq_f32_e32 v88, v88
	s_nop 0
	v_mul_f32_e32 v89, 0x45800000, v88
	v_cndmask_b32_e64 v90, v88, v89, s[48:49]
	v_or_b32_e32 v88, 3, v110
	v_ashrrev_i32_e32 v89, 31, v88
	v_lshlrev_b64 v[92:93], 12, v[88:89]
	v_lshl_add_u64 v[92:93], s[58:59], 0, v[92:93]
	v_lshl_add_u64 v[98:99], v[92:93], 0, v[210:211]
	v_mul_f32_e32 v100, v101, v90
	v_lshlrev_b64 v[88:89], 11, v[88:89]
	v_mul_f32_e32 v100, v149, v100
	v_lshl_add_u64 v[88:89], s[60:61], 0, v[88:89]
	v_mul_f32_e32 v95, v95, v90
	v_mul_f32_e32 v95, v148, v95
	v_lshl_add_u64 v[92:93], v[92:93], 0, v[118:119]
	v_cvt_pk_bf16_f32 v110, v80, v81
	s_waitcnt vmcnt(63)
	v_mov_b32_e32 v94, v185
	v_lshlrev_b32_e32 v94, 16, v94
	v_mul_f32_e32 v101, 0xbfb8aa3b, v94
	v_exp_f32_e32 v101, v101
	s_nop 0
	v_add_f32_e32 v101, 1.0, v101
	v_rcp_f32_e32 v101, v101
	s_nop 0
	v_mul_f32_e32 v94, v101, v94
	v_mul_f32_e32 v94, v94, v100
	v_cvt_pk_bf16_f32 v94, v94, s0
	v_lshl_add_u64 v[100:101], v[88:89], 0, v[210:211]
	global_store_short v[100:101], v94, off offset:1024
	v_lshl_add_u64 v[88:89], v[88:89], 0, v[118:119]
	s_waitcnt vmcnt(63)
	v_mov_b32_e32 v94, v186
	v_lshlrev_b32_e32 v94, 16, v94
	v_mul_f32_e32 v102, 0xbfb8aa3b, v94
	v_exp_f32_e32 v102, v102
	s_nop 0
	v_add_f32_e32 v102, 1.0, v102
	v_rcp_f32_e32 v102, v102
	s_nop 0
	v_mul_f32_e32 v94, v102, v94
	v_mul_f32_e32 v94, v95, v94
	v_cvt_pk_bf16_f32 v94, v94, s0
	global_store_short v[100:101], v94, off offset:1056
	v_mul_f32_e32 v95, v105, v90
	v_mul_f32_e32 v95, v147, v95
	v_mul_f32_e32 v90, v91, v90
	v_mul_f32_e32 v90, v146, v90
	s_waitcnt vmcnt(63)
	v_mov_b32_e32 v94, v187
	v_lshlrev_b32_e32 v94, 16, v94
	v_mul_f32_e32 v98, 0xbfb8aa3b, v94
	v_exp_f32_e32 v98, v98
	s_nop 0
	v_add_f32_e32 v98, 1.0, v98
	v_rcp_f32_e32 v98, v98
	s_nop 0
	v_mul_f32_e32 v94, v98, v94
	v_mul_f32_e32 v94, v95, v94
	v_cvt_pk_bf16_f32 v94, v94, s0
	global_store_short v[100:101], v94, off offset:1088
	v_mfma_f32_16x16x32_bf16 v[98:101], v[4:7], v[76:79], 0
	s_waitcnt vmcnt(63)
	v_mov_b32_e32 v92, v188
	v_lshlrev_b32_e32 v92, 16, v92
	v_mul_f32_e32 v91, 0xbfb8aa3b, v92
	v_exp_f32_e32 v91, v91
	s_nop 3
	v_cndmask_b32_e64 v86, v100, v86, s[44:45]
	v_cndmask_b32_e64 v87, v101, v87, s[46:47]
	v_cndmask_b32_e32 v84, v98, v84, vcc
	v_add_f32_e32 v91, 1.0, v91
	v_rcp_f32_e32 v91, v91
	v_cndmask_b32_e64 v85, v85, v99, s[42:43]
	v_cvt_pk_bf16_f32 v108, v84, v85
	v_cvt_pk_bf16_f32 v109, v86, v87
	v_mul_f32_e32 v91, v91, v92
	v_mul_f32_e32 v90, v90, v91
	v_cvt_pk_bf16_f32 v90, v90, s0
	global_store_short v[88:89], v90, off offset:1024
	v_mfma_f32_16x16x32_bf16 v[88:91], v[0:3], v[76:79], 0
	v_mfma_f32_16x16x32_bf16 v[92:95], v[8:11], v[76:79], 0
	v_mfma_f32_16x16x32_bf16 v[0:3], v[0:3], v[12:15], 0
	s_nop 5
	v_cvt_pk_bf16_f32 v100, v88, v89
	v_cvt_pk_bf16_f32 v101, v90, v91
	v_cvt_pk_bf16_f32 v102, v92, v93
	v_cvt_pk_bf16_f32 v103, v94, v95
	v_mfma_f32_16x16x32_bf16 v[8:11], v[8:11], v[12:15], 0
	v_cvt_pk_bf16_f32 v52, v0, v1
	v_cvt_pk_bf16_f32 v53, v2, v3
	v_mfma_f32_16x16x32_bf16 v[80:83], v[100:103], v[64:67], 0
	v_mfma_f32_16x16x32_bf16 v[80:83], v[108:111], v[60:63], v[80:83]
	s_nop 3
	v_cvt_pk_bf16_f32 v54, v8, v9
	v_cvt_pk_bf16_f32 v55, v10, v11
	v_mfma_f32_16x16x32_bf16 v[84:87], v[76:79], v[68:71], v[80:83]
	v_mfma_f32_16x16x32_bf16 v[80:83], v[100:103], v[48:51], 0
	v_mfma_f32_16x16x32_bf16 v[80:83], v[108:111], v[44:47], v[80:83]
	s_nop 5
	v_mov_b32_e32 v88, v84
	v_mfma_f32_16x16x32_bf16 v[80:83], v[76:79], v[40:43], v[80:83]
	v_mfma_f32_16x16x32_bf16 v[4:7], v[4:7], v[12:15], 0
; template <bool GLA>
; __device__ __forceinline__ void chunk_pass_c(const ChunkIn& ci, const float* wgl, int unit, unsigned char* wl, int lane, const float* Sb, const float* ng, bf16_t* omix) {
;     ...
;         for (int jt = 0; jt < 4; ++jt) {
;             const f32x4 z = {0.f, 0.f, 0.f, 0.f};
;             if (jt < it) st[jt] = __builtin_amdgcn_mfma_f32_16x16x32_bf16(kf[jt], qf[it], z, 0, 0, 0);
;             else if (jt > it) st[jt] = __builtin_amdgcn_mfma_f32_16x16x32_bf16(kb[jt], qb[it], z, 0, 0, 0);
;             else {
;                 const f32x4 lo = __builtin_amdgcn_mfma_f32_16x16x32_bf16(kf[jt], qf[it], z, 0, 0, 0), up = __builtin_amdgcn_mfma_f32_16x16x32_bf16(kb[jt], qb[it], z, 0, 0, 0);
; #pragma unroll
;                 for (int r = 0; r < 4; ++r) st[jt][r] = (4 * kq + r <= row) ? lo[r] : up[r];
;             }
;         }
;         bf16x8 af[2];
; #pragma unroll
;         for (int p = 0; p < 2; ++p)
;             af[p] = __builtin_bit_cast(bf16x8, (u32x4){cvtpk(st[2 * p][0], st[2 * p][1]), cvtpk(st[2 * p][2], st[2 * p][3]), cvtpk(st[2 * p + 1][0], st[2 * p + 1][1]), cvtpk(st[2 * p + 1][2], st[2 * p + 1][3])});
;         f32x4 o[4]; float ss[4] = {0.f, 0.f, 0.f, 0.f};
; #pragma unroll
;         for (int et = 0; et < 4; ++et) {
;             f32x4 acc = {0.f, 0.f, 0.f, 0.f};
;             acc = __builtin_amdgcn_mfma_f32_16x16x32_bf16(af[0], vfr[et][0], acc, 0, 0, 0);
;             acc = __builtin_amdgcn_mfma_f32_16x16x32_bf16(af[1], vfr[et][1], acc, 0, 0, 0);
;             acc = __builtin_amdgcn_mfma_f32_16x16x32_bf16(qf[it], sfr[et], acc, 0, 0, 0);
;             o[et] = acc;
; #pragma unroll
;             for (int r = 0; r < 4; ++r) ss[r] += acc[r] * acc[r];
;         }
; #pragma unroll
;         for (int r = 0; r < 4; ++r) {
;             ss[r] += swz_xor<1>(ss[r]); ss[r] += swz_xor<2>(ss[r]); ss[r] += swz_xor<4>(ss[r]); ss[r] += swz_xor<8>(ss[r]);
;             const float rs = rsqrtf(ss[r] * (1.0f / 64.0f) + EPS);
;             const int t = t0 + 16 * it + 4 * kq + r;
; #pragma unroll
;             for (int et = 0; et < 4; ++et) {
;                 const int e = 16 * et + row;
;                 const float gt = __uint_as_float((unsigned)ci.proj[(size_t)t * DINP + gcol + e] << 16);
;                 const float val = o[et][r] * rs * gn[et] * pg8::silu_f(gt);
	v_mfma_f32_16x16x32_bf16 v[0:3], v[52:55], v[64:67], 0
	s_nop 5
	v_mov_b32_e32 v89, v80
	v_pk_mul_f32 v[104:105], v[88:89], v[88:89]
	v_mov_b32_e32 v88, v85
	v_mov_b32_e32 v89, v81
	v_pk_mul_f32 v[106:107], v[88:89], v[88:89]
	v_mov_b32_e32 v88, v86
	v_mov_b32_e32 v89, v82
	v_pk_mul_f32 v[92:93], v[88:89], v[88:89]
	v_mov_b32_e32 v88, v87
	v_mov_b32_e32 v89, v83
	v_pk_mul_f32 v[98:99], v[88:89], v[88:89]
	v_mfma_f32_16x16x32_bf16 v[88:91], v[100:103], v[36:39], 0
	v_cvt_pk_bf16_f32 v4, v4, v5
	v_cvt_pk_bf16_f32 v5, v6, v7
	v_cvt_pk_bf16_f32 v6, v56, v57
	v_mfma_f32_16x16x32_bf16 v[100:103], v[100:103], v[24:27], 0
	v_cvt_pk_bf16_f32 v7, v58, v59
	v_mfma_f32_16x16x32_bf16 v[88:91], v[108:111], v[32:35], v[88:91]
	v_mfma_f32_16x16x32_bf16 v[100:103], v[108:111], v[20:23], v[100:103]
	v_mfma_f32_16x16x32_bf16 v[88:91], v[76:79], v[28:31], v[88:91]
	v_mfma_f32_16x16x32_bf16 v[76:79], v[76:79], v[16:19], v[100:103]
	v_mfma_f32_16x16x32_bf16 v[0:3], v[4:7], v[60:63], v[0:3]
	s_nop 5
	v_mov_b32_e32 v94, v88
	v_mov_b32_e32 v95, v76
	v_pk_mul_f32 v[108:109], v[94:95], v[94:95]
	v_mov_b32_e32 v94, v89
	v_mov_b32_e32 v95, v77
	v_pk_mul_f32 v[110:111], v[94:95], v[94:95]
	v_mov_b32_e32 v94, v90
	v_mov_b32_e32 v95, v78
	v_pk_mul_f32 v[100:101], v[94:95], v[94:95]
	v_mov_b32_e32 v94, v91
	v_mov_b32_e32 v95, v79
	v_pk_mul_f32 v[102:103], v[94:95], v[94:95]
	v_or_b32_e32 v94, s65, v97
	v_ashrrev_i32_e32 v95, 31, v94
	v_lshlrev_b64 v[112:113], 12, v[94:95]
	v_lshl_add_u64 v[114:115], s[58:59], 0, v[112:113]
	v_lshlrev_b64 v[112:113], 11, v[94:95]
	v_lshl_add_u64 v[116:117], s[60:61], 0, v[112:113]
	v_lshl_add_u64 v[112:113], v[114:115], 0, v[210:211]
	v_lshl_add_u64 v[124:125], v[114:115], 0, v[118:119]
	v_lshl_add_u64 v[114:115], v[116:117], 0, v[118:119]
	v_mfma_f32_16x16x32_bf16 v[8:11], v[12:15], v[68:71], v[0:3]
	s_waitcnt vmcnt(63)
	v_mov_b32_e32 v95, v189
	v_lshlrev_b32_e32 v95, 16, v95
	v_mul_f32_e32 v122, 0xbfb8aa3b, v95
	v_exp_f32_e32 v122, v122
	v_mfma_f32_16x16x32_bf16 v[0:3], v[52:55], v[48:51], 0
	v_add_f32_e32 v122, 1.0, v122
	v_rcp_f32_e32 v122, v122
	v_mfma_f32_16x16x32_bf16 v[36:39], v[52:55], v[36:39], 0
	v_mul_f32_e32 v95, v122, v95
	v_lshl_add_u64 v[122:123], v[116:117], 0, v[210:211]
	v_mov_b32_e32 v116, v106
	v_mov_b32_e32 v117, v104
	v_mov_b32_e32 v104, v107
	v_pk_add_f32 v[104:105], v[116:117], v[104:105]
	v_mov_b32_e32 v106, v110
	v_mov_b32_e32 v107, v108
	v_pk_add_f32 v[104:105], v[104:105], v[106:107]
	v_mov_b32_e32 v108, v111
	v_pk_add_f32 v[104:105], v[104:105], v[108:109]
	ds_swizzle_b32 v107, v105 offset:swizzle(SWAP,1)
	ds_swizzle_b32 v106, v104 offset:swizzle(SWAP,1)
	v_mfma_f32_16x16x32_bf16 v[24:27], v[52:55], v[24:27], 0
	s_waitcnt lgkmcnt(0)
	v_pk_add_f32 v[104:105], v[104:105], v[106:107]
	ds_swizzle_b32 v107, v105 offset:swizzle(SWAP,2)
	ds_swizzle_b32 v106, v104 offset:swizzle(SWAP,2)
	v_mfma_f32_16x16x32_bf16 v[0:3], v[4:7], v[44:47], v[0:3]
	s_waitcnt lgkmcnt(0)
	v_pk_add_f32 v[104:105], v[104:105], v[106:107]
	ds_swizzle_b32 v107, v105 offset:swizzle(SWAP,4)
	ds_swizzle_b32 v106, v104 offset:swizzle(SWAP,4)
	v_mfma_f32_16x16x32_bf16 v[32:35], v[4:7], v[32:35], v[36:39]
	s_waitcnt lgkmcnt(0)
	v_pk_add_f32 v[104:105], v[104:105], v[106:107]
	ds_swizzle_b32 v107, v105 offset:swizzle(SWAP,8)
	ds_swizzle_b32 v106, v104 offset:swizzle(SWAP,8)
	v_mfma_f32_16x16x32_bf16 v[4:7], v[4:7], v[20:23], v[24:27]
	s_waitcnt lgkmcnt(0)
	v_pk_add_f32 v[104:105], v[104:105], v[106:107]
	s_nop 0
	v_pk_fma_f32 v[104:105], v[104:105], s[6:7], v[120:121] op_sel_hi:[1,0,0]
	v_mfma_f32_16x16x32_bf16 v[28:31], v[12:15], v[28:31], v[32:35]
	v_mul_f32_e32 v106, 0x4b800000, v105
	v_cmp_gt_f32_e64 s[50:51], s96, v105
	v_cmp_gt_f32_e64 s[48:49], s96, v104
	v_mfma_f32_16x16x32_bf16 v[4:7], v[12:15], v[16:19], v[4:7]
	v_cndmask_b32_e64 v105, v105, v106, s[50:51]
	v_rsq_f32_e32 v105, v105
	v_mfma_f32_16x16x32_bf16 v[0:3], v[12:15], v[40:43], v[0:3]
	s_nop 0
	v_mov_b32_e32 v12, v28
	v_mul_f32_e32 v106, 0x45800000, v105
	v_cndmask_b32_e64 v105, v105, v106, s[50:51]
	v_mul_f32_e32 v84, v84, v105
	v_mul_f32_e32 v84, v149, v84
	v_mul_f32_e32 v84, v95, v84
	v_cvt_pk_bf16_f32 v84, v84, s0
	global_store_short v[122:123], v84, off offset:1024
	v_mul_f32_e32 v80, v80, v105
	v_mul_f32_e32 v80, v148, v80
	v_mul_f32_e32 v76, v76, v105
	v_mul_f32_e32 v76, v146, v76
	v_mov_b32_e32 v13, v4
	v_pk_mul_f32 v[18:19], v[12:13], v[12:13]
	v_mov_b32_e32 v12, v29
	v_mov_b32_e32 v13, v5
	v_pk_mul_f32 v[20:21], v[12:13], v[12:13]
	v_mov_b32_e32 v12, v30
	v_mov_b32_e32 v13, v6
	v_pk_mul_f32 v[14:15], v[12:13], v[12:13]
	v_mov_b32_e32 v12, v31
	v_mov_b32_e32 v13, v7
	v_pk_mul_f32 v[16:17], v[12:13], v[12:13]
	v_or_b32_e32 v12, s27, v97
	v_ashrrev_i32_e32 v13, 31, v12
	v_lshlrev_b64 v[22:23], 12, v[12:13]
	v_lshl_add_u64 v[24:25], s[58:59], 0, v[22:23]
	v_lshlrev_b64 v[22:23], 11, v[12:13]
	v_lshl_add_u64 v[26:27], s[60:61], 0, v[22:23]
	v_lshl_add_u64 v[22:23], v[24:25], 0, v[210:211]
	v_mov_b32_e32 v40, v8
	v_mov_b32_e32 v41, v0
	v_pk_mul_f32 v[44:45], v[40:41], v[40:41]
	v_mov_b32_e32 v40, v9
	v_mov_b32_e32 v41, v1
	v_pk_mul_f32 v[46:47], v[40:41], v[40:41]
	v_lshl_add_u64 v[34:35], v[24:25], 0, v[118:119]
	v_lshl_add_u64 v[24:25], v[26:27], 0, v[118:119]
	v_mov_b32_e32 v36, v20
	v_mov_b32_e32 v37, v18
	v_mov_b32_e32 v18, v21
	v_mov_b32_e32 v40, v10
	v_mov_b32_e32 v41, v2
	v_mov_b32_e32 v42, v11
	v_mov_b32_e32 v43, v3
	v_pk_mul_f32 v[40:41], v[40:41], v[40:41]
	v_pk_mul_f32 v[42:43], v[42:43], v[42:43]
	s_waitcnt vmcnt(63)
; __device__ __forceinline__ unsigned cvtpk(float lo, float hi) { f32x2_t v = {lo, hi}; bf16x2_t b = __builtin_convertvector(v, bf16x2_t); return __builtin_bit_cast(unsigned, b); }
; template <int X> __device__ __forceinline__ float swz_xor(float v) { return __int_as_float(__builtin_amdgcn_ds_swizzle(__float_as_int(v), (X << 10) | 0x1F)); }
; __device__ __forceinline__ float silu_f(float g) { return g * __builtin_amdgcn_rcpf(1.0f + __expf(-g)); }
; template <bool GLA>
; __device__ __forceinline__ void chunk_pass_c(const ChunkIn& ci, const float* wgl, int unit, unsigned char* wl, int lane, const float* Sb, const float* ng, bf16_t* omix) {
;     ...
;         for (int r = 0; r < 4; ++r) {
;             ss[r] += swz_xor<1>(ss[r]); ss[r] += swz_xor<2>(ss[r]); ss[r] += swz_xor<4>(ss[r]); ss[r] += swz_xor<8>(ss[r]);
;             const float rs = rsqrtf(ss[r] * (1.0f / 64.0f) + EPS);
;             const int t = t0 + 16 * it + 4 * kq + r;
; #pragma unroll
;             for (int et = 0; et < 4; ++et) {
;                 const int e = 16 * et + row;
;                 const float gt = __uint_as_float((unsigned)ci.proj[(size_t)t * DINP + gcol + e] << 16);
;                 const float val = o[et][r] * rs * gn[et] * pg8::silu_f(gt);
;                 omix[(size_t)t * 1024 + ocol + e] = (bf16_t)(cvtpk(val, 0.f) & 0xffffu);
;             }
;         }
	v_mov_b32_e32 v84, v190
	v_lshlrev_b32_e32 v84, 16, v84
	v_mul_f32_e32 v95, 0xbfb8aa3b, v84
	v_exp_f32_e32 v95, v95
	s_nop 0
	v_add_f32_e32 v95, 1.0, v95
	v_rcp_f32_e32 v95, v95
	s_nop 0
	v_mul_f32_e32 v84, v95, v84
	v_mul_f32_e32 v80, v84, v80
	v_cvt_pk_bf16_f32 v80, v80, s0
	global_store_short v[122:123], v80, off offset:1056
	v_mul_f32_e32 v84, v88, v105
	v_mul_f32_e32 v84, v147, v84
	s_waitcnt vmcnt(63)
	v_mov_b32_e32 v80, v191
	v_lshlrev_b32_e32 v80, 16, v80
	v_mul_f32_e32 v88, 0xbfb8aa3b, v80
	v_exp_f32_e32 v88, v88
	s_nop 0
	v_add_f32_e32 v88, 1.0, v88
	v_rcp_f32_e32 v88, v88
	s_nop 0
	v_mul_f32_e32 v80, v88, v80
	v_mul_f32_e32 v80, v84, v80
	v_cvt_pk_bf16_f32 v80, v80, s0
	global_store_short v[122:123], v80, off offset:1088
	s_waitcnt vmcnt(63)
	v_mov_b32_e32 v80, v192
	v_lshlrev_b32_e32 v80, 16, v80
	v_mul_f32_e32 v84, 0xbfb8aa3b, v80
	v_exp_f32_e32 v84, v84
	s_nop 0
	v_add_f32_e32 v84, 1.0, v84
	v_rcp_f32_e32 v84, v84
	s_nop 0
	v_mul_f32_e32 v80, v84, v80
	v_mul_f32_e32 v76, v76, v80
	v_cvt_pk_bf16_f32 v76, v76, s0
	global_store_short v[114:115], v76, off offset:1024
	v_mul_f32_e32 v76, 0x4b800000, v104
	v_cndmask_b32_e64 v76, v104, v76, s[48:49]
	v_rsq_f32_e32 v76, v76
	v_or_b32_e32 v104, 1, v94
	v_ashrrev_i32_e32 v105, 31, v104
	v_lshlrev_b64 v[106:107], 12, v[104:105]
	v_lshl_add_u64 v[106:107], s[58:59], 0, v[106:107]
	v_mul_f32_e32 v80, 0x45800000, v76
	v_lshl_add_u64 v[108:109], v[106:107], 0, v[210:211]
	v_cndmask_b32_e64 v76, v76, v80, s[48:49]
	v_mul_f32_e32 v84, v85, v76
	v_lshlrev_b64 v[104:105], 11, v[104:105]
	v_mul_f32_e32 v84, v149, v84
	v_lshl_add_u64 v[104:105], s[60:61], 0, v[104:105]
	v_mul_f32_e32 v81, v81, v76
	v_mul_f32_e32 v81, v148, v81
	s_waitcnt vmcnt(63)
	v_mov_b32_e32 v80, v193
	v_lshlrev_b32_e32 v80, 16, v80
	v_mul_f32_e32 v85, 0xbfb8aa3b, v80
	v_exp_f32_e32 v85, v85
	s_nop 0
	v_add_f32_e32 v85, 1.0, v85
	v_rcp_f32_e32 v85, v85
	s_nop 0
	v_mul_f32_e32 v80, v85, v80
	v_mul_f32_e32 v80, v80, v84
	v_cvt_pk_bf16_f32 v80, v80, s0
	v_lshl_add_u64 v[84:85], v[104:105], 0, v[210:211]
	global_store_short v[84:85], v80, off offset:1024
	s_waitcnt vmcnt(63)
	v_mov_b32_e32 v80, v194
	v_lshlrev_b32_e32 v80, 16, v80
	v_mul_f32_e32 v88, 0xbfb8aa3b, v80
	v_exp_f32_e32 v88, v88
	s_nop 0
	v_add_f32_e32 v88, 1.0, v88
	v_rcp_f32_e32 v88, v88
	s_nop 0
	v_mul_f32_e32 v80, v88, v80
	v_mul_f32_e32 v80, v81, v80
	v_cvt_pk_bf16_f32 v80, v80, s0
	global_store_short v[84:85], v80, off offset:1056
	v_mul_f32_e32 v81, v89, v76
	v_mul_f32_e32 v81, v147, v81
	v_mul_f32_e32 v76, v77, v76
	v_mul_f32_e32 v76, v146, v76
	s_waitcnt vmcnt(63)
	v_mov_b32_e32 v80, v195
	v_lshlrev_b32_e32 v80, 16, v80
	v_mul_f32_e32 v88, 0xbfb8aa3b, v80
	v_exp_f32_e32 v88, v88
	s_nop 0
	v_add_f32_e32 v88, 1.0, v88
	v_rcp_f32_e32 v88, v88
	s_nop 0
	v_mul_f32_e32 v80, v88, v80
	v_mul_f32_e32 v80, v81, v80
	v_cvt_pk_bf16_f32 v80, v80, s0
	global_store_short v[84:85], v80, off offset:1088
	v_lshl_add_u64 v[80:81], v[106:107], 0, v[118:119]
	s_waitcnt vmcnt(63)
	v_mov_b32_e32 v80, v196
	v_lshlrev_b32_e32 v80, 16, v80
	v_mul_f32_e32 v77, 0xbfb8aa3b, v80
	v_exp_f32_e32 v77, v77
	s_nop 0
	v_add_f32_e32 v77, 1.0, v77
	v_rcp_f32_e32 v77, v77
	s_nop 0
	v_mul_f32_e32 v77, v77, v80
	v_mul_f32_e32 v76, v76, v77
	v_cvt_pk_bf16_f32 v80, v76, s0
	v_lshl_add_u64 v[76:77], v[104:105], 0, v[118:119]
	global_store_short v[76:77], v80, off offset:1024
	v_or_b32_e32 v76, 2, v94
	v_ashrrev_i32_e32 v77, 31, v76
	v_lshlrev_b64 v[80:81], 12, v[76:77]
	v_lshl_add_u64 v[80:81], s[58:59], 0, v[80:81]
	v_lshl_add_u64 v[84:85], v[80:81], 0, v[210:211]
	v_mov_b32_e32 v104, v98
	v_mov_b32_e32 v105, v92
	v_mov_b32_e32 v92, v99
	v_pk_add_f32 v[92:93], v[104:105], v[92:93]
	v_mov_b32_e32 v98, v102
	v_mov_b32_e32 v99, v100
	v_pk_add_f32 v[92:93], v[92:93], v[98:99]
	v_mov_b32_e32 v100, v103
	v_pk_add_f32 v[92:93], v[92:93], v[100:101]
	ds_swizzle_b32 v99, v93 offset:swizzle(SWAP,1)
	ds_swizzle_b32 v98, v92 offset:swizzle(SWAP,1)
	v_lshlrev_b64 v[76:77], 11, v[76:77]
	v_lshl_add_u64 v[76:77], s[60:61], 0, v[76:77]
	v_lshl_add_u64 v[80:81], v[80:81], 0, v[118:119]
	s_waitcnt lgkmcnt(0)
	v_pk_add_f32 v[92:93], v[92:93], v[98:99]
	ds_swizzle_b32 v99, v93 offset:swizzle(SWAP,2)
	ds_swizzle_b32 v98, v92 offset:swizzle(SWAP,2)
	s_waitcnt lgkmcnt(0)
	v_pk_add_f32 v[92:93], v[92:93], v[98:99]
	ds_swizzle_b32 v99, v93 offset:swizzle(SWAP,4)
	ds_swizzle_b32 v98, v92 offset:swizzle(SWAP,4)
	s_waitcnt lgkmcnt(0)
	v_pk_add_f32 v[92:93], v[92:93], v[98:99]
	ds_swizzle_b32 v99, v93 offset:swizzle(SWAP,8)
	ds_swizzle_b32 v98, v92 offset:swizzle(SWAP,8)
	s_waitcnt lgkmcnt(0)
	v_pk_add_f32 v[92:93], v[92:93], v[98:99]
	s_nop 0
	v_pk_fma_f32 v[92:93], v[92:93], s[6:7], v[120:121] op_sel_hi:[1,0,0]
	s_waitcnt vmcnt(63)
	v_mov_b32_e32 v88, v197
	v_lshlrev_b32_e32 v88, 16, v88
	v_mul_f32_e32 v89, 0xbfb8aa3b, v88
	v_exp_f32_e32 v89, v89
	v_mul_f32_e32 v98, 0x4b800000, v93
	v_cmp_gt_f32_e64 s[50:51], s96, v93
	v_cmp_gt_f32_e64 s[48:49], s96, v92
	v_add_f32_e32 v89, 1.0, v89
	v_cndmask_b32_e64 v93, v93, v98, s[50:51]
	v_rsq_f32_e32 v93, v93
	v_rcp_f32_e32 v89, v89
	v_mul_f32_e32 v98, 0x45800000, v93
	v_cndmask_b32_e64 v93, v93, v98, s[50:51]
	v_mul_f32_e32 v86, v86, v93
	v_mul_f32_e32 v95, v89, v88
	v_mul_f32_e32 v86, v149, v86
	v_mul_f32_e32 v86, v95, v86
	v_lshl_add_u64 v[88:89], v[76:77], 0, v[210:211]
	v_cvt_pk_bf16_f32 v86, v86, s0
	global_store_short v[88:89], v86, off offset:1024
	v_mul_f32_e32 v82, v82, v93
	v_mul_f32_e32 v82, v148, v82
	v_mul_f32_e32 v78, v78, v93
	v_mul_f32_e32 v78, v146, v78
	v_lshl_add_u64 v[76:77], v[76:77], 0, v[118:119]
	s_waitcnt vmcnt(63)
; __device__ __forceinline__ unsigned cvtpk(float lo, float hi) { f32x2_t v = {lo, hi}; bf16x2_t b = __builtin_convertvector(v, bf16x2_t); return __builtin_bit_cast(unsigned, b); }
; template <int X> __device__ __forceinline__ float swz_xor(float v) { return __int_as_float(__builtin_amdgcn_ds_swizzle(__float_as_int(v), (X << 10) | 0x1F)); }
; __device__ __forceinline__ float silu_f(float g) { return g * __builtin_amdgcn_rcpf(1.0f + __expf(-g)); }
; template <bool GLA>
; __device__ __forceinline__ void chunk_pass_c(const ChunkIn& ci, const float* wgl, int unit, unsigned char* wl, int lane, const float* Sb, const float* ng, bf16_t* omix) {
;     ...
;         for (int r = 0; r < 4; ++r) {
;             ss[r] += swz_xor<1>(ss[r]); ss[r] += swz_xor<2>(ss[r]); ss[r] += swz_xor<4>(ss[r]); ss[r] += swz_xor<8>(ss[r]);
;             const float rs = rsqrtf(ss[r] * (1.0f / 64.0f) + EPS);
;             const int t = t0 + 16 * it + 4 * kq + r;
; #pragma unroll
;             for (int et = 0; et < 4; ++et) {
;                 const int e = 16 * et + row;
;                 const float gt = __uint_as_float((unsigned)ci.proj[(size_t)t * DINP + gcol + e] << 16);
;                 const float val = o[et][r] * rs * gn[et] * pg8::silu_f(gt);
;                 omix[(size_t)t * 1024 + ocol + e] = (bf16_t)(cvtpk(val, 0.f) & 0xffffu);
;             }
;         }
	v_mov_b32_e32 v86, v198
	v_lshlrev_b32_e32 v86, 16, v86
	v_mul_f32_e32 v95, 0xbfb8aa3b, v86
	v_exp_f32_e32 v95, v95
	s_nop 0
	v_add_f32_e32 v95, 1.0, v95
	v_rcp_f32_e32 v95, v95
	s_nop 0
	v_mul_f32_e32 v86, v95, v86
	v_mul_f32_e32 v82, v82, v86
	v_cvt_pk_bf16_f32 v82, v82, s0
	global_store_short v[88:89], v82, off offset:1056
	v_mul_f32_e32 v84, v90, v93
	v_mul_f32_e32 v84, v147, v84
	s_waitcnt vmcnt(63)
	v_mov_b32_e32 v82, v199
	v_lshlrev_b32_e32 v82, 16, v82
	v_mul_f32_e32 v85, 0xbfb8aa3b, v82
	v_exp_f32_e32 v85, v85
	s_nop 0
	v_add_f32_e32 v85, 1.0, v85
	v_rcp_f32_e32 v85, v85
	s_nop 0
	v_mul_f32_e32 v82, v85, v82
	v_mul_f32_e32 v82, v84, v82
	v_cvt_pk_bf16_f32 v82, v82, s0
	global_store_short v[88:89], v82, off offset:1088
	s_waitcnt vmcnt(63)
	v_mov_b32_e32 v80, v200
	v_lshlrev_b32_e32 v80, 16, v80
	v_mul_f32_e32 v81, 0xbfb8aa3b, v80
	v_exp_f32_e32 v81, v81
	s_nop 0
	v_add_f32_e32 v81, 1.0, v81
	v_rcp_f32_e32 v81, v81
	s_nop 0
	v_mul_f32_e32 v80, v81, v80
	v_mul_f32_e32 v78, v78, v80
	v_cvt_pk_bf16_f32 v78, v78, s0
	global_store_short v[76:77], v78, off offset:1024
	v_mul_f32_e32 v76, 0x4b800000, v92
	v_cndmask_b32_e64 v76, v92, v76, s[48:49]
	v_rsq_f32_e32 v76, v76
	s_nop 0
	v_mul_f32_e32 v77, 0x45800000, v76
	v_cndmask_b32_e64 v78, v76, v77, s[48:49]
	v_or_b32_e32 v76, 3, v94
	v_ashrrev_i32_e32 v77, 31, v76
	v_lshlrev_b64 v[80:81], 12, v[76:77]
	v_lshl_add_u64 v[80:81], s[58:59], 0, v[80:81]
	v_lshl_add_u64 v[84:85], v[80:81], 0, v[210:211]
	v_mul_f32_e32 v86, v87, v78
	v_lshlrev_b64 v[76:77], 11, v[76:77]
	v_mul_f32_e32 v86, v149, v86
	v_lshl_add_u64 v[76:77], s[60:61], 0, v[76:77]
	v_mul_f32_e32 v83, v83, v78
	v_mul_f32_e32 v83, v148, v83
	v_lshl_add_u64 v[80:81], v[80:81], 0, v[118:119]
	s_waitcnt vmcnt(63)
	v_mov_b32_e32 v82, v201
	v_lshlrev_b32_e32 v82, 16, v82
	v_mul_f32_e32 v87, 0xbfb8aa3b, v82
	v_exp_f32_e32 v87, v87
	s_nop 0
	v_add_f32_e32 v87, 1.0, v87
	v_rcp_f32_e32 v87, v87
	s_nop 0
	v_mul_f32_e32 v82, v87, v82
	v_mul_f32_e32 v82, v82, v86
	v_cvt_pk_bf16_f32 v82, v82, s0
	v_lshl_add_u64 v[86:87], v[76:77], 0, v[210:211]
	global_store_short v[86:87], v82, off offset:1024
	v_lshl_add_u64 v[76:77], v[76:77], 0, v[118:119]
	s_waitcnt vmcnt(63)
	v_mov_b32_e32 v82, v202
	v_lshlrev_b32_e32 v82, 16, v82
	v_mul_f32_e32 v88, 0xbfb8aa3b, v82
	v_exp_f32_e32 v88, v88
	s_nop 0
	v_add_f32_e32 v88, 1.0, v88
	v_rcp_f32_e32 v88, v88
	s_nop 0
	v_mul_f32_e32 v82, v88, v82
	v_mul_f32_e32 v82, v83, v82
	v_cvt_pk_bf16_f32 v82, v82, s0
	global_store_short v[86:87], v82, off offset:1056
	v_mul_f32_e32 v83, v91, v78
	v_mul_f32_e32 v83, v147, v83
	v_mul_f32_e32 v78, v79, v78
	v_mul_f32_e32 v78, v146, v78
	s_waitcnt vmcnt(63)
	v_mov_b32_e32 v82, v203
	v_lshlrev_b32_e32 v82, 16, v82
	v_mul_f32_e32 v84, 0xbfb8aa3b, v82
	v_exp_f32_e32 v84, v84
	s_nop 0
	v_add_f32_e32 v84, 1.0, v84
	v_rcp_f32_e32 v84, v84
	s_nop 0
	v_mul_f32_e32 v82, v84, v82
	v_mul_f32_e32 v82, v83, v82
	v_cvt_pk_bf16_f32 v82, v82, s0
	global_store_short v[86:87], v82, off offset:1088
	s_waitcnt vmcnt(63)
	v_mov_b32_e32 v80, v204
	v_lshlrev_b32_e32 v80, 16, v80
	v_mul_f32_e32 v79, 0xbfb8aa3b, v80
	v_exp_f32_e32 v79, v79
	s_nop 0
	v_add_f32_e32 v79, 1.0, v79
	v_rcp_f32_e32 v79, v79
	s_nop 0
	v_mul_f32_e32 v79, v79, v80
	v_mul_f32_e32 v78, v78, v79
	v_cvt_pk_bf16_f32 v78, v78, s0
	global_store_short v[76:77], v78, off offset:1024
	s_waitcnt vmcnt(63)
	v_mov_b32_e32 v13, v205
	v_lshlrev_b32_e32 v13, 16, v13
	v_mul_f32_e32 v32, 0xbfb8aa3b, v13
	v_exp_f32_e32 v32, v32
	s_nop 0
	v_add_f32_e32 v32, 1.0, v32
	v_rcp_f32_e32 v32, v32
	s_nop 0
	v_mul_f32_e32 v13, v32, v13
	v_lshl_add_u64 v[32:33], v[26:27], 0, v[210:211]
	v_mov_b32_e32 v26, v46
	v_mov_b32_e32 v27, v44
	v_mov_b32_e32 v44, v47
	v_pk_add_f32 v[26:27], v[26:27], v[44:45]
	s_nop 0
	v_pk_add_f32 v[26:27], v[26:27], v[36:37]
	s_nop 0
	v_pk_add_f32 v[18:19], v[26:27], v[18:19]
	ds_swizzle_b32 v21, v19 offset:swizzle(SWAP,1)
	ds_swizzle_b32 v20, v18 offset:swizzle(SWAP,1)
	s_waitcnt lgkmcnt(0)
	v_pk_add_f32 v[18:19], v[18:19], v[20:21]
	ds_swizzle_b32 v21, v19 offset:swizzle(SWAP,2)
	ds_swizzle_b32 v20, v18 offset:swizzle(SWAP,2)
	s_waitcnt lgkmcnt(0)
	v_pk_add_f32 v[18:19], v[18:19], v[20:21]
	ds_swizzle_b32 v21, v19 offset:swizzle(SWAP,4)
	ds_swizzle_b32 v20, v18 offset:swizzle(SWAP,4)
	s_waitcnt lgkmcnt(0)
	v_pk_add_f32 v[18:19], v[18:19], v[20:21]
	ds_swizzle_b32 v21, v19 offset:swizzle(SWAP,8)
	ds_swizzle_b32 v20, v18 offset:swizzle(SWAP,8)
	s_waitcnt lgkmcnt(0)
	v_pk_add_f32 v[18:19], v[18:19], v[20:21]
	s_nop 0
	v_pk_fma_f32 v[18:19], v[18:19], s[6:7], v[120:121] op_sel_hi:[1,0,0]
	s_nop 0
	v_mul_f32_e32 v20, 0x4b800000, v19
	v_cmp_gt_f32_e64 s[42:43], s96, v19
	v_cmp_gt_f32_e32 vcc, s96, v18
	s_nop 0
	v_cndmask_b32_e64 v19, v19, v20, s[42:43]
	v_rsq_f32_e32 v19, v19
	s_nop 0
	v_mul_f32_e32 v20, 0x45800000, v19
	v_cndmask_b32_e64 v19, v19, v20, s[42:43]
	v_mul_f32_e32 v8, v8, v19
	v_mul_f32_e32 v8, v149, v8
	v_mul_f32_e32 v8, v13, v8
	v_cvt_pk_bf16_f32 v8, v8, s0
	global_store_short v[32:33], v8, off offset:1024
	v_mul_f32_e32 v0, v0, v19
	v_mul_f32_e32 v0, v148, v0
	v_mul_f32_e32 v4, v4, v19
	v_mul_f32_e32 v4, v146, v4
	s_waitcnt vmcnt(63)
	v_mov_b32_e32 v8, v206
	v_lshlrev_b32_e32 v8, 16, v8
	v_mul_f32_e32 v13, 0xbfb8aa3b, v8
	v_exp_f32_e32 v13, v13
	s_nop 0
	v_add_f32_e32 v13, 1.0, v13
	v_rcp_f32_e32 v13, v13
	s_nop 0
	v_mul_f32_e32 v8, v13, v8
	v_mul_f32_e32 v0, v8, v0
	v_cvt_pk_bf16_f32 v0, v0, s0
	global_store_short v[32:33], v0, off offset:1056
	v_mul_f32_e32 v8, v28, v19
	v_mul_f32_e32 v8, v147, v8
	s_waitcnt vmcnt(63)
; __device__ __forceinline__ unsigned cvtpk(float lo, float hi) { f32x2_t v = {lo, hi}; bf16x2_t b = __builtin_convertvector(v, bf16x2_t); return __builtin_bit_cast(unsigned, b); }
; template <int X> __device__ __forceinline__ float swz_xor(float v) { return __int_as_float(__builtin_amdgcn_ds_swizzle(__float_as_int(v), (X << 10) | 0x1F)); }
; __device__ __forceinline__ float silu_f(float g) { return g * __builtin_amdgcn_rcpf(1.0f + __expf(-g)); }
; template <bool GLA>
; __device__ __forceinline__ void chunk_pass_c(const ChunkIn& ci, const float* wgl, int unit, unsigned char* wl, int lane, const float* Sb, const float* ng, bf16_t* omix) {
;     ...
;         for (int r = 0; r < 4; ++r) {
;             ss[r] += swz_xor<1>(ss[r]); ss[r] += swz_xor<2>(ss[r]); ss[r] += swz_xor<4>(ss[r]); ss[r] += swz_xor<8>(ss[r]);
;             const float rs = rsqrtf(ss[r] * (1.0f / 64.0f) + EPS);
;             const int t = t0 + 16 * it + 4 * kq + r;
; #pragma unroll
;             for (int et = 0; et < 4; ++et) {
;                 const int e = 16 * et + row;
;                 const float gt = __uint_as_float((unsigned)ci.proj[(size_t)t * DINP + gcol + e] << 16);
;                 const float val = o[et][r] * rs * gn[et] * pg8::silu_f(gt);
;                 omix[(size_t)t * 1024 + ocol + e] = (bf16_t)(cvtpk(val, 0.f) & 0xffffu);
;             }
;         }
	v_mov_b32_e32 v0, v207
	v_lshlrev_b32_e32 v0, 16, v0
	v_mul_f32_e32 v13, 0xbfb8aa3b, v0
	v_exp_f32_e32 v13, v13
	s_nop 0
	v_add_f32_e32 v13, 1.0, v13
	v_rcp_f32_e32 v13, v13
	s_nop 0
	v_mul_f32_e32 v0, v13, v0
	v_mul_f32_e32 v0, v8, v0
	v_cvt_pk_bf16_f32 v0, v0, s0
	global_store_short v[32:33], v0, off offset:1088
	s_waitcnt vmcnt(63)
	v_mov_b32_e32 v0, v208
	v_lshlrev_b32_e32 v0, 16, v0
	v_mul_f32_e32 v8, 0xbfb8aa3b, v0
	v_exp_f32_e32 v8, v8
	s_nop 0
	v_add_f32_e32 v8, 1.0, v8
	v_rcp_f32_e32 v8, v8
	s_nop 0
	v_mul_f32_e32 v0, v8, v0
	v_mul_f32_e32 v0, v4, v0
	v_cvt_pk_bf16_f32 v0, v0, s0
	global_store_short v[24:25], v0, off offset:1024
	v_mul_f32_e32 v0, 0x4b800000, v18
	v_cndmask_b32_e32 v0, v18, v0, vcc
	v_rsq_f32_e32 v0, v0
	v_or_b32_e32 v18, 1, v12
	v_ashrrev_i32_e32 v19, 31, v18
	v_lshlrev_b64 v[20:21], 12, v[18:19]
	v_lshl_add_u64 v[20:21], s[58:59], 0, v[20:21]
	v_mul_f32_e32 v4, 0x45800000, v0
	v_lshl_add_u64 v[22:23], v[20:21], 0, v[210:211]
	v_cndmask_b32_e32 v4, v0, v4, vcc
	v_mul_f32_e32 v8, v9, v4
	v_lshlrev_b64 v[18:19], 11, v[18:19]
	v_mul_f32_e32 v8, v149, v8
	v_lshl_add_u64 v[18:19], s[60:61], 0, v[18:19]
	v_mul_f32_e32 v1, v1, v4
	v_mul_f32_e32 v1, v148, v1
	s_waitcnt vmcnt(63)
	v_mov_b32_e32 v0, v209
	v_lshlrev_b32_e32 v0, 16, v0
	v_mul_f32_e32 v9, 0xbfb8aa3b, v0
	v_exp_f32_e32 v9, v9
	s_nop 0
	v_add_f32_e32 v9, 1.0, v9
	v_rcp_f32_e32 v9, v9
	s_nop 0
	v_mul_f32_e32 v0, v9, v0
	v_mul_f32_e32 v0, v0, v8
	v_cvt_pk_bf16_f32 v0, v0, s0
	v_lshl_add_u64 v[8:9], v[18:19], 0, v[210:211]
	global_store_short v[8:9], v0, off offset:1024
	s_waitcnt vmcnt(63)
	v_mov_b32_e32 v0, v212
	v_lshlrev_b32_e32 v0, 16, v0
	v_mul_f32_e32 v13, 0xbfb8aa3b, v0
	v_exp_f32_e32 v13, v13
	s_nop 0
	v_add_f32_e32 v13, 1.0, v13
	v_rcp_f32_e32 v13, v13
	s_nop 0
	v_mul_f32_e32 v0, v13, v0
	v_mul_f32_e32 v0, v1, v0
	v_cvt_pk_bf16_f32 v0, v0, s0
	global_store_short v[8:9], v0, off offset:1056
	v_mul_f32_e32 v1, v29, v4
	v_mul_f32_e32 v1, v147, v1
	v_mov_b32_e32 v22, v16
	v_mov_b32_e32 v23, v14
	v_mov_b32_e32 v14, v17
	s_waitcnt vmcnt(63)
	v_mov_b32_e32 v0, v213
	v_lshlrev_b32_e32 v0, 16, v0
	v_mul_f32_e32 v13, 0xbfb8aa3b, v0
	v_exp_f32_e32 v13, v13
	s_nop 0
	v_add_f32_e32 v13, 1.0, v13
	v_rcp_f32_e32 v13, v13
	s_nop 0
	v_mul_f32_e32 v0, v13, v0
	v_mul_f32_e32 v0, v1, v0
	v_cvt_pk_bf16_f32 v0, v0, s0
	global_store_short v[8:9], v0, off offset:1088
	v_lshl_add_u64 v[0:1], v[20:21], 0, v[118:119]
	v_mul_f32_e32 v1, v5, v4
	v_mul_f32_e32 v1, v146, v1
	v_mov_b32_e32 v20, v42
	v_mov_b32_e32 v21, v40
	v_mov_b32_e32 v40, v43
	v_pk_add_f32 v[20:21], v[20:21], v[40:41]
	s_waitcnt vmcnt(63)
	v_mov_b32_e32 v0, v214
	v_lshlrev_b32_e32 v0, 16, v0
	v_mul_f32_e32 v4, 0xbfb8aa3b, v0
	v_exp_f32_e32 v4, v4
	v_pk_add_f32 v[20:21], v[20:21], v[22:23]
	v_add_f32_e32 v4, 1.0, v4
	v_rcp_f32_e32 v4, v4
	v_pk_add_f32 v[14:15], v[20:21], v[14:15]
	ds_swizzle_b32 v17, v15 offset:swizzle(SWAP,1)
	ds_swizzle_b32 v16, v14 offset:swizzle(SWAP,1)
	v_mul_f32_e32 v0, v4, v0
	v_mul_f32_e32 v0, v1, v0
	v_cvt_pk_bf16_f32 v4, v0, s0
	v_lshl_add_u64 v[0:1], v[18:19], 0, v[118:119]
	global_store_short v[0:1], v4, off offset:1024
	v_or_b32_e32 v0, 2, v12
	v_ashrrev_i32_e32 v1, 31, v0
	v_lshlrev_b64 v[4:5], 12, v[0:1]
	v_lshl_add_u64 v[4:5], s[58:59], 0, v[4:5]
	v_lshl_add_u64 v[8:9], v[4:5], 0, v[210:211]
	s_waitcnt lgkmcnt(0)
	v_pk_add_f32 v[14:15], v[14:15], v[16:17]
	ds_swizzle_b32 v17, v15 offset:swizzle(SWAP,2)
	ds_swizzle_b32 v16, v14 offset:swizzle(SWAP,2)
	v_lshlrev_b64 v[0:1], 11, v[0:1]
	v_lshl_add_u64 v[0:1], s[60:61], 0, v[0:1]
	v_lshl_add_u64 v[4:5], v[4:5], 0, v[118:119]
	s_waitcnt lgkmcnt(0)
	v_pk_add_f32 v[14:15], v[14:15], v[16:17]
	ds_swizzle_b32 v17, v15 offset:swizzle(SWAP,4)
	ds_swizzle_b32 v16, v14 offset:swizzle(SWAP,4)
	s_waitcnt lgkmcnt(0)
	v_pk_add_f32 v[14:15], v[14:15], v[16:17]
	ds_swizzle_b32 v17, v15 offset:swizzle(SWAP,8)
	ds_swizzle_b32 v16, v14 offset:swizzle(SWAP,8)
	s_waitcnt lgkmcnt(0)
	v_pk_add_f32 v[14:15], v[14:15], v[16:17]
	s_nop 0
	v_pk_fma_f32 v[14:15], v[14:15], s[6:7], v[120:121] op_sel_hi:[1,0,0]
	s_waitcnt vmcnt(63)
; __device__ __forceinline__ unsigned cvtpk(float lo, float hi) { f32x2_t v = {lo, hi}; bf16x2_t b = __builtin_convertvector(v, bf16x2_t); return __builtin_bit_cast(unsigned, b); }
; template <int X> __device__ __forceinline__ float swz_xor(float v) { return __int_as_float(__builtin_amdgcn_ds_swizzle(__float_as_int(v), (X << 10) | 0x1F)); }
; __device__ __forceinline__ float silu_f(float g) { return g * __builtin_amdgcn_rcpf(1.0f + __expf(-g)); }
; template <bool GLA>
; __device__ __forceinline__ void chunk_pass_c(const ChunkIn& ci, const float* wgl, int unit, unsigned char* wl, int lane, const float* Sb, const float* ng, bf16_t* omix) {
;     ...
;         for (int r = 0; r < 4; ++r) {
;             ss[r] += swz_xor<1>(ss[r]); ss[r] += swz_xor<2>(ss[r]); ss[r] += swz_xor<4>(ss[r]); ss[r] += swz_xor<8>(ss[r]);
;             const float rs = rsqrtf(ss[r] * (1.0f / 64.0f) + EPS);
;             const int t = t0 + 16 * it + 4 * kq + r;
; #pragma unroll
;             for (int et = 0; et < 4; ++et) {
;                 const int e = 16 * et + row;
;                 const float gt = __uint_as_float((unsigned)ci.proj[(size_t)t * DINP + gcol + e] << 16);
;                 const float val = o[et][r] * rs * gn[et] * pg8::silu_f(gt);
;                 omix[(size_t)t * 1024 + ocol + e] = (bf16_t)(cvtpk(val, 0.f) & 0xffffu);
;             }
;         }
;     }
;     __builtin_amdgcn_s_waitcnt(0); asm volatile("" ::: "memory");
	v_mov_b32_e32 v13, v215
	v_lshlrev_b32_e32 v13, 16, v13
	v_mul_f32_e32 v18, 0xbfb8aa3b, v13
	v_exp_f32_e32 v18, v18
	v_mul_f32_e32 v16, 0x4b800000, v15
	v_cmp_gt_f32_e64 s[42:43], s96, v15
	v_cmp_gt_f32_e32 vcc, s96, v14
	v_add_f32_e32 v18, 1.0, v18
	v_cndmask_b32_e64 v15, v15, v16, s[42:43]
	v_rsq_f32_e32 v15, v15
	v_rcp_f32_e32 v18, v18
	v_mul_f32_e32 v16, 0x45800000, v15
	v_cndmask_b32_e64 v15, v15, v16, s[42:43]
	v_mul_f32_e32 v10, v10, v15
	v_mul_f32_e32 v13, v18, v13
	v_mul_f32_e32 v10, v149, v10
	v_mul_f32_e32 v10, v13, v10
	v_lshl_add_u64 v[18:19], v[0:1], 0, v[210:211]
	v_cvt_pk_bf16_f32 v10, v10, s0
	global_store_short v[18:19], v10, off offset:1024
	v_mul_f32_e32 v2, v2, v15
	v_mul_f32_e32 v2, v148, v2
	v_lshl_add_u64 v[0:1], v[0:1], 0, v[118:119]
	s_waitcnt vmcnt(63)
	v_mov_b32_e32 v10, v216
	v_lshlrev_b32_e32 v10, 16, v10
	v_mul_f32_e32 v13, 0xbfb8aa3b, v10
	v_exp_f32_e32 v13, v13
	s_nop 0
	v_add_f32_e32 v13, 1.0, v13
	v_rcp_f32_e32 v13, v13
	s_nop 0
	v_mul_f32_e32 v10, v13, v10
	v_mul_f32_e32 v2, v2, v10
	v_cvt_pk_bf16_f32 v2, v2, s0
	global_store_short v[18:19], v2, off offset:1056
	v_mul_f32_e32 v8, v30, v15
	v_mul_f32_e32 v8, v147, v8
	s_waitcnt vmcnt(63)
	v_mov_b32_e32 v2, v217
	v_lshlrev_b32_e32 v2, 16, v2
	v_mul_f32_e32 v9, 0xbfb8aa3b, v2
	v_exp_f32_e32 v9, v9
	s_nop 0
	v_add_f32_e32 v9, 1.0, v9
	v_rcp_f32_e32 v9, v9
	s_nop 0
	v_mul_f32_e32 v2, v9, v2
	v_mul_f32_e32 v2, v8, v2
	v_cvt_pk_bf16_f32 v2, v2, s0
	global_store_short v[18:19], v2, off offset:1088
	v_mul_f32_e32 v4, v6, v15
	v_mul_f32_e32 v4, v146, v4
	s_waitcnt vmcnt(63)
	v_mov_b32_e32 v2, v218
	v_lshlrev_b32_e32 v2, 16, v2
	v_mul_f32_e32 v5, 0xbfb8aa3b, v2
	v_exp_f32_e32 v5, v5
	s_nop 0
	v_add_f32_e32 v5, 1.0, v5
	v_rcp_f32_e32 v5, v5
	s_nop 0
	v_mul_f32_e32 v2, v5, v2
	v_mul_f32_e32 v2, v4, v2
	v_cvt_pk_bf16_f32 v2, v2, s0
	global_store_short v[0:1], v2, off offset:1024
	v_mul_f32_e32 v0, 0x4b800000, v14
	v_cndmask_b32_e32 v0, v14, v0, vcc
	v_rsq_f32_e32 v0, v0
	s_nop 0
	v_mul_f32_e32 v1, 0x45800000, v0
	v_cndmask_b32_e32 v6, v0, v1, vcc
	v_or_b32_e32 v0, 3, v12
	v_ashrrev_i32_e32 v1, 31, v0
	v_lshlrev_b64 v[4:5], 12, v[0:1]
	v_lshl_add_u64 v[4:5], s[58:59], 0, v[4:5]
	v_lshl_add_u64 v[8:9], v[4:5], 0, v[210:211]
	v_mul_f32_e32 v10, v11, v6
	v_lshlrev_b64 v[0:1], 11, v[0:1]
	v_mul_f32_e32 v10, v149, v10
	v_lshl_add_u64 v[0:1], s[60:61], 0, v[0:1]
	v_mul_f32_e32 v3, v3, v6
	v_mul_f32_e32 v3, v148, v3
	s_waitcnt vmcnt(63)
	v_mov_b32_e32 v2, v219
	v_lshlrev_b32_e32 v2, 16, v2
	v_mul_f32_e32 v11, 0xbfb8aa3b, v2
	v_exp_f32_e32 v11, v11
	s_nop 0
	v_add_f32_e32 v11, 1.0, v11
	v_rcp_f32_e32 v11, v11
	s_nop 0
	v_mul_f32_e32 v2, v11, v2
	v_mul_f32_e32 v2, v2, v10
	v_cvt_pk_bf16_f32 v2, v2, s0
	v_lshl_add_u64 v[10:11], v[0:1], 0, v[210:211]
	global_store_short v[10:11], v2, off offset:1024
	v_lshl_add_u64 v[0:1], v[0:1], 0, v[118:119]
	s_waitcnt vmcnt(63)
	v_mov_b32_e32 v2, v220
	v_lshlrev_b32_e32 v2, 16, v2
	v_mul_f32_e32 v12, 0xbfb8aa3b, v2
	v_exp_f32_e32 v12, v12
	s_nop 0
	v_add_f32_e32 v12, 1.0, v12
	v_rcp_f32_e32 v12, v12
	s_nop 0
	v_mul_f32_e32 v2, v12, v2
	v_mul_f32_e32 v2, v3, v2
	v_cvt_pk_bf16_f32 v2, v2, s0
	global_store_short v[10:11], v2, off offset:1056
	v_mul_f32_e32 v3, v31, v6
	v_mul_f32_e32 v3, v147, v3
	s_waitcnt vmcnt(63)
	v_mov_b32_e32 v2, v221
	v_lshlrev_b32_e32 v2, 16, v2
	v_mul_f32_e32 v8, 0xbfb8aa3b, v2
	v_exp_f32_e32 v8, v8
	s_nop 0
	v_add_f32_e32 v8, 1.0, v8
	v_rcp_f32_e32 v8, v8
	s_nop 0
	v_mul_f32_e32 v2, v8, v2
	v_mul_f32_e32 v2, v3, v2
	v_cvt_pk_bf16_f32 v2, v2, s0
	global_store_short v[10:11], v2, off offset:1088
	v_lshl_add_u64 v[2:3], v[4:5], 0, v[118:119]
	v_mul_f32_e32 v3, v7, v6
	v_mul_f32_e32 v3, v146, v3
	s_waitcnt vmcnt(63)
	v_mov_b32_e32 v2, v222
	v_lshlrev_b32_e32 v2, 16, v2
	v_mul_f32_e32 v4, 0xbfb8aa3b, v2
	v_exp_f32_e32 v4, v4
	s_nop 0
	v_add_f32_e32 v4, 1.0, v4
	v_rcp_f32_e32 v4, v4
	s_nop 0
	v_mul_f32_e32 v2, v4, v2
	v_mul_f32_e32 v2, v3, v2
	v_cvt_pk_bf16_f32 v2, v2, s0
	global_store_short v[0:1], v2, off offset:1024
	s_waitcnt lgkmcnt(0)

; __device__ __forceinline__ unsigned cvtpk(float lo, float hi) { f32x2_t v = {lo, hi}; bf16x2_t b = __builtin_convertvector(v, bf16x2_t); return __builtin_bit_cast(unsigned, b); }
; __device__ __forceinline__ void chunk_load_vt(const bf16_t* proj, int t0, int vcol, unsigned char* wl, int lane) {
;     const bf16_t* vp = proj + (size_t)(t0 + lane) * DINP + vcol;
; #pragma unroll
;     for (int cidx = 0; cidx < 8; ++cidx) {
;         const u32x4 v = *(const u32x4*)(vp + cidx * 8);
;         const unsigned w4[4] = {v.x, v.y, v.z, v.w};
; #pragma unroll
;         for (int j = 0; j < 4; ++j) {
;             *(bf16_t*)(wl + (cidx * 8 + 2 * j) * GP + lane * 2) = (bf16_t)(w4[j] & 0xffffu);
;             *(bf16_t*)(wl + (cidx * 8 + 2 * j + 1) * GP + lane * 2) = (bf16_t)(w4[j] >> 16);
;         }
;     }
; }
; template <bool GLA>
; __device__ __forceinline__ void chunk_pass_c(const ChunkIn& ci, const float* wgl, int unit, unsigned char* wl, int lane, const float* Sb, const float* ng, bf16_t* omix) {
;     ...
;     chunk_load_vt(ci.proj, t0, (GLA ? C_GV : C_RV) + h * 64, wl, lane);
;     unsigned char* sst = wl + 64 * GP;
;     { const float* sp = Sb + (size_t)unit * 2048 + lane;
;       float sv[32];
; #pragma unroll
;       for (int d = 0; d < 32; ++d) sv[d] = sp[d * 64];
; #pragma unroll
;       for (int q4 = 0; q4 < 4; ++q4) {
;           u32x4 w; w.x = cvtpk(sv[4 * q4 + 0], sv[4 * q4 + 1]); w.y = cvtpk(sv[4 * q4 + 2], sv[4 * q4 + 3]); w.z = cvtpk(sv[16 + 4 * q4 + 0], sv[16 + 4 * q4 + 1]); w.w = cvtpk(sv[16 + 4 * q4 + 2], sv[16 + 4 * q4 + 3]);
;           *(u32x4*)(sst + lane * 64 + q4 * 16) = w;
;       } }
.LBB0_215:
	v_mov_b32_e32 v0, v211
	v_readlane_b32 s3, v254, 60
	v_mbcnt_lo_u32_b32 v0, -1, v0
	s_waitcnt vmcnt(35)
	v_mbcnt_hi_u32_b32 v133, -1, v0
	v_and_b32_e32 v147, 63, v133
	v_lshrrev_b32_e32 v119, 4, v147
	s_mov_b64 s[6:7], -1
	s_cmpk_gt_i32 s25, 0x7ff
	v_and_b32_e32 v156, 15, v133
	v_lshlrev_b32_e32 v210, 2, v147
	v_lshl_add_u32 v158, v147, 1, s3
	v_lshl_add_u32 v157, v147, 6, s3
	v_lshlrev_b32_e32 v97, 2, v119
	v_lshlrev_b32_e32 v114, 3, v119
	s_cbranch_scc0 .LBB0_217
	s_load_dwordx2 s[4:5], s[0:1], 0x88
	s_mov_b32 s65, s17
	v_mov_b32_e32 v115, v211
	v_cmp_lt_u32_e64 s[42:43], v97, v156
	v_lshlrev_b32_e32 v110, 1, v156
	s_waitcnt lgkmcnt(0)
	s_add_u32 s48, s4, s56
	s_addc_u32 s49, s5, s57
	s_add_i32 s3, s90, 0xffff8000
	s_and_b32 s4, s3, 0x7fc0
	v_or_b32_e32 v0, s4, v147
	s_lshl_b64 s[4:5], s[64:65], 2
	s_add_u32 s4, s37, s4
	v_lshlrev_b32_e32 v28, 12, v0
	s_addc_u32 s5, s70, s5
	global_load_dwordx4 v[0:3], v28, s[58:59] offset:2912
	global_load_dwordx4 v[4:7], v28, s[58:59] offset:2928
	global_load_dwordx4 v[8:11], v28, s[58:59] offset:2944
	global_load_dwordx4 v[12:15], v28, s[58:59] offset:2960
	global_load_dwordx4 v[16:19], v28, s[58:59] offset:2976
	global_load_dwordx4 v[20:23], v28, s[58:59] offset:2992
	global_load_dwordx4 v[24:27], v28, s[58:59] offset:3008
	s_nop 0
	global_load_dwordx4 v[28:31], v28, s[58:59] offset:3024
	v_lshl_add_u64 v[32:33], s[4:5], 0, v[210:211]
	v_add_co_u32_e32 v32, vcc, s10, v32
	global_load_dword v34, v210, s[4:5]
	global_load_dword v35, v210, s[4:5] offset:256
	global_load_dword v36, v210, s[4:5] offset:512
	global_load_dword v37, v210, s[4:5] offset:768
	global_load_dword v38, v210, s[4:5] offset:1024
	global_load_dword v39, v210, s[4:5] offset:1280
	global_load_dword v40, v210, s[4:5] offset:1536
	global_load_dword v41, v210, s[4:5] offset:1792
	global_load_dword v42, v210, s[4:5] offset:2048
	global_load_dword v43, v210, s[4:5] offset:2304
	global_load_dword v44, v210, s[4:5] offset:2560
	global_load_dword v45, v210, s[4:5] offset:2816
	global_load_dword v46, v210, s[4:5] offset:3072
	global_load_dword v47, v210, s[4:5] offset:3328
	global_load_dword v48, v210, s[4:5] offset:3584
	global_load_dword v49, v210, s[4:5] offset:3840
	v_addc_co_u32_e32 v33, vcc, 0, v33, vcc
	global_load_dword v50, v[32:33], off
	global_load_dword v51, v[32:33], off offset:256
	global_load_dword v52, v[32:33], off offset:512
	global_load_dword v53, v[32:33], off offset:768
	global_load_dword v54, v[32:33], off offset:1024
	global_load_dword v55, v[32:33], off offset:1280
	global_load_dword v56, v[32:33], off offset:1536
	global_load_dword v57, v[32:33], off offset:1792
	global_load_dword v58, v[32:33], off offset:2048
	global_load_dword v59, v[32:33], off offset:2304
	global_load_dword v60, v[32:33], off offset:2560
	global_load_dword v61, v[32:33], off offset:2816
	global_load_dword v62, v[32:33], off offset:3072
	global_load_dword v63, v[32:33], off offset:3328
	global_load_dword v64, v[32:33], off offset:3584
	s_nop 0
	global_load_dword v32, v[32:33], off offset:3840
	s_and_b32 s6, s90, 0x7fc0
	v_readlane_b32 s4, v255, 14
	s_or_b32 s5, s6, 16
	s_or_b32 s3, s3, 48
	v_or_b32_e32 v165, s6, v97
	v_mov_b32_e32 v111, v211
	v_lshlrev_b32_e32 v159, 2, v156
	v_or_b32_e32 v177, 48, v147
	s_waitcnt vmcnt(39)
	ds_write_b16 v158, v0
	ds_write_b16_d16_hi v158, v0 offset:144
	ds_write_b16 v158, v1 offset:288
	ds_write_b16_d16_hi v158, v1 offset:432
	ds_write_b16 v158, v2 offset:576
	ds_write_b16_d16_hi v158, v2 offset:720
	ds_write_b16 v158, v3 offset:864
	ds_write_b16_d16_hi v158, v3 offset:1008
	s_waitcnt vmcnt(38)
	ds_write_b16 v158, v4 offset:1152
	ds_write_b16_d16_hi v158, v4 offset:1296
	ds_write_b16 v158, v5 offset:1440
	ds_write_b16_d16_hi v158, v5 offset:1584
	ds_write_b16 v158, v6 offset:1728
	ds_write_b16_d16_hi v158, v6 offset:1872
	ds_write_b16 v158, v7 offset:2016
	ds_write_b16_d16_hi v158, v7 offset:2160
	s_waitcnt vmcnt(37)
	ds_write_b16 v158, v8 offset:2304
	ds_write_b16_d16_hi v158, v8 offset:2448
	ds_write_b16 v158, v9 offset:2592
	ds_write_b16_d16_hi v158, v9 offset:2736
	ds_write_b16 v158, v10 offset:2880
	ds_write_b16_d16_hi v158, v10 offset:3024
	ds_write_b16 v158, v11 offset:3168
	ds_write_b16_d16_hi v158, v11 offset:3312
	s_waitcnt vmcnt(36)
	ds_write_b16 v158, v12 offset:3456
	ds_write_b16_d16_hi v158, v12 offset:3600
	ds_write_b16 v158, v13 offset:3744
	ds_write_b16_d16_hi v158, v13 offset:3888
	ds_write_b16 v158, v14 offset:4032
	ds_write_b16_d16_hi v158, v14 offset:4176
	ds_write_b16 v158, v15 offset:4320
	ds_write_b16_d16_hi v158, v15 offset:4464
	s_waitcnt vmcnt(35)
	ds_write_b16 v158, v16 offset:4608
	ds_write_b16_d16_hi v158, v16 offset:4752
	ds_write_b16 v158, v17 offset:4896
	ds_write_b16_d16_hi v158, v17 offset:5040
	ds_write_b16 v158, v18 offset:5184
	ds_write_b16_d16_hi v158, v18 offset:5328
	ds_write_b16 v158, v19 offset:5472
	ds_write_b16_d16_hi v158, v19 offset:5616
	s_waitcnt vmcnt(34)
	ds_write_b16 v158, v20 offset:5760
	ds_write_b16_d16_hi v158, v20 offset:5904
	ds_write_b16 v158, v21 offset:6048
	ds_write_b16_d16_hi v158, v21 offset:6192
	ds_write_b16 v158, v22 offset:6336
	ds_write_b16_d16_hi v158, v22 offset:6480
	ds_write_b16 v158, v23 offset:6624
	ds_write_b16_d16_hi v158, v23 offset:6768
	s_waitcnt vmcnt(33)
	ds_write_b16 v158, v24 offset:6912
	ds_write_b16_d16_hi v158, v24 offset:7056
	ds_write_b16 v158, v25 offset:7200
	ds_write_b16_d16_hi v158, v25 offset:7344
	ds_write_b16 v158, v26 offset:7488
	ds_write_b16_d16_hi v158, v26 offset:7632
	ds_write_b16 v158, v27 offset:7776
	ds_write_b16_d16_hi v158, v27 offset:7920
	s_waitcnt vmcnt(32)
; __device__ __forceinline__ unsigned cvtpk(float lo, float hi) { f32x2_t v = {lo, hi}; bf16x2_t b = __builtin_convertvector(v, bf16x2_t); return __builtin_bit_cast(unsigned, b); }
; template <bool GLA>
; __device__ __forceinline__ void chunk_load(const ChunkIn& ci, int t, int h, int kq, ChunkRaw& r) {
;     const bf16_t* pr = ci.proj + (size_t)t * DINP;
;     const int cq = GLA ? C_GQ : C_RQ, ck = GLA ? C_GK : C_RK;
;     r.qa = *(const u32x2*)(pr + cq + h * 32 + 4 * kq); r.qb = *(const u32x2*)(pr + cq + h * 32 + 16 + 4 * kq);
;     r.ka = *(const u32x2*)(pr + ck + h * 32 + 4 * kq); r.kb = *(const u32x2*)(pr + ck + h * 32 + 16 + 4 * kq);
;     if (GLA) { r.g0 = *(const u32x4*)(pr + C_GG); r.g1 = *(const u32x4*)(pr + C_GG + 8); }
; template <bool GLA>
; __device__ __forceinline__ void chunk_pass_c(const ChunkIn& ci, const float* wgl, int unit, unsigned char* wl, int lane, const float* Sb, const float* ng, bf16_t* omix) {
;     ...
;     { const float* sp = Sb + (size_t)unit * 2048 + lane;
;       float sv[32];
; #pragma unroll
;       for (int d = 0; d < 32; ++d) sv[d] = sp[d * 64];
; #pragma unroll
;       for (int q4 = 0; q4 < 4; ++q4) {
;           u32x4 w; w.x = cvtpk(sv[4 * q4 + 0], sv[4 * q4 + 1]); w.y = cvtpk(sv[4 * q4 + 2], sv[4 * q4 + 3]); w.z = cvtpk(sv[16 + 4 * q4 + 0], sv[16 + 4 * q4 + 1]); w.w = cvtpk(sv[16 + 4 * q4 + 2], sv[16 + 4 * q4 + 3]);
;           *(u32x4*)(sst + lane * 64 + q4 * 16) = w;
;       } }
;     asm volatile("" ::: "memory");
;     float carry[8] = {0.f, 0.f, 0.f, 0.f, 0.f, 0.f, 0.f, 0.f};
;     int hh_ = h; asm volatile("" : "+s"(hh_)); const float hf = (float)hh_;
;     const float lg = GLA ? 0.f : __logf(1.0f - __builtin_amdgcn_exp2f(-5.0f - hf));
;     bf16x8 qf[4], kf[4], qb[4], kb[4];
;     ChunkRaw raw[4];
; #pragma unroll
;     for (int it = 0; it < 4; ++it) chunk_load<GLA>(ci, t0 + 16 * it + row, h, kq, raw[it]);
;     bf16x8 wfr[2]; f32x4 bfr[2]; if (GLA) chunk_gate_frags(wgl, h, row, kq, wfr, bfr);
	ds_write_b16 v158, v28 offset:8064
	ds_write_b16_d16_hi v158, v28 offset:8208
	ds_write_b16 v158, v29 offset:8352
	ds_write_b16_d16_hi v158, v29 offset:8496
	ds_write_b16 v158, v30 offset:8640
	ds_write_b16_d16_hi v158, v30 offset:8784
	ds_write_b16 v158, v31 offset:8928
	ds_write_b16_d16_hi v158, v31 offset:9072
	s_waitcnt vmcnt(30)
	v_cvt_pk_bf16_f32 v0, v34, v35
	s_waitcnt vmcnt(28)
	v_cvt_pk_bf16_f32 v1, v36, v37
	s_waitcnt vmcnt(14)
	v_cvt_pk_bf16_f32 v2, v50, v51
	s_waitcnt vmcnt(12)
	v_cvt_pk_bf16_f32 v3, v52, v53
	ds_write_b128 v157, v[0:3] offset:9216
	v_cvt_pk_bf16_f32 v0, v38, v39
	v_cvt_pk_bf16_f32 v1, v40, v41
	s_waitcnt vmcnt(10)
	v_cvt_pk_bf16_f32 v2, v54, v55
	s_waitcnt vmcnt(8)
	v_cvt_pk_bf16_f32 v3, v56, v57
	ds_write_b128 v157, v[0:3] offset:9232
	v_cvt_pk_bf16_f32 v0, v42, v43
	v_cvt_pk_bf16_f32 v1, v44, v45
	s_waitcnt vmcnt(6)
	v_cvt_pk_bf16_f32 v2, v58, v59
	s_waitcnt vmcnt(4)
	v_cvt_pk_bf16_f32 v3, v60, v61
	ds_write_b128 v157, v[0:3] offset:9248
	v_cvt_pk_bf16_f32 v0, v46, v47
	v_cvt_pk_bf16_f32 v1, v48, v49
	s_waitcnt vmcnt(2)
	v_cvt_pk_bf16_f32 v2, v62, v63
	s_waitcnt vmcnt(0)
	v_cvt_pk_bf16_f32 v3, v64, v32
	v_or_b32_e32 v6, s6, v156
	ds_write_b128 v157, v[0:3] offset:9264
	v_and_b32_e32 v0, 48, v147
	v_mov_b32_e32 v1, v211
	v_lshlrev_b32_e32 v4, 12, v6
	v_mov_b32_e32 v5, v211
	v_lshl_add_u64 v[2:3], s[22:23], 0, v[0:1]
	v_lshl_add_u64 v[4:5], s[62:63], 0, v[4:5]
	v_lshlrev_b32_e32 v6, 6, v6
	v_mov_b32_e32 v7, v211
	v_lshl_add_u64 v[0:1], s[20:21], 0, v[0:1]
	v_lshl_add_u64 v[4:5], v[4:5], 0, v[114:115]
	v_lshl_add_u64 v[8:9], v[2:3], 0, v[6:7]
	global_load_dwordx2 v[24:25], v[4:5], off offset:2400
	global_load_dwordx2 v[26:27], v[4:5], off offset:2432
	v_lshl_add_u64 v[6:7], v[0:1], 0, v[6:7]
	global_load_dwordx4 v[8:11], v[8:9], off
	s_nop 0
	global_load_dwordx4 v[16:19], v[6:7], off
	global_load_dwordx2 v[32:33], v[4:5], off offset:2656
	global_load_dwordx2 v[34:35], v[4:5], off offset:2688
	v_cvt_f32_i32_e32 v12, s4
	v_mov_b32_e32 v5, v211
	s_or_b32 s4, s6, 32
	s_mov_b32 s6, 0x358637bd
	v_sub_f32_e32 v6, 0xc0a00000, v12
	v_exp_f32_e32 v6, v6
	s_waitcnt vmcnt(5)
	v_lshlrev_b32_e32 v40, 16, v24
	v_sub_f32_e32 v36, 1.0, v6
	v_or_b32_e32 v6, s5, v156
	v_lshlrev_b32_e32 v4, 12, v6
	v_lshl_add_u64 v[4:5], s[62:63], 0, v[4:5]
	v_lshl_add_u64 v[4:5], v[4:5], 0, v[114:115]
	global_load_dwordx2 v[144:145], v[4:5], off offset:2400
	global_load_dwordx2 v[142:143], v[4:5], off offset:2432
	global_load_dwordx2 v[30:31], v[4:5], off offset:2656
	global_load_dwordx2 v[28:29], v[4:5], off offset:2688
	v_lshlrev_b32_e32 v4, 6, v6
	v_mov_b32_e32 v5, v211
	v_lshl_add_u64 v[6:7], v[2:3], 0, v[4:5]
	v_lshl_add_u64 v[4:5], v[0:1], 0, v[4:5]
	global_load_dwordx4 v[76:79], v[6:7], off
	global_load_dwordx4 v[80:83], v[4:5], off
	v_or_b32_e32 v6, s4, v156
	v_lshlrev_b32_e32 v4, 12, v6
	v_mov_b32_e32 v5, v211
	v_lshl_add_u64 v[4:5], s[62:63], 0, v[4:5]
	v_lshl_add_u64 v[4:5], v[4:5], 0, v[114:115]
	global_load_dwordx2 v[130:131], v[4:5], off offset:2400
	global_load_dwordx2 v[128:129], v[4:5], off offset:2432
	global_load_dwordx2 v[22:23], v[4:5], off offset:2656
	global_load_dwordx2 v[20:21], v[4:5], off offset:2688
	v_lshlrev_b32_e32 v4, 6, v6
	v_mov_b32_e32 v5, v211
	v_lshl_add_u64 v[6:7], v[2:3], 0, v[4:5]
	v_lshl_add_u64 v[4:5], v[0:1], 0, v[4:5]
	global_load_dwordx4 v[64:67], v[6:7], off
	global_load_dwordx4 v[68:71], v[4:5], off
	v_or_b32_e32 v4, s3, v156
	v_mov_b32_e32 v5, v211
	v_lshlrev_b64 v[6:7], 12, v[4:5]
	v_lshl_add_u64 v[6:7], s[62:63], 0, v[6:7]
	v_cmp_gt_f32_e32 vcc, s96, v36
	v_lshl_add_u64 v[6:7], v[6:7], 0, v[114:115]
	s_and_b64 s[8:9], vcc, exec
	global_load_dwordx2 v[108:109], v[6:7], off offset:2400
	global_load_dwordx2 v[106:107], v[6:7], off offset:2432
	global_load_dwordx2 v[14:15], v[6:7], off offset:2656
	global_load_dwordx2 v[12:13], v[6:7], off offset:2688
	v_lshlrev_b64 v[4:5], 6, v[4:5]
	s_cselect_b32 s7, 32, 0
	v_lshl_add_u64 v[2:3], v[2:3], 0, v[4:5]
	v_ldexp_f32 v6, v36, s7
	v_lshl_add_u64 v[4:5], v[0:1], 0, v[4:5]
	v_log_f32_e32 v36, v6
	global_load_dwordx4 v[0:3], v[2:3], off
	s_nop 0
	global_load_dwordx4 v[4:7], v[4:5], off
	s_mov_b32 s7, 0x3f317217
	v_cndmask_b32_e32 v37, 0, v237, vcc
	v_mul_f32_e32 v38, 0x3f317217, v36
	v_fma_f32 v38, v36, s7, -v38
	v_fmac_f32_e32 v38, 0x3377d1cf, v36
	s_mov_b32 s7, 0x7f800000
	v_fmac_f32_e32 v38, 0x3f317217, v36
	v_cmp_lt_f32_e64 vcc, |v36|, s7
	v_and_b32_e32 v41, 0xffff0000, v24
	s_waitcnt vmcnt(18)
; __device__ __forceinline__ unsigned cvtpk(float lo, float hi) { f32x2_t v = {lo, hi}; bf16x2_t b = __builtin_convertvector(v, bf16x2_t); return __builtin_bit_cast(unsigned, b); }
; template <bool GLA>
; __device__ __forceinline__ void chunk_tile(const ChunkRaw& raw, const bf16x8 (&wfr)[2], const f32x4 (&bfr)[2], int h, int it, int row, int kq, float lg, float (&carry)[8], float (&bq)[8], float (&qv)[8], float (&kv)[8]) {
;     ...
; #pragma unroll
;         for (int j = 0; j < 4; ++j) {
;             qv[j] = (q[j] * cc[j] - q[4 + j] * ss[j]) * qs; qv[4 + j] = (q[j] * ss[j] + q[4 + j] * cc[j]) * qs;
;             kv[j] = k[j] * cc[j] - k[4 + j] * ss[j];        kv[4 + j] = k[j] * ss[j] + k[4 + j] * cc[j];
;         }
; #pragma unroll
;         for (int j = 0; j < 8; ++j) { bq[j] = (float)(16 * it + row + 1) * lg; carry[j] = 64.0f * lg; }
; template <bool GLA>
; __device__ __forceinline__ void chunk_pass_c(const ChunkIn& ci, const float* wgl, int unit, unsigned char* wl, int lane, const float* Sb, const float* ng, bf16_t* omix) {
;     ...
;         float a[8], bneg[8], cpos[8], dneg[8];
; #pragma unroll
;         for (int j = 0; j < 8; ++j) { const float eb = __expf(bq[j]), enb = __expf(-bq[j]); a[j] = qv[j] * eb; bneg[j] = kv[j] * enb; cpos[j] = qv[j] * enb; dneg[j] = kv[j] * eb; }
;         qf[it] = __builtin_bit_cast(bf16x8, (u32x4){cvtpk(a[0], a[1]), cvtpk(a[2], a[3]), cvtpk(a[4], a[5]), cvtpk(a[6], a[7])});
;         kf[it] = __builtin_bit_cast(bf16x8, (u32x4){cvtpk(bneg[0], bneg[1]), cvtpk(bneg[2], bneg[3]), cvtpk(bneg[4], bneg[5]), cvtpk(bneg[6], bneg[7])});
;         qb[it] = __builtin_bit_cast(bf16x8, (u32x4){cvtpk(cpos[0], cpos[1]), cvtpk(cpos[2], cpos[3]), cvtpk(cpos[4], cpos[5]), cvtpk(cpos[6], cpos[7])});
;         kb[it] = __builtin_bit_cast(bf16x8, (u32x4){cvtpk(dneg[0], dneg[1]), cvtpk(dneg[2], dneg[3]), cvtpk(dneg[4], dneg[5]), cvtpk(dneg[6], dneg[7])});
	v_lshlrev_b32_e32 v50, 16, v34
	v_cndmask_b32_e32 v36, v36, v38, vcc
	v_sub_f32_e32 v39, v36, v37
	v_add_u32_e32 v36, 1, v156
	v_cvt_f32_ubyte0_e32 v36, v36
	v_mul_f32_e32 v37, v39, v36
	v_mul_f32_e32 v36, 0x3fb8aa3b, v37
	v_mul_f32_e32 v37, 0xbfb8aa3b, v37
	v_exp_f32_e32 v36, v36
	v_exp_f32_e32 v38, v37
	v_and_b32_e32 v51, 0xffff0000, v34
	v_lshlrev_b32_e32 v42, 16, v26
	v_and_b32_e32 v43, 0xffff0000, v26
	v_pk_mul_f32 v[44:45], v[16:17], v[40:41]
	v_lshlrev_b32_e32 v48, 16, v32
	v_and_b32_e32 v49, 0xffff0000, v32
	v_pk_mul_f32 v[52:53], v[8:9], v[50:51]
	v_pk_fma_f32 v[44:45], v[8:9], v[42:43], v[44:45]
	v_pk_mul_f32 v[42:43], v[16:17], v[42:43]
	v_pk_fma_f32 v[52:53], v[16:17], v[48:49], v[52:53]
	v_pk_mul_f32 v[16:17], v[16:17], v[50:51]
	v_pk_fma_f32 v[40:41], v[8:9], v[40:41], v[42:43] neg_lo:[0,0,1] neg_hi:[0,0,1]
	v_pk_fma_f32 v[8:9], v[8:9], v[48:49], v[16:17] neg_lo:[0,0,1] neg_hi:[0,0,1]
	v_lshlrev_b32_e32 v24, 16, v27
	v_pk_mul_f32 v[16:17], v[38:39], v[8:9] op_sel_hi:[0,1]
	v_pk_mul_f32 v[48:49], v[36:37], v[8:9] op_sel_hi:[0,1]
	v_lshlrev_b32_e32 v8, 16, v25
	v_and_b32_e32 v9, 0xffff0000, v25
	v_and_b32_e32 v25, 0xffff0000, v27
	v_pk_mul_f32 v[26:27], v[18:19], v[8:9]
	v_lshlrev_b32_e32 v34, 16, v35
	v_and_b32_e32 v35, 0xffff0000, v35
	v_pk_fma_f32 v[26:27], v[10:11], v[24:25], v[26:27]
	v_pk_mul_f32 v[24:25], v[18:19], v[24:25]
	v_lshlrev_b32_e32 v32, 16, v33
	v_and_b32_e32 v33, 0xffff0000, v33
	v_pk_mul_f32 v[56:57], v[10:11], v[34:35]
	s_mov_b32 s8, 0x3e3504f3
	v_pk_fma_f32 v[8:9], v[10:11], v[8:9], v[24:25] neg_lo:[0,0,1] neg_hi:[0,0,1]
	v_pk_fma_f32 v[56:57], v[18:19], v[32:33], v[56:57]
	v_pk_mul_f32 v[18:19], v[18:19], v[34:35]
	v_pk_mul_f32 v[8:9], v[8:9], s[8:9] op_sel_hi:[1,0]
	v_pk_fma_f32 v[10:11], v[10:11], v[32:33], v[18:19] neg_lo:[0,0,1] neg_hi:[0,0,1]
	v_pk_mul_f32 v[24:25], v[36:37], v[8:9] op_sel_hi:[0,1]
	v_pk_mul_f32 v[32:33], v[36:37], v[10:11] op_sel_hi:[0,1]
	v_cvt_pk_bf16_f32 v89, v24, v25
	v_cvt_pk_bf16_f32 v25, v32, v33
	v_add_u32_e32 v32, 17, v156
	v_cvt_f32_ubyte0_e32 v32, v32
	v_mul_f32_e32 v164, v39, v32
	v_pk_mul_f32 v[44:45], v[44:45], s[8:9] op_sel_hi:[1,0]
	v_pk_mul_f32 v[40:41], v[40:41], s[8:9] op_sel_hi:[1,0]
	v_pk_mul_f32 v[26:27], v[26:27], s[8:9] op_sel_hi:[1,0]
	v_pk_mul_f32 v[34:35], v[38:39], v[56:57] op_sel_hi:[0,1]
	v_mul_f32_e32 v32, 0x3fb8aa3b, v164
	v_pk_mul_f32 v[42:43], v[36:37], v[40:41] op_sel_hi:[0,1]
	v_pk_mul_f32 v[46:47], v[36:37], v[44:45] op_sel_hi:[0,1]
	v_pk_mul_f32 v[50:51], v[38:39], v[52:53] op_sel_hi:[0,1]
	v_pk_mul_f32 v[52:53], v[36:37], v[52:53] op_sel_hi:[0,1]
	v_pk_mul_f32 v[54:55], v[38:39], v[8:9] op_sel_hi:[0,1]
	v_pk_mul_f32 v[8:9], v[36:37], v[26:27] op_sel_hi:[0,1]
	v_pk_mul_f32 v[26:27], v[38:39], v[26:27] op_sel_hi:[0,1]
	v_pk_mul_f32 v[18:19], v[38:39], v[10:11] op_sel_hi:[0,1]
	v_pk_mul_f32 v[36:37], v[36:37], v[56:57] op_sel_hi:[0,1]
	v_cvt_pk_bf16_f32 v11, v34, v35
	v_exp_f32_e32 v146, v32
	s_waitcnt vmcnt(14)
	v_lshlrev_b32_e32 v34, 16, v28
	v_and_b32_e32 v35, 0xffff0000, v28
	v_cvt_pk_bf16_f32 v91, v8, v9
	v_cvt_pk_bf16_f32 v9, v18, v19
	v_cvt_pk_bf16_f32 v19, v26, v27
	v_cvt_pk_bf16_f32 v27, v36, v37
	v_lshlrev_b32_e32 v32, 16, v30
	v_and_b32_e32 v33, 0xffff0000, v30
	s_waitcnt vmcnt(13)
	v_pk_mul_f32 v[36:37], v[76:77], v[34:35]
	v_lshlrev_b32_e32 v28, 16, v29
	v_and_b32_e32 v29, 0xffff0000, v29
	s_waitcnt vmcnt(12)
	v_pk_fma_f32 v[148:149], v[80:81], v[32:33], v[36:37]
	v_lshlrev_b32_e32 v30, 16, v31
	v_and_b32_e32 v31, 0xffff0000, v31
	v_pk_mul_f32 v[36:37], v[78:79], v[28:29]
	v_pk_mul_f32 v[28:29], v[82:83], v[28:29]
	v_pk_mul_f32 v[34:35], v[80:81], v[34:35]
	v_pk_fma_f32 v[154:155], v[78:79], v[30:31], v[28:29] neg_lo:[0,0,1] neg_hi:[0,0,1]
	v_pk_fma_f32 v[152:153], v[82:83], v[30:31], v[36:37]
	v_pk_mul_f32 v[28:29], v[146:147], v[154:155] op_sel_hi:[0,1]
	v_cvt_pk_bf16_f32 v85, v28, v29
	v_add_u32_e32 v28, 33, v156
	v_cvt_f32_ubyte0_e32 v28, v28
	v_mul_f32_e32 v163, v39, v28
	v_pk_fma_f32 v[150:151], v[76:77], v[32:33], v[34:35] neg_lo:[0,0,1] neg_hi:[0,0,1]
	v_pk_mul_f32 v[30:31], v[146:147], v[152:153] op_sel_hi:[0,1]
	v_mul_f32_e32 v28, 0x3fb8aa3b, v163
	v_pk_mul_f32 v[32:33], v[146:147], v[150:151] op_sel_hi:[0,1]
	v_cvt_pk_bf16_f32 v87, v30, v31
	v_exp_f32_e32 v132, v28
	s_waitcnt vmcnt(8)
	v_lshlrev_b32_e32 v30, 16, v20
	v_and_b32_e32 v31, 0xffff0000, v20
	v_cvt_pk_bf16_f32 v84, v32, v33
	v_lshlrev_b32_e32 v28, 16, v22
	v_and_b32_e32 v29, 0xffff0000, v22
	s_waitcnt vmcnt(7)
	v_pk_mul_f32 v[32:33], v[64:65], v[30:31]
	v_lshlrev_b32_e32 v20, 16, v21
	v_and_b32_e32 v21, 0xffff0000, v21
	s_waitcnt vmcnt(6)
	v_pk_fma_f32 v[134:135], v[68:69], v[28:29], v[32:33]
	v_lshlrev_b32_e32 v22, 16, v23
	v_and_b32_e32 v23, 0xffff0000, v23
	v_pk_mul_f32 v[32:33], v[66:67], v[20:21]
	v_pk_mul_f32 v[20:21], v[70:71], v[20:21]
	v_cvt_pk_bf16_f32 v8, v16, v17
	v_pk_fma_f32 v[140:141], v[66:67], v[22:23], v[20:21] neg_lo:[0,0,1] neg_hi:[0,0,1]
	v_cvt_pk_bf16_f32 v10, v50, v51
	v_pk_mul_f32 v[20:21], v[132:133], v[140:141] op_sel_hi:[0,1]
	v_cvt_pk_bf16_f32 v73, v20, v21
	v_add_u32_e32 v20, 49, v156
	v_cvt_pk_bf16_f32 v24, v48, v49
	v_cvt_pk_bf16_f32 v26, v52, v53
	v_cvt_f32_ubyte0_e32 v20, v20
	v_pk_mul_f32 v[30:31], v[68:69], v[30:31]
	v_pk_fma_f32 v[138:139], v[70:71], v[22:23], v[32:33]
	v_mul_f32_e32 v162, v39, v20
	v_pk_fma_f32 v[136:137], v[64:65], v[28:29], v[30:31] neg_lo:[0,0,1] neg_hi:[0,0,1]
	v_pk_mul_f32 v[22:23], v[132:133], v[138:139] op_sel_hi:[0,1]
	v_mul_f32_e32 v20, 0x3fb8aa3b, v162
	v_pk_mul_f32 v[40:41], v[38:39], v[40:41] op_sel_hi:[0,1]
	v_pk_mul_f32 v[44:45], v[38:39], v[44:45] op_sel_hi:[0,1]
	v_pk_mul_f32 v[34:35], v[146:147], v[148:149] op_sel_hi:[0,1]
	v_pk_mul_f32 v[28:29], v[132:133], v[136:137] op_sel_hi:[0,1]
	v_cvt_pk_bf16_f32 v75, v22, v23
	v_exp_f32_e32 v118, v20
	s_waitcnt vmcnt(2)
; __device__ __forceinline__ unsigned cvtpk(float lo, float hi) { f32x2_t v = {lo, hi}; bf16x2_t b = __builtin_convertvector(v, bf16x2_t); return __builtin_bit_cast(unsigned, b); }
; template <int X> __device__ __forceinline__ float swz_xor(float v) { return __int_as_float(__builtin_amdgcn_ds_swizzle(__float_as_int(v), (X << 10) | 0x1F)); }
; template <bool GLA>
; __device__ __forceinline__ void chunk_pass_c(const ChunkIn& ci, const float* wgl, int unit, unsigned char* wl, int lane, const float* Sb, const float* ng, bf16_t* omix) {
;     ...
;         for (int jt = 0; jt < 4; ++jt) {
;             const f32x4 z = {0.f, 0.f, 0.f, 0.f};
;             if (jt < it) st[jt] = __builtin_amdgcn_mfma_f32_16x16x32_bf16(kf[jt], qf[it], z, 0, 0, 0);
;             else if (jt > it) st[jt] = __builtin_amdgcn_mfma_f32_16x16x32_bf16(kb[jt], qb[it], z, 0, 0, 0);
;             else {
;                 const f32x4 lo = __builtin_amdgcn_mfma_f32_16x16x32_bf16(kf[jt], qf[it], z, 0, 0, 0), up = __builtin_amdgcn_mfma_f32_16x16x32_bf16(kb[jt], qb[it], z, 0, 0, 0);
; #pragma unroll
;                 for (int r = 0; r < 4; ++r) st[jt][r] = (4 * kq + r <= row) ? lo[r] : up[r];
;             }
;         }
;         bf16x8 af[2];
; #pragma unroll
;         for (int p = 0; p < 2; ++p)
;             af[p] = __builtin_bit_cast(bf16x8, (u32x4){cvtpk(st[2 * p][0], st[2 * p][1]), cvtpk(st[2 * p][2], st[2 * p][3]), cvtpk(st[2 * p + 1][0], st[2 * p + 1][1]), cvtpk(st[2 * p + 1][2], st[2 * p + 1][3])});
;     ...
;         for (int r = 0; r < 4; ++r) {
;             ss[r] += swz_xor<1>(ss[r]); ss[r] += swz_xor<2>(ss[r]); ss[r] += swz_xor<4>(ss[r]); ss[r] += swz_xor<8>(ss[r]);
;             const float rs = rsqrtf(ss[r] * (1.0f / 64.0f) + EPS);
;             const int t = t0 + 16 * it + 4 * kq + r;
; #pragma unroll
;             for (int et = 0; et < 4; ++et) {
;                 const int e = 16 * et + row;
;                 const float gt = __uint_as_float((unsigned)ci.proj[(size_t)t * DINP + gcol + e] << 16);
	v_lshlrev_b32_e32 v22, 16, v12
	v_and_b32_e32 v23, 0xffff0000, v12
	v_cvt_pk_bf16_f32 v88, v42, v43
	v_cvt_pk_bf16_f32 v90, v46, v47
	v_cvt_pk_bf16_f32 v16, v40, v41
	v_cvt_pk_bf16_f32 v17, v54, v55
	v_cvt_pk_bf16_f32 v18, v44, v45
	v_cvt_pk_bf16_f32 v86, v34, v35
	v_cvt_pk_bf16_f32 v72, v28, v29
	v_lshlrev_b32_e32 v20, 16, v14
	v_and_b32_e32 v21, 0xffff0000, v14
	s_waitcnt vmcnt(1)
	v_pk_mul_f32 v[28:29], v[0:1], v[22:23]
	v_lshlrev_b32_e32 v12, 16, v13
	v_and_b32_e32 v13, 0xffff0000, v13
	s_waitcnt vmcnt(0)
	v_pk_fma_f32 v[120:121], v[4:5], v[20:21], v[28:29]
	v_pk_mul_f32 v[22:23], v[4:5], v[22:23]
	v_lshlrev_b32_e32 v14, 16, v15
	v_and_b32_e32 v15, 0xffff0000, v15
	v_pk_mul_f32 v[28:29], v[2:3], v[12:13]
	v_pk_mul_f32 v[12:13], v[6:7], v[12:13]
	v_mfma_f32_16x16x32_bf16 v[32:35], v[8:11], v[88:91], 0
	v_fma_f32 v122, v0, v20, -v22
	v_fma_f32 v123, v1, v21, -v23
	v_pk_fma_f32 v[124:125], v[6:7], v[14:15], v[28:29]
	v_pk_fma_f32 v[126:127], v[2:3], v[14:15], v[12:13] neg_lo:[0,0,1] neg_hi:[0,0,1]
	v_mfma_f32_16x16x32_bf16 v[24:27], v[24:27], v[16:19], 0
	v_mul_f32_e64 v30, v132, v134
	v_mul_f32_e64 v31, v132, v135
	v_pk_mul_f32 v[20:21], v[118:119], v[122:123] op_sel_hi:[0,1]
	v_pk_mul_f32 v[22:23], v[118:119], v[120:121] op_sel_hi:[0,1]
	v_pk_mul_f32 v[14:15], v[118:119], v[126:127] op_sel_hi:[0,1]
	v_pk_mul_f32 v[28:29], v[118:119], v[124:125] op_sel_hi:[0,1]
	v_cvt_pk_bf16_f32 v74, v30, v31
	v_cvt_pk_bf16_f32 v12, v20, v21
	v_cvt_pk_bf16_f32 v13, v14, v15
	v_cvt_pk_bf16_f32 v14, v22, v23
	v_cvt_pk_bf16_f32 v15, v28, v29
	v_cmp_gt_u32_e32 vcc, v97, v156
	v_mfma_f32_16x16x32_bf16 v[36:39], v[84:87], v[16:19], 0
	v_mul_u32_u24_e32 v20, 0x90, v156
	v_cndmask_b32_e32 v24, v32, v24, vcc
	v_or_b32_e32 v32, 2, v97
	v_cmp_gt_u32_e64 s[44:45], v32, v156
	v_or_b32_e32 v32, 3, v97
	v_cmp_gt_u32_e64 s[46:47], v32, v156
	v_readlane_b32 s7, v254, 60
	v_cndmask_b32_e64 v25, v25, v33, s[42:43]
	v_cndmask_b32_e64 v26, v34, v26, s[44:45]
	v_cndmask_b32_e64 v27, v35, v27, s[46:47]
	s_waitcnt vmcnt(0) expcnt(0) lgkmcnt(0)
	v_mov_b32_e32 v213, v211
	v_lshlrev_b32_e32 v212, 12, v165
	v_lshl_add_u64 v[214:215], s[58:59], 0, v[212:213]
	v_lshl_add_u64 v[216:217], v[214:215], 0, v[110:111]
	global_load_ushort v178, v[216:217], off offset:3424
	global_load_ushort v179, v[216:217], off offset:3456
	global_load_ushort v180, v[216:217], off offset:3488
	v_mov_b32_e32 v213, v211
	v_lshlrev_b32_e32 v212, 12, v165
	v_lshl_add_u64 v[214:215], s[58:59], 0, v[212:213]
	v_lshlrev_b32_e32 v216, 1, v177
	v_mov_b32_e32 v217, v211
	v_lshl_add_u64 v[218:219], v[214:215], 0, v[216:217]
	global_load_ushort v181, v[218:219], off offset:3424
	v_or_b32_e32 v212, 1, v165
	v_lshlrev_b32_e32 v214, 12, v212
	v_mov_b32_e32 v215, v211
	v_lshl_add_u64 v[214:215], s[58:59], 0, v[214:215]
	v_lshl_add_u64 v[216:217], v[214:215], 0, v[110:111]
	global_load_ushort v182, v[216:217], off offset:3424
	global_load_ushort v183, v[216:217], off offset:3456
	global_load_ushort v184, v[216:217], off offset:3488
	v_lshlrev_b32_e32 v212, 1, v177
	v_mov_b32_e32 v213, v211
	v_or_b32_e32 v214, 1, v165
	v_lshlrev_b32_e32 v216, 12, v214
	v_mov_b32_e32 v217, v211
	v_lshl_add_u64 v[216:217], s[58:59], 0, v[216:217]
	v_lshl_add_u64 v[218:219], v[216:217], 0, v[212:213]
	global_load_ushort v185, v[218:219], off offset:3424
	v_or_b32_e32 v212, 2, v165
	v_mov_b32_e32 v215, v211
	v_lshlrev_b32_e32 v214, 12, v212
	v_lshl_add_u64 v[214:215], s[58:59], 0, v[214:215]
	v_lshl_add_u64 v[216:217], v[214:215], 0, v[110:111]
	global_load_ushort v186, v[216:217], off offset:3424
	global_load_ushort v187, v[216:217], off offset:3456
	global_load_ushort v188, v[216:217], off offset:3488
	v_lshlrev_b32_e32 v212, 1, v177
	v_mov_b32_e32 v213, v211
	v_or_b32_e32 v214, 2, v165
	v_mov_b32_e32 v217, v211
	v_lshlrev_b32_e32 v216, 12, v214
	v_lshl_add_u64 v[216:217], s[58:59], 0, v[216:217]
	v_lshl_add_u64 v[216:217], v[216:217], 0, v[212:213]
	global_load_ushort v189, v[216:217], off offset:3424
	v_or_b32_e32 v212, 3, v165
	v_mov_b32_e32 v215, v211
	v_lshlrev_b32_e32 v214, 12, v212
	v_lshl_add_u64 v[216:217], s[58:59], 0, v[214:215]
	v_lshl_add_u64 v[218:219], v[216:217], 0, v[110:111]
	global_load_ushort v190, v[218:219], off offset:3424
	global_load_ushort v191, v[218:219], off offset:3456
	global_load_ushort v192, v[218:219], off offset:3488
	v_lshlrev_b32_e32 v212, 1, v177
	v_mov_b32_e32 v213, v211
	v_or_b32_e32 v214, 3, v165
	v_mov_b32_e32 v217, v211
	v_lshlrev_b32_e32 v216, 12, v214
	v_lshl_add_u64 v[218:219], s[58:59], 0, v[216:217]
	v_lshl_add_u64 v[220:221], v[218:219], 0, v[212:213]
	global_load_ushort v193, v[220:221], off offset:3424
	v_mov_b32_e32 v213, v211
	v_or_b32_e32 v214, s5, v97
	v_lshlrev_b32_e32 v212, 12, v214
	v_lshl_add_u64 v[212:213], s[58:59], 0, v[212:213]
	v_lshl_add_u64 v[216:217], v[212:213], 0, v[110:111]
	global_load_ushort v194, v[216:217], off offset:3424
	global_load_ushort v195, v[216:217], off offset:3456
	global_load_ushort v196, v[216:217], off offset:3488
	v_lshlrev_b32_e32 v212, 1, v177
	v_mov_b32_e32 v213, v211
	v_mov_b32_e32 v215, v211
	v_or_b32_e32 v216, s5, v97
	v_lshlrev_b32_e32 v214, 12, v216
	v_lshl_add_u64 v[214:215], s[58:59], 0, v[214:215]
	v_lshl_add_u64 v[214:215], v[214:215], 0, v[212:213]
	global_load_ushort v197, v[214:215], off offset:3424
	v_or_b32_e32 v212, s5, v97
	v_or_b32_e32 v214, 1, v212
	v_mov_b32_e32 v217, v211
	v_lshlrev_b32_e32 v216, 12, v214
	v_lshl_add_u64 v[216:217], s[58:59], 0, v[216:217]
	v_lshl_add_u64 v[218:219], v[216:217], 0, v[110:111]
	global_load_ushort v198, v[218:219], off offset:3424
	global_load_ushort v199, v[218:219], off offset:3456
; template <bool GLA>
; __device__ __forceinline__ void chunk_pass_c(const ChunkIn& ci, const float* wgl, int unit, unsigned char* wl, int lane, const float* Sb, const float* ng, bf16_t* omix) {
;     ...
;     bf16x8 vfr[4][2], sfr[4];
; #pragma unroll
;     for (int et = 0; et < 4; ++et) {
; #pragma unroll
;         for (int p = 0; p < 2; ++p) {
;             const u32x2 lo = *(const u32x2*)(wl + (16 * et + row) * GP + (32 * p + 4 * kq) * 2), hh = *(const u32x2*)(wl + (16 * et + row) * GP + (32 * p + 16 + 4 * kq) * 2);
;             vfr[et][p] = __builtin_bit_cast(bf16x8, (u32x4){lo.x, lo.y, hh.x, hh.y});
;         }
;         sfr[et] = *(const bf16x8*)(sst + (16 * et + row) * 64 + kq * 16);
;     }
;     const int gcol = (GLA ? C_GR : C_RG) + h * 64, ocol = (GLA ? 512 : 768) + h * 64;
;     float gn[4];
; #pragma unroll
;     for (int et = 0; et < 4; ++et) gn[et] = ng[16 * et + row];
; #pragma unroll
;     for (int it = 0; it < 4; ++it) {
;         f32x4 st[4];
; #pragma unroll
;         for (int jt = 0; jt < 4; ++jt) {
;             const f32x4 z = {0.f, 0.f, 0.f, 0.f};
;             if (jt < it) st[jt] = __builtin_amdgcn_mfma_f32_16x16x32_bf16(kf[jt], qf[it], z, 0, 0, 0);
;             else if (jt > it) st[jt] = __builtin_amdgcn_mfma_f32_16x16x32_bf16(kb[jt], qb[it], z, 0, 0, 0);
;             else {
;                 const f32x4 lo = __builtin_amdgcn_mfma_f32_16x16x32_bf16(kf[jt], qf[it], z, 0, 0, 0), up = __builtin_amdgcn_mfma_f32_16x16x32_bf16(kb[jt], qb[it], z, 0, 0, 0);
; #pragma unroll
;                 for (int r = 0; r < 4; ++r) st[jt][r] = (4 * kq + r <= row) ? lo[r] : up[r];
;             }
;         }
;         bf16x8 af[2];
; #pragma unroll
;         for (int p = 0; p < 2; ++p)
;             af[p] = __builtin_bit_cast(bf16x8, (u32x4){cvtpk(st[2 * p][0], st[2 * p][1]), cvtpk(st[2 * p][2], st[2 * p][3]), cvtpk(st[2 * p + 1][0], st[2 * p + 1][1]), cvtpk(st[2 * p + 1][2], st[2 * p + 1][3])});
;         f32x4 o[4]; float ss[4] = {0.f, 0.f, 0.f, 0.f};
; #pragma unroll
;         for (int et = 0; et < 4; ++et) {
;             f32x4 acc = {0.f, 0.f, 0.f, 0.f};
;             acc = __builtin_amdgcn_mfma_f32_16x16x32_bf16(af[0], vfr[et][0], acc, 0, 0, 0);
;             acc = __builtin_amdgcn_mfma_f32_16x16x32_bf16(af[1], vfr[et][1], acc, 0, 0, 0);
;             acc = __builtin_amdgcn_mfma_f32_16x16x32_bf16(qf[it], sfr[et], acc, 0, 0, 0);
	global_load_ushort v200, v[218:219], off offset:3488
	v_lshlrev_b32_e32 v212, 1, v177
	v_mov_b32_e32 v213, v211
	v_or_b32_e32 v214, s5, v97
	v_or_b32_e32 v216, 1, v214
	v_mov_b32_e32 v219, v211
	v_lshlrev_b32_e32 v218, 12, v216
	v_lshl_add_u64 v[218:219], s[58:59], 0, v[218:219]
	v_lshl_add_u64 v[218:219], v[218:219], 0, v[212:213]
	global_load_ushort v201, v[218:219], off offset:3424
	v_or_b32_e32 v212, s5, v97
	v_or_b32_e32 v214, 2, v212
	v_mov_b32_e32 v217, v211
	v_lshlrev_b32_e32 v216, 12, v214
	v_lshl_add_u64 v[216:217], s[58:59], 0, v[216:217]
	v_lshl_add_u64 v[218:219], v[216:217], 0, v[110:111]
	global_load_ushort v202, v[218:219], off offset:3424
	global_load_ushort v203, v[218:219], off offset:3456
	global_load_ushort v204, v[218:219], off offset:3488
	v_lshlrev_b32_e32 v212, 1, v177
	v_mov_b32_e32 v213, v211
	v_or_b32_e32 v214, s5, v97
	v_or_b32_e32 v216, 2, v214
	v_mov_b32_e32 v219, v211
	v_lshlrev_b32_e32 v218, 12, v216
	v_lshl_add_u64 v[218:219], s[58:59], 0, v[218:219]
	v_lshl_add_u64 v[218:219], v[218:219], 0, v[212:213]
	global_load_ushort v205, v[218:219], off offset:3424
	v_or_b32_e32 v212, s5, v97
	v_or_b32_e32 v214, 3, v212
	v_mov_b32_e32 v217, v211
	v_lshlrev_b32_e32 v216, 12, v214
	v_lshl_add_u64 v[216:217], s[58:59], 0, v[216:217]
	v_lshl_add_u64 v[218:219], v[216:217], 0, v[110:111]
	global_load_ushort v206, v[218:219], off offset:3424
	global_load_ushort v207, v[218:219], off offset:3456
	global_load_ushort v208, v[218:219], off offset:3488
	v_lshlrev_b32_e32 v212, 1, v177
	v_mov_b32_e32 v213, v211
	v_or_b32_e32 v214, s5, v97
	v_or_b32_e32 v216, 3, v214
	v_mov_b32_e32 v219, v211
	v_lshlrev_b32_e32 v218, 12, v216
	v_lshl_add_u64 v[218:219], s[58:59], 0, v[218:219]
	v_lshl_add_u64 v[220:221], v[218:219], 0, v[212:213]
	global_load_ushort v209, v[220:221], off offset:3424
	v_add3_u32 v48, s7, v20, v114
	v_mfma_f32_16x16x32_bf16 v[40:43], v[72:75], v[16:19], 0
	v_cvt_pk_bf16_f32 v166, v24, v25
	v_cvt_pk_bf16_f32 v167, v26, v27
	v_cvt_pk_bf16_f32 v168, v36, v37
	v_mfma_f32_16x16x32_bf16 v[16:19], v[12:15], v[16:19], 0
	v_cvt_pk_bf16_f32 v169, v38, v39
	ds_read2_b64 v[28:31], v48 offset1:4
	ds_read2_b64 v[20:23], v48 offset0:8 offset1:12
	s_nop 0
	v_cvt_pk_bf16_f32 v170, v40, v41
	v_cvt_pk_bf16_f32 v171, v42, v43
	s_nop 1
	v_cvt_pk_bf16_f32 v172, v16, v17
	v_cvt_pk_bf16_f32 v173, v18, v19
	s_waitcnt lgkmcnt(1)
	v_mfma_f32_16x16x32_bf16 v[16:19], v[166:169], v[28:31], 0
	v_lshlrev_b32_e32 v24, 6, v156
	v_and_b32_e32 v25, 48, v133
	v_add3_u32 v60, s7, v25, v24
	ds_read_b128 v[24:27], v60 offset:9216
	s_waitcnt lgkmcnt(1)
	v_mfma_f32_16x16x32_bf16 v[32:35], v[170:173], v[20:23], v[16:19]
	v_add_u32_e32 v40, 0x800, v48
	ds_read2_b64 v[44:47], v40 offset0:32 offset1:36
	v_mov_b32_e32 v41, v211
	ds_read_b128 v[16:19], v60 offset:10240
	s_waitcnt lgkmcnt(2)
	v_mfma_f32_16x16x32_bf16 v[92:95], v[88:91], v[24:27], v[32:35]
	s_nop 2
	ds_read2_b64 v[32:35], v40 offset0:40 offset1:44
	v_lshlrev_b32_e32 v40, 12, v165
	v_lshl_add_u64 v[174:175], s[58:59], 0, v[40:41]
	v_lshl_add_u64 v[112:113], v[174:175], 0, v[110:111]
	s_waitcnt lgkmcnt(2)
	v_mfma_f32_16x16x32_bf16 v[36:39], v[166:169], v[44:47], 0
	v_add_u32_e32 v40, 0x1000, v48
	v_mov_b32_e32 v160, v93
	s_waitcnt lgkmcnt(0)
	v_mfma_f32_16x16x32_bf16 v[36:39], v[170:173], v[32:35], v[36:39]
	v_mfma_f32_16x16x32_bf16 v[102:105], v[88:91], v[16:19], v[36:39]
	ds_read2_b64 v[56:59], v40 offset0:64 offset1:68
	ds_read2_b64 v[52:55], v40 offset0:72 offset1:76
	s_nop 4
	ds_read_b128 v[36:39], v60 offset:11264
	global_load_dword v115, v159, s[48:49]
	v_mov_b32_e32 v117, v102
	s_waitcnt lgkmcnt(2)
	v_mfma_f32_16x16x32_bf16 v[40:43], v[166:169], v[56:59], 0
	v_mov_b32_e32 v161, v103
	v_pk_mul_f32 v[160:161], v[160:161], v[160:161]
	s_waitcnt lgkmcnt(1)
	v_mfma_f32_16x16x32_bf16 v[48:51], v[170:173], v[52:55], v[40:43]
	s_waitcnt lgkmcnt(0)
	v_mfma_f32_16x16x32_bf16 v[98:101], v[88:91], v[36:39], v[48:51]
	s_nop 1
	v_mul_u32_u24_e32 v40, 0x90, v177
	v_add3_u32 v116, s7, v40, v114
	ds_read_b128 v[40:43], v60 offset:12288
	ds_read2_b64 v[60:63], v116 offset1:4
	ds_read2_b64 v[48:51], v116 offset0:8 offset1:12
	s_waitcnt lgkmcnt(1)
	v_mfma_f32_16x16x32_bf16 v[166:169], v[166:169], v[60:63], 0
	v_mov_b32_e32 v116, v92
	v_pk_mul_f32 v[116:117], v[116:117], v[116:117]
	s_waitcnt lgkmcnt(0)
	v_mfma_f32_16x16x32_bf16 v[166:169], v[170:173], v[48:51], v[166:169]
	v_mov_b32_e32 v170, v160
	v_mov_b32_e32 v171, v116
	v_mov_b32_e32 v116, v161
	v_mfma_f32_16x16x32_bf16 v[88:91], v[88:91], v[40:43], v[166:169]
	v_add_f32_e64 v116, v170, v116
	v_add_f32_e64 v117, v171, v117
	s_waitcnt vmcnt(1)
	v_mov_b32_e32 v176, v178
	v_mov_b32_e32 v213, v211
	v_or_b32_e32 v214, s4, v97
	v_lshlrev_b32_e32 v212, 12, v214
	v_lshl_add_u64 v[212:213], s[58:59], 0, v[212:213]
	v_lshl_add_u64 v[216:217], v[212:213], 0, v[110:111]
	global_load_ushort v178, v[216:217], off offset:3424
	v_lshlrev_b32_e32 v170, 16, v176
	v_mov_b32_e32 v166, v98
	s_nop 2
	v_mov_b32_e32 v167, v88
	v_mov_b32_e32 v168, v99
	v_mov_b32_e32 v169, v89
	v_pk_mul_f32 v[166:167], v[166:167], v[166:167]
	v_pk_mul_f32 v[168:169], v[168:169], v[168:169]
	v_mov_b32_e32 v161, v166
	v_mov_b32_e32 v160, v168
	v_pk_add_f32 v[116:117], v[116:117], v[160:161]
	v_mov_b32_e32 v166, v169
	v_pk_add_f32 v[116:117], v[116:117], v[166:167]
	ds_swizzle_b32 v161, v117 offset:swizzle(SWAP,1)
	ds_swizzle_b32 v160, v116 offset:swizzle(SWAP,1)
	v_lshlrev_b32_e32 v168, 2, v177
	v_mov_b32_e32 v169, v211
	s_waitcnt lgkmcnt(0)
	v_pk_add_f32 v[116:117], v[116:117], v[160:161]
	ds_swizzle_b32 v161, v117 offset:swizzle(SWAP,2)
	ds_swizzle_b32 v160, v116 offset:swizzle(SWAP,2)
	s_waitcnt lgkmcnt(0)
; __device__ __forceinline__ unsigned cvtpk(float lo, float hi) { f32x2_t v = {lo, hi}; bf16x2_t b = __builtin_convertvector(v, bf16x2_t); return __builtin_bit_cast(unsigned, b); }
; template <int X> __device__ __forceinline__ float swz_xor(float v) { return __int_as_float(__builtin_amdgcn_ds_swizzle(__float_as_int(v), (X << 10) | 0x1F)); }
; __device__ __forceinline__ float silu_f(float g) { return g * __builtin_amdgcn_rcpf(1.0f + __expf(-g)); }
; template <bool GLA>
; __device__ __forceinline__ void chunk_pass_c(const ChunkIn& ci, const float* wgl, int unit, unsigned char* wl, int lane, const float* Sb, const float* ng, bf16_t* omix) {
;     ...
;         for (int r = 0; r < 4; ++r) {
;             ss[r] += swz_xor<1>(ss[r]); ss[r] += swz_xor<2>(ss[r]); ss[r] += swz_xor<4>(ss[r]); ss[r] += swz_xor<8>(ss[r]);
;             const float rs = rsqrtf(ss[r] * (1.0f / 64.0f) + EPS);
;             const int t = t0 + 16 * it + 4 * kq + r;
; #pragma unroll
;             for (int et = 0; et < 4; ++et) {
;                 const int e = 16 * et + row;
;                 const float gt = __uint_as_float((unsigned)ci.proj[(size_t)t * DINP + gcol + e] << 16);
;                 const float val = o[et][r] * rs * gn[et] * pg8::silu_f(gt);
;                 omix[(size_t)t * 1024 + ocol + e] = (bf16_t)(cvtpk(val, 0.f) & 0xffffu);
;             }
;         }
	v_pk_add_f32 v[116:117], v[116:117], v[160:161]
	ds_swizzle_b32 v167, v117 offset:swizzle(SWAP,4)
	ds_swizzle_b32 v166, v116 offset:swizzle(SWAP,4)
	global_load_dword v161, v159, s[48:49] offset:64
	global_load_dword v160, v159, s[48:49] offset:128
	s_nop 0
	global_load_dword v159, v168, s[48:49]
	v_mul_f32_e32 v168, 0xbfb8aa3b, v170
	v_exp_f32_e32 v171, v168
	v_lshlrev_b32_e32 v168, 11, v165
	s_waitcnt lgkmcnt(0)
	v_pk_add_f32 v[116:117], v[116:117], v[166:167]
	ds_swizzle_b32 v167, v117 offset:swizzle(SWAP,8)
	ds_swizzle_b32 v166, v116 offset:swizzle(SWAP,8)
	v_add_f32_e32 v171, 1.0, v171
	v_rcp_f32_e32 v171, v171
	v_lshl_add_u64 v[168:169], s[60:61], 0, v[168:169]
	s_waitcnt lgkmcnt(0)
	v_pk_add_f32 v[166:167], v[116:117], v[166:167]
	v_mov_b64_e32 v[116:117], s[6:7]
	s_mov_b32 s6, 0x3c800000
	v_pk_fma_f32 v[166:167], v[166:167], s[6:7], v[116:117] op_sel_hi:[1,0,0]
	s_nop 0
	v_mul_f32_e32 v172, 0x4b800000, v167
	v_cmp_gt_f32_e64 s[48:49], s96, v167
	s_nop 1
	v_cndmask_b32_e64 v167, v167, v172, s[48:49]
	v_rsq_f32_e32 v167, v167
	v_mul_f32_e32 v172, v171, v170
	v_lshl_add_u64 v[170:171], v[168:169], 0, v[110:111]
	v_mul_f32_e32 v173, 0x45800000, v167
	v_cndmask_b32_e64 v167, v167, v173, s[48:49]
	v_mul_f32_e32 v92, v92, v167
	s_waitcnt vmcnt(3)
	v_mul_f32_e32 v92, v115, v92
	v_mul_f32_e32 v92, v172, v92
	v_cvt_pk_bf16_f32 v92, v92, s0
	global_store_short v[170:171], v92, off offset:1536
	v_mul_f32_e32 v102, v102, v167
	v_mul_f32_e32 v98, v98, v167
	v_mul_f32_e32 v88, v88, v167
	v_cmp_gt_f32_e64 s[48:49], s96, v166
	s_waitcnt vmcnt(3)
	v_mul_f32_e32 v102, v161, v102
	s_waitcnt vmcnt(2)
	v_mul_f32_e32 v98, v160, v98
	s_waitcnt vmcnt(1)
	v_mul_f32_e32 v88, v159, v88
	s_waitcnt vmcnt(0)
	v_mov_b32_e32 v92, v179
	global_load_ushort v179, v[216:217], off offset:3456
	v_lshlrev_b32_e32 v92, 16, v92
	v_mul_f32_e32 v172, 0xbfb8aa3b, v92
	v_exp_f32_e32 v172, v172
	s_nop 0
	v_add_f32_e32 v172, 1.0, v172
	v_rcp_f32_e32 v172, v172
	s_nop 0
	v_mul_f32_e32 v92, v172, v92
	v_mul_f32_e32 v92, v92, v102
	v_cvt_pk_bf16_f32 v92, v92, s0
	global_store_short v[170:171], v92, off offset:1568
	v_lshlrev_b32_e32 v112, 1, v177
	v_mov_b32_e32 v113, v211
	v_lshl_add_u64 v[172:173], v[174:175], 0, v[112:113]
	v_lshl_add_u64 v[168:169], v[168:169], 0, v[112:113]
	s_waitcnt vmcnt(37)
	v_mov_b32_e32 v92, v180
	global_load_ushort v180, v[216:217], off offset:3488
	v_lshlrev_b32_e32 v92, 16, v92
	v_mul_f32_e32 v102, 0xbfb8aa3b, v92
	v_exp_f32_e32 v102, v102
	s_nop 0
	v_add_f32_e32 v102, 1.0, v102
	v_rcp_f32_e32 v102, v102
	s_nop 0
	v_mul_f32_e32 v92, v102, v92
	v_mul_f32_e32 v92, v98, v92
	v_cvt_pk_bf16_f32 v92, v92, s0
	global_store_short v[170:171], v92, off offset:1600
	v_mov_b32_e32 v173, v211
	s_waitcnt vmcnt(38)
	v_mov_b32_e32 v92, v181
	v_lshlrev_b32_e32 v212, 1, v177
	v_mov_b32_e32 v213, v211
	v_mov_b32_e32 v215, v211
	v_or_b32_e32 v216, s4, v97
	v_lshlrev_b32_e32 v214, 12, v216
	v_lshl_add_u64 v[214:215], s[58:59], 0, v[214:215]
	v_lshl_add_u64 v[214:215], v[214:215], 0, v[212:213]
	global_load_ushort v181, v[214:215], off offset:3424
	v_lshlrev_b32_e32 v92, 16, v92
	v_mul_f32_e32 v98, 0xbfb8aa3b, v92
	v_exp_f32_e32 v98, v98
	s_nop 0
	v_add_f32_e32 v98, 1.0, v98
	v_rcp_f32_e32 v98, v98
	s_nop 0
	v_mul_f32_e32 v92, v98, v92
	v_mul_f32_e32 v88, v88, v92
	v_cvt_pk_bf16_f32 v88, v88, s0
	global_store_short v[168:169], v88, off offset:1536
	v_or_b32_e32 v88, 1, v165
	v_lshlrev_b32_e32 v168, 12, v88
	v_mov_b32_e32 v169, v211
	v_lshl_add_u64 v[168:169], s[58:59], 0, v[168:169]
	v_lshl_add_u64 v[170:171], v[168:169], 0, v[110:111]
	v_lshlrev_b32_e32 v172, 11, v88
	v_mul_f32_e32 v88, 0x4b800000, v166
	v_cndmask_b32_e64 v88, v166, v88, s[48:49]
	v_rsq_f32_e32 v88, v88
	v_lshl_add_u64 v[166:167], s[60:61], 0, v[172:173]
	v_lshl_add_u64 v[172:173], v[166:167], 0, v[110:111]
	v_mul_f32_e32 v102, 0x45800000, v88
	v_cndmask_b32_e64 v88, v88, v102, s[48:49]
	v_mul_f32_e32 v93, v93, v88
	v_mul_f32_e32 v93, v115, v93
	v_mul_f32_e32 v99, v99, v88
	v_mul_f32_e32 v99, v160, v99
	s_waitcnt vmcnt(39)
	v_mov_b32_e32 v92, v182
	v_or_b32_e32 v212, s4, v97
	v_or_b32_e32 v214, 1, v212
	v_mov_b32_e32 v217, v211
	v_lshlrev_b32_e32 v216, 12, v214
	v_lshl_add_u64 v[216:217], s[58:59], 0, v[216:217]
	v_lshl_add_u64 v[218:219], v[216:217], 0, v[110:111]
	global_load_ushort v182, v[218:219], off offset:3424
	v_lshlrev_b32_e32 v92, 16, v92
	v_mul_f32_e32 v98, 0xbfb8aa3b, v92
	v_exp_f32_e32 v98, v98
	s_nop 0
	v_add_f32_e32 v98, 1.0, v98
	v_rcp_f32_e32 v98, v98
	s_nop 0
	v_mul_f32_e32 v92, v98, v92
	v_mul_f32_e32 v92, v92, v93
	v_cvt_pk_bf16_f32 v92, v92, s0
	global_store_short v[172:173], v92, off offset:1536
	v_mul_f32_e32 v98, v103, v88
	v_mul_f32_e32 v98, v161, v98
	v_mul_f32_e32 v88, v89, v88
	v_mul_f32_e32 v88, v159, v88
	s_waitcnt vmcnt(40)
	v_mov_b32_e32 v92, v183
	global_load_ushort v183, v[218:219], off offset:3456
	v_lshlrev_b32_e32 v92, 16, v92
	v_mul_f32_e32 v93, 0xbfb8aa3b, v92
	v_exp_f32_e32 v93, v93
	s_nop 0
	v_add_f32_e32 v93, 1.0, v93
	v_rcp_f32_e32 v93, v93
	s_nop 0
	v_mul_f32_e32 v92, v93, v92
	v_mul_f32_e32 v92, v98, v92
	v_cvt_pk_bf16_f32 v92, v92, s0
	global_store_short v[172:173], v92, off offset:1568
	s_waitcnt vmcnt(41)
	v_mov_b32_e32 v92, v184
	global_load_ushort v184, v[218:219], off offset:3488
	v_lshlrev_b32_e32 v98, 16, v92
	v_mul_f32_e32 v92, 0xbfb8aa3b, v98
	v_exp_f32_e32 v92, v92
	s_nop 0
	v_add_f32_e32 v92, 1.0, v92
	v_rcp_f32_e32 v102, v92
	v_lshl_add_u64 v[92:93], v[168:169], 0, v[112:113]
	v_mov_b32_e32 v169, v91
	v_mul_f32_e32 v98, v102, v98
	v_mul_f32_e32 v98, v99, v98
	v_cvt_pk_bf16_f32 v98, v98, s0
	global_store_short v[172:173], v98, off offset:1600
	v_lshl_add_u64 v[98:99], v[166:167], 0, v[112:113]
	v_or_b32_e32 v172, 2, v165
	v_mov_b32_e32 v93, v211
	v_mov_b32_e32 v167, v90
	s_waitcnt vmcnt(42)
; __device__ __forceinline__ unsigned cvtpk(float lo, float hi) { f32x2_t v = {lo, hi}; bf16x2_t b = __builtin_convertvector(v, bf16x2_t); return __builtin_bit_cast(unsigned, b); }
; template <int X> __device__ __forceinline__ float swz_xor(float v) { return __int_as_float(__builtin_amdgcn_ds_swizzle(__float_as_int(v), (X << 10) | 0x1F)); }
; __device__ __forceinline__ float silu_f(float g) { return g * __builtin_amdgcn_rcpf(1.0f + __expf(-g)); }
; template <bool GLA>
; __device__ __forceinline__ void chunk_pass_c(const ChunkIn& ci, const float* wgl, int unit, unsigned char* wl, int lane, const float* Sb, const float* ng, bf16_t* omix) {
;     ...
;         f32x4 o[4]; float ss[4] = {0.f, 0.f, 0.f, 0.f};
; #pragma unroll
;         for (int et = 0; et < 4; ++et) {
;             f32x4 acc = {0.f, 0.f, 0.f, 0.f};
;             acc = __builtin_amdgcn_mfma_f32_16x16x32_bf16(af[0], vfr[et][0], acc, 0, 0, 0);
;             acc = __builtin_amdgcn_mfma_f32_16x16x32_bf16(af[1], vfr[et][1], acc, 0, 0, 0);
;             acc = __builtin_amdgcn_mfma_f32_16x16x32_bf16(qf[it], sfr[et], acc, 0, 0, 0);
;             o[et] = acc;
; #pragma unroll
;             for (int r = 0; r < 4; ++r) ss[r] += acc[r] * acc[r];
;         }
; #pragma unroll
;         for (int r = 0; r < 4; ++r) {
;             ss[r] += swz_xor<1>(ss[r]); ss[r] += swz_xor<2>(ss[r]); ss[r] += swz_xor<4>(ss[r]); ss[r] += swz_xor<8>(ss[r]);
;             const float rs = rsqrtf(ss[r] * (1.0f / 64.0f) + EPS);
;             const int t = t0 + 16 * it + 4 * kq + r;
; #pragma unroll
;             for (int et = 0; et < 4; ++et) {
;                 const int e = 16 * et + row;
;                 const float gt = __uint_as_float((unsigned)ci.proj[(size_t)t * DINP + gcol + e] << 16);
;                 const float val = o[et][r] * rs * gn[et] * pg8::silu_f(gt);
;                 omix[(size_t)t * 1024 + ocol + e] = (bf16_t)(cvtpk(val, 0.f) & 0xffffu);
;             }
;         }
	v_mov_b32_e32 v92, v185
	v_lshlrev_b32_e32 v212, 1, v177
	v_mov_b32_e32 v213, v211
	v_or_b32_e32 v214, s4, v97
	v_or_b32_e32 v216, 1, v214
	v_mov_b32_e32 v219, v211
	v_lshlrev_b32_e32 v218, 12, v216
	v_lshl_add_u64 v[218:219], s[58:59], 0, v[218:219]
	v_lshl_add_u64 v[218:219], v[218:219], 0, v[212:213]
	global_load_ushort v185, v[218:219], off offset:3424
	v_lshlrev_b32_e32 v168, 16, v92
	v_mul_f32_e32 v92, 0xbfb8aa3b, v168
	v_exp_f32_e32 v102, v92
	v_lshlrev_b32_e32 v92, 12, v172
	v_lshl_add_u64 v[92:93], s[58:59], 0, v[92:93]
	v_add_f32_e32 v102, 1.0, v102
	v_rcp_f32_e32 v166, v102
	v_lshl_add_u64 v[102:103], v[92:93], 0, v[110:111]
	v_lshl_add_u64 v[92:93], v[92:93], 0, v[112:113]
	v_mul_f32_e32 v89, v166, v168
	v_mul_f32_e32 v88, v88, v89
	v_cvt_pk_bf16_f32 v88, v88, s0
	global_store_short v[98:99], v88, off offset:1536
	v_mov_b32_e32 v88, v94
	v_mov_b32_e32 v89, v104
	v_mov_b32_e32 v98, v95
	v_mov_b32_e32 v99, v105
	v_mov_b32_e32 v166, v100
	v_mov_b32_e32 v168, v101
	v_pk_mul_f32 v[88:89], v[88:89], v[88:89]
	v_pk_mul_f32 v[98:99], v[98:99], v[98:99]
	v_pk_mul_f32 v[166:167], v[166:167], v[166:167]
	v_pk_mul_f32 v[168:169], v[168:169], v[168:169]
	v_mov_b32_e32 v170, v98
	v_mov_b32_e32 v171, v88
	v_mov_b32_e32 v88, v99
	v_mov_b32_e32 v98, v168
	v_mov_b32_e32 v99, v166
	v_pk_add_f32 v[88:89], v[170:171], v[88:89]
	v_mov_b32_e32 v166, v169
	v_pk_add_f32 v[88:89], v[88:89], v[98:99]
	s_waitcnt vmcnt(43)
	v_mov_b32_e32 v173, v186
	v_or_b32_e32 v212, s4, v97
	v_or_b32_e32 v214, 2, v212
	v_mov_b32_e32 v217, v211
	v_lshlrev_b32_e32 v216, 12, v214
	v_lshl_add_u64 v[216:217], s[58:59], 0, v[216:217]
	v_lshl_add_u64 v[218:219], v[216:217], 0, v[110:111]
	global_load_ushort v186, v[218:219], off offset:3424
	v_lshlrev_b32_e32 v168, 16, v173
	v_pk_add_f32 v[88:89], v[88:89], v[166:167]
	ds_swizzle_b32 v99, v89 offset:swizzle(SWAP,1)
	ds_swizzle_b32 v98, v88 offset:swizzle(SWAP,1)
	v_mov_b32_e32 v167, v211
	v_lshlrev_b32_e32 v166, 11, v172
	s_waitcnt lgkmcnt(0)
	v_pk_add_f32 v[88:89], v[88:89], v[98:99]
	ds_swizzle_b32 v99, v89 offset:swizzle(SWAP,2)
	ds_swizzle_b32 v98, v88 offset:swizzle(SWAP,2)
	s_waitcnt lgkmcnt(0)
	v_pk_add_f32 v[88:89], v[88:89], v[98:99]
	ds_swizzle_b32 v99, v89 offset:swizzle(SWAP,4)
	ds_swizzle_b32 v98, v88 offset:swizzle(SWAP,4)
	s_waitcnt lgkmcnt(0)
	v_pk_add_f32 v[88:89], v[88:89], v[98:99]
	ds_swizzle_b32 v99, v89 offset:swizzle(SWAP,8)
	ds_swizzle_b32 v98, v88 offset:swizzle(SWAP,8)
	s_waitcnt lgkmcnt(0)
	v_pk_add_f32 v[88:89], v[88:89], v[98:99]
	s_nop 0
	v_pk_fma_f32 v[88:89], v[88:89], s[6:7], v[116:117] op_sel_hi:[1,0,0]
	s_nop 0
	v_mul_f32_e32 v98, 0x4b800000, v89
	v_cmp_gt_f32_e64 s[48:49], s96, v89
	s_nop 1
	v_cndmask_b32_e64 v89, v89, v98, s[48:49]
	v_mul_f32_e32 v98, 0xbfb8aa3b, v168
	v_exp_f32_e32 v169, v98
	v_rsq_f32_e32 v89, v89
	v_lshl_add_u64 v[98:99], s[60:61], 0, v[166:167]
	v_lshl_add_u64 v[166:167], v[98:99], 0, v[110:111]
	v_add_f32_e32 v169, 1.0, v169
	v_rcp_f32_e32 v169, v169
	v_mul_f32_e32 v170, 0x45800000, v89
	v_cndmask_b32_e64 v89, v89, v170, s[48:49]
	v_mul_f32_e32 v94, v94, v89
	v_mul_f32_e32 v94, v115, v94
	v_mul_f32_e32 v168, v169, v168
	v_mul_f32_e32 v94, v168, v94
	v_cvt_pk_bf16_f32 v94, v94, s0
	global_store_short v[166:167], v94, off offset:1536
	v_mul_f32_e32 v104, v104, v89
	v_mul_f32_e32 v104, v161, v104
	v_mul_f32_e32 v100, v100, v89
	v_mul_f32_e32 v100, v160, v100
	v_mul_f32_e32 v89, v90, v89
	v_mul_f32_e32 v89, v159, v89
	v_cmp_gt_f32_e64 s[48:49], s96, v88
	s_waitcnt vmcnt(44)
	v_mov_b32_e32 v94, v187
	global_load_ushort v187, v[218:219], off offset:3456
	v_lshlrev_b32_e32 v94, 16, v94
	v_mul_f32_e32 v168, 0xbfb8aa3b, v94
	v_exp_f32_e32 v168, v168
	s_nop 0
	v_add_f32_e32 v168, 1.0, v168
	v_rcp_f32_e32 v168, v168
	s_nop 0
	v_mul_f32_e32 v94, v168, v94
	v_mul_f32_e32 v94, v104, v94
	v_cvt_pk_bf16_f32 v94, v94, s0
	global_store_short v[166:167], v94, off offset:1568
	v_and_b32_e32 v103, 0xffff0000, v142
	s_waitcnt vmcnt(45)
	v_mov_b32_e32 v94, v188
	global_load_ushort v188, v[218:219], off offset:3488
	v_lshlrev_b32_e32 v94, 16, v94
	v_mul_f32_e32 v102, 0xbfb8aa3b, v94
	v_exp_f32_e32 v102, v102
	s_nop 0
	v_add_f32_e32 v102, 1.0, v102
	v_rcp_f32_e32 v102, v102
	s_nop 0
	v_mul_f32_e32 v94, v102, v94
	v_mul_f32_e32 v94, v100, v94
	v_cvt_pk_bf16_f32 v94, v94, s0
	global_store_short v[166:167], v94, off offset:1600
	v_or_b32_e32 v94, 3, v165
	v_mov_b32_e32 v93, v211
	s_waitcnt vmcnt(46)
; template <bool GLA>
; __device__ __forceinline__ void chunk_pass_c(const ChunkIn& ci, const float* wgl, int unit, unsigned char* wl, int lane, const float* Sb, const float* ng, bf16_t* omix) {
;     ...
;     for (int it = 0; it < 4; ++it) {
;         f32x4 st[4];
; #pragma unroll
;         for (int jt = 0; jt < 4; ++jt) {
;             const f32x4 z = {0.f, 0.f, 0.f, 0.f};
;             if (jt < it) st[jt] = __builtin_amdgcn_mfma_f32_16x16x32_bf16(kf[jt], qf[it], z, 0, 0, 0);
;             else if (jt > it) st[jt] = __builtin_amdgcn_mfma_f32_16x16x32_bf16(kb[jt], qb[it], z, 0, 0, 0);
;             else {
;                 const f32x4 lo = __builtin_amdgcn_mfma_f32_16x16x32_bf16(kf[jt], qf[it], z, 0, 0, 0), up = __builtin_amdgcn_mfma_f32_16x16x32_bf16(kb[jt], qb[it], z, 0, 0, 0);
; #pragma unroll
;                 for (int r = 0; r < 4; ++r) st[jt][r] = (4 * kq + r <= row) ? lo[r] : up[r];
;             }
;         }
;         bf16x8 af[2];
; #pragma unroll
;         for (int p = 0; p < 2; ++p)
;             af[p] = __builtin_bit_cast(bf16x8, (u32x4){cvtpk(st[2 * p][0], st[2 * p][1]), cvtpk(st[2 * p][2], st[2 * p][3]), cvtpk(st[2 * p + 1][0], st[2 * p + 1][1]), cvtpk(st[2 * p + 1][2], st[2 * p + 1][3])});
;         f32x4 o[4]; float ss[4] = {0.f, 0.f, 0.f, 0.f};
; #pragma unroll
;         for (int et = 0; et < 4; ++et) {
;             f32x4 acc = {0.f, 0.f, 0.f, 0.f};
;             acc = __builtin_amdgcn_mfma_f32_16x16x32_bf16(af[0], vfr[et][0], acc, 0, 0, 0);
;             acc = __builtin_amdgcn_mfma_f32_16x16x32_bf16(af[1], vfr[et][1], acc, 0, 0, 0);
;             acc = __builtin_amdgcn_mfma_f32_16x16x32_bf16(qf[it], sfr[et], acc, 0, 0, 0);
;             o[et] = acc;
; #pragma unroll
;             for (int r = 0; r < 4; ++r) ss[r] += acc[r] * acc[r];
;         }
; #pragma unroll
;         for (int r = 0; r < 4; ++r) {
;             ss[r] += swz_xor<1>(ss[r]); ss[r] += swz_xor<2>(ss[r]); ss[r] += swz_xor<4>(ss[r]); ss[r] += swz_xor<8>(ss[r]);
;             const float rs = rsqrtf(ss[r] * (1.0f / 64.0f) + EPS);
;             const int t = t0 + 16 * it + 4 * kq + r;
; #pragma unroll
;             for (int et = 0; et < 4; ++et) {
;                 const int e = 16 * et + row;
;                 const float gt = __uint_as_float((unsigned)ci.proj[(size_t)t * DINP + gcol + e] << 16);
;                 const float val = o[et][r] * rs * gn[et] * pg8::silu_f(gt);
	v_mov_b32_e32 v92, v189
	v_lshlrev_b32_e32 v212, 1, v177
	v_mov_b32_e32 v213, v211
	v_or_b32_e32 v214, s4, v97
	v_or_b32_e32 v216, 2, v214
	v_mov_b32_e32 v219, v211
	v_lshlrev_b32_e32 v218, 12, v216
	v_lshl_add_u64 v[218:219], s[58:59], 0, v[218:219]
	v_lshl_add_u64 v[218:219], v[218:219], 0, v[212:213]
	global_load_ushort v189, v[218:219], off offset:3424
	v_lshlrev_b32_e32 v100, 16, v92
	v_mul_f32_e32 v92, 0xbfb8aa3b, v100
	v_exp_f32_e32 v102, v92
	v_lshlrev_b32_e32 v92, 12, v94
	v_lshl_add_u64 v[168:169], s[58:59], 0, v[92:93]
	v_lshl_add_u64 v[92:93], v[98:99], 0, v[112:113]
	v_add_f32_e32 v98, 1.0, v102
	v_rcp_f32_e32 v102, v98
	v_lshl_add_u64 v[98:99], v[168:169], 0, v[110:111]
	v_mul_f32_e32 v90, v102, v100
	v_mul_f32_e32 v89, v89, v90
	v_cvt_pk_bf16_f32 v89, v89, s0
	global_store_short v[92:93], v89, off offset:1536
	v_mul_f32_e32 v90, 0xbfb8aa3b, v164
	v_mov_b32_e32 v93, v211
	v_lshlrev_b32_e32 v92, 11, v94
	v_exp_f32_e32 v90, v90
	v_lshl_add_u64 v[170:171], s[60:61], 0, v[92:93]
	v_lshlrev_b32_e32 v92, 16, v144
	v_and_b32_e32 v93, 0xffff0000, v144
	v_lshlrev_b32_e32 v102, 16, v142
	v_lshlrev_b32_e32 v144, 16, v145
	v_and_b32_e32 v145, 0xffff0000, v145
	v_lshlrev_b32_e32 v142, 16, v143
	v_and_b32_e32 v143, 0xffff0000, v143
	v_pk_mul_f32 v[164:165], v[80:81], v[92:93]
	v_pk_mul_f32 v[80:81], v[80:81], v[102:103]
	v_pk_mul_f32 v[166:167], v[82:83], v[144:145]
	v_pk_mul_f32 v[82:83], v[82:83], v[142:143]
	v_pk_fma_f32 v[102:103], v[76:77], v[102:103], v[164:165]
	v_pk_fma_f32 v[76:77], v[76:77], v[92:93], v[80:81] neg_lo:[0,0,1] neg_hi:[0,0,1]
	v_pk_fma_f32 v[80:81], v[78:79], v[142:143], v[166:167]
	v_pk_fma_f32 v[78:79], v[78:79], v[144:145], v[82:83] neg_lo:[0,0,1] neg_hi:[0,0,1]
	v_pk_mul_f32 v[82:83], v[102:103], s[8:9] op_sel_hi:[1,0]
	v_pk_mul_f32 v[76:77], v[76:77], s[8:9] op_sel_hi:[1,0]
	v_pk_mul_f32 v[92:93], v[90:91], v[150:151] op_sel_hi:[0,1]
	v_pk_mul_f32 v[102:103], v[90:91], v[148:149] op_sel_hi:[0,1]
	v_pk_mul_f32 v[148:149], v[80:81], s[8:9] op_sel_hi:[1,0]
	v_pk_mul_f32 v[150:151], v[78:79], s[8:9] op_sel_hi:[1,0]
	v_pk_mul_f32 v[78:79], v[90:91], v[154:155] op_sel_hi:[0,1]
	v_pk_mul_f32 v[80:81], v[90:91], v[152:153] op_sel_hi:[0,1]
	v_pk_mul_f32 v[142:143], v[146:147], v[76:77] op_sel_hi:[0,1]
	v_pk_mul_f32 v[152:153], v[90:91], v[76:77] op_sel_hi:[0,1]
	v_pk_mul_f32 v[164:165], v[90:91], v[82:83] op_sel_hi:[0,1]
	v_cvt_pk_bf16_f32 v76, v92, v93
	v_cvt_pk_bf16_f32 v77, v78, v79
	v_cvt_pk_bf16_f32 v78, v102, v103
	v_pk_mul_f32 v[92:93], v[90:91], v[150:151] op_sel_hi:[0,1]
	v_pk_mul_f32 v[102:103], v[90:91], v[148:149] op_sel_hi:[0,1]
	v_mul_f32_e32 v90, 0x4b800000, v88
	v_pk_mul_f32 v[154:155], v[146:147], v[148:149] op_sel_hi:[0,1]
	v_cvt_pk_bf16_f32 v149, v92, v93
	v_cndmask_b32_e64 v88, v88, v90, s[48:49]
	v_rsq_f32_e32 v90, v88
	v_cvt_pk_bf16_f32 v79, v80, v81
	v_pk_mul_f32 v[144:145], v[146:147], v[82:83] op_sel_hi:[0,1]
	v_pk_mul_f32 v[82:83], v[146:147], v[150:151] op_sel_hi:[0,1]
	v_mul_f32_e32 v94, 0x45800000, v90
	v_cndmask_b32_e64 v90, v90, v94, s[48:49]
	v_mul_f32_e32 v94, v95, v90
	v_mul_f32_e32 v94, v115, v94
	v_cvt_pk_bf16_f32 v80, v142, v143
	v_cvt_pk_bf16_f32 v81, v82, v83
	v_cvt_pk_bf16_f32 v82, v144, v145
	v_cvt_pk_bf16_f32 v83, v154, v155
	v_cvt_pk_bf16_f32 v148, v152, v153
	v_cvt_pk_bf16_f32 v150, v164, v165
	v_cvt_pk_bf16_f32 v151, v102, v103
	v_mfma_f32_16x16x32_bf16 v[152:155], v[76:79], v[80:83], 0
	v_mul_f32_e32 v101, v101, v90
	v_mul_f32_e32 v101, v160, v101
	s_waitcnt vmcnt(47)
	v_mov_b32_e32 v89, v190
	v_or_b32_e32 v212, s4, v97
	v_or_b32_e32 v214, 3, v212
	v_mov_b32_e32 v217, v211
	v_lshlrev_b32_e32 v216, 12, v214
	v_lshl_add_u64 v[216:217], s[58:59], 0, v[216:217]
	v_lshl_add_u64 v[218:219], v[216:217], 0, v[110:111]
	global_load_ushort v190, v[218:219], off offset:3424
	v_lshlrev_b32_e32 v92, 16, v89
	v_mul_f32_e32 v88, 0xbfb8aa3b, v92
	v_exp_f32_e32 v93, v88
	v_lshl_add_u64 v[88:89], v[170:171], 0, v[110:111]
	v_mfma_f32_16x16x32_bf16 v[84:87], v[84:87], v[148:151], 0
	v_add_f32_e32 v93, 1.0, v93
	v_rcp_f32_e32 v93, v93
	v_mfma_f32_16x16x32_bf16 v[142:145], v[8:11], v[80:83], 0
	v_mul_f32_e32 v92, v93, v92
	v_mul_f32_e32 v92, v92, v94
	v_cvt_pk_bf16_f32 v92, v92, s0
	global_store_short v[88:89], v92, off offset:1536
	v_cndmask_b32_e32 v102, v152, v84, vcc
	v_cndmask_b32_e64 v103, v85, v153, s[42:43]
	v_cndmask_b32_e64 v104, v154, v86, s[44:45]
	v_cvt_pk_bf16_f32 v86, v102, v103
	v_mul_f32_e32 v103, v105, v90
	v_mul_f32_e32 v103, v161, v103
	v_cndmask_b32_e64 v87, v155, v87, s[46:47]
	v_mfma_f32_16x16x32_bf16 v[164:167], v[72:75], v[148:151], 0
	v_cvt_pk_bf16_f32 v84, v142, v143
	v_cvt_pk_bf16_f32 v85, v144, v145
	v_cvt_pk_bf16_f32 v87, v104, v87
	v_mfma_f32_16x16x32_bf16 v[92:95], v[12:15], v[148:151], 0
	v_mul_f32_e32 v90, v91, v90
	s_nop 2
	v_cvt_pk_bf16_f32 v152, v164, v165
	v_cvt_pk_bf16_f32 v153, v166, v167
	v_mfma_f32_16x16x32_bf16 v[142:145], v[84:87], v[28:31], 0
	v_mul_f32_e32 v90, v159, v90
	v_cvt_pk_bf16_f32 v154, v92, v93
	v_cvt_pk_bf16_f32 v155, v94, v95
	v_mfma_f32_16x16x32_bf16 v[148:151], v[84:87], v[44:47], 0
	s_waitcnt vmcnt(48)
	v_mov_b32_e32 v100, v191
	global_load_ushort v191, v[218:219], off offset:3456
	v_lshlrev_b32_e32 v100, 16, v100
	v_mul_f32_e32 v102, 0xbfb8aa3b, v100
	v_exp_f32_e32 v102, v102
	v_mfma_f32_16x16x32_bf16 v[92:95], v[152:155], v[20:23], v[142:145]
	v_add_f32_e32 v102, 1.0, v102
	v_rcp_f32_e32 v102, v102
	v_mfma_f32_16x16x32_bf16 v[142:145], v[152:155], v[32:35], v[148:151]
	v_mul_f32_e32 v100, v102, v100
	v_mul_f32_e32 v100, v103, v100
	v_cvt_pk_bf16_f32 v100, v100, s0
	global_store_short v[88:89], v100, off offset:1568
	v_mfma_f32_16x16x32_bf16 v[102:105], v[84:87], v[56:59], 0
	s_waitcnt vmcnt(49)
; __device__ __forceinline__ unsigned cvtpk(float lo, float hi) { f32x2_t v = {lo, hi}; bf16x2_t b = __builtin_convertvector(v, bf16x2_t); return __builtin_bit_cast(unsigned, b); }
; template <int X> __device__ __forceinline__ float swz_xor(float v) { return __int_as_float(__builtin_amdgcn_ds_swizzle(__float_as_int(v), (X << 10) | 0x1F)); }
; __device__ __forceinline__ float silu_f(float g) { return g * __builtin_amdgcn_rcpf(1.0f + __expf(-g)); }
; template <bool GLA>
; __device__ __forceinline__ void chunk_pass_c(const ChunkIn& ci, const float* wgl, int unit, unsigned char* wl, int lane, const float* Sb, const float* ng, bf16_t* omix) {
;     ...
;         f32x4 o[4]; float ss[4] = {0.f, 0.f, 0.f, 0.f};
; #pragma unroll
;         for (int et = 0; et < 4; ++et) {
;             f32x4 acc = {0.f, 0.f, 0.f, 0.f};
;             acc = __builtin_amdgcn_mfma_f32_16x16x32_bf16(af[0], vfr[et][0], acc, 0, 0, 0);
;             acc = __builtin_amdgcn_mfma_f32_16x16x32_bf16(af[1], vfr[et][1], acc, 0, 0, 0);
;             acc = __builtin_amdgcn_mfma_f32_16x16x32_bf16(qf[it], sfr[et], acc, 0, 0, 0);
;             o[et] = acc;
; #pragma unroll
;             for (int r = 0; r < 4; ++r) ss[r] += acc[r] * acc[r];
;         }
; #pragma unroll
;         for (int r = 0; r < 4; ++r) {
;             ss[r] += swz_xor<1>(ss[r]); ss[r] += swz_xor<2>(ss[r]); ss[r] += swz_xor<4>(ss[r]); ss[r] += swz_xor<8>(ss[r]);
;             const float rs = rsqrtf(ss[r] * (1.0f / 64.0f) + EPS);
;             const int t = t0 + 16 * it + 4 * kq + r;
; #pragma unroll
;             for (int et = 0; et < 4; ++et) {
;                 const int e = 16 * et + row;
;                 const float gt = __uint_as_float((unsigned)ci.proj[(size_t)t * DINP + gcol + e] << 16);
;                 const float val = o[et][r] * rs * gn[et] * pg8::silu_f(gt);
;                 omix[(size_t)t * 1024 + ocol + e] = (bf16_t)(cvtpk(val, 0.f) & 0xffffu);
;             }
;         }
	v_mov_b32_e32 v98, v192
	global_load_ushort v192, v[218:219], off offset:3488
	v_lshlrev_b32_e32 v100, 16, v98
	v_mul_f32_e32 v98, 0xbfb8aa3b, v100
	v_exp_f32_e32 v146, v98
	v_lshl_add_u64 v[98:99], v[168:169], 0, v[112:113]
	v_mfma_f32_16x16x32_bf16 v[84:87], v[84:87], v[60:63], 0
	v_add_f32_e32 v146, 1.0, v146
	v_rcp_f32_e32 v146, v146
	v_mfma_f32_16x16x32_bf16 v[148:151], v[152:155], v[48:51], v[84:87]
	v_mul_f32_e32 v100, v146, v100
	v_mul_f32_e32 v100, v101, v100
	v_cvt_pk_bf16_f32 v100, v100, s0
	global_store_short v[88:89], v100, off offset:1600
	v_mfma_f32_16x16x32_bf16 v[98:101], v[80:83], v[24:27], v[92:95]
	v_mov_b32_e32 v89, v211
	s_waitcnt vmcnt(50)
	v_mov_b32_e32 v146, v193
	v_lshlrev_b32_e32 v212, 1, v177
	v_mov_b32_e32 v213, v211
	v_or_b32_e32 v214, s4, v97
	v_or_b32_e32 v216, 3, v214
	v_mov_b32_e32 v219, v211
	v_lshlrev_b32_e32 v218, 12, v216
	v_lshl_add_u64 v[218:219], s[58:59], 0, v[218:219]
	v_lshl_add_u64 v[220:221], v[218:219], 0, v[212:213]
	global_load_ushort v193, v[220:221], off offset:3424
	v_lshlrev_b32_e32 v146, 16, v146
	v_mul_f32_e32 v84, 0xbfb8aa3b, v146
	v_exp_f32_e32 v84, v84
	v_mfma_f32_16x16x32_bf16 v[92:95], v[80:83], v[16:19], v[142:145]
	v_add_f32_e32 v84, 1.0, v84
	s_nop 1
	v_rcp_f32_e32 v144, v84
	v_mfma_f32_16x16x32_bf16 v[102:105], v[152:155], v[52:55], v[102:105]
	v_or_b32_e32 v154, s5, v97
	v_lshlrev_b32_e32 v88, 12, v154
	v_mul_f32_e32 v91, v144, v146
	v_mul_f32_e32 v90, v90, v91
	v_lshl_add_u64 v[88:89], s[58:59], 0, v[88:89]
	v_lshl_add_u64 v[152:153], v[170:171], 0, v[112:113]
	v_cvt_pk_bf16_f32 v90, v90, s0
	v_lshl_add_u64 v[142:143], v[88:89], 0, v[110:111]
	global_store_short v[152:153], v90, off offset:1536
	v_mfma_f32_16x16x32_bf16 v[84:87], v[80:83], v[36:39], v[102:105]
	v_mov_b32_e32 v90, v98
	v_mov_b32_e32 v91, v92
	v_pk_mul_f32 v[90:91], v[90:91], v[90:91]
	v_mfma_f32_16x16x32_bf16 v[80:83], v[80:83], v[40:43], v[148:151]
	v_mov_b32_e32 v102, v99
	v_mov_b32_e32 v103, v93
	s_nop 1
	v_mov_b32_e32 v104, v84
	v_mov_b32_e32 v144, v85
	v_pk_mul_f32 v[102:103], v[102:103], v[102:103]
	s_nop 0
	v_mov_b32_e32 v105, v80
	v_mov_b32_e32 v145, v81
	v_pk_mul_f32 v[104:105], v[104:105], v[104:105]
	v_pk_mul_f32 v[144:145], v[144:145], v[144:145]
	v_mov_b32_e32 v148, v102
	v_mov_b32_e32 v149, v90
	v_mov_b32_e32 v90, v103
	v_mov_b32_e32 v102, v144
	v_mov_b32_e32 v103, v104
	v_pk_add_f32 v[90:91], v[148:149], v[90:91]
	v_mov_b32_e32 v104, v145
	v_pk_add_f32 v[90:91], v[90:91], v[102:103]
	v_lshl_add_u64 v[88:89], v[88:89], 0, v[112:113]
	v_pk_add_f32 v[90:91], v[90:91], v[104:105]
	ds_swizzle_b32 v103, v91 offset:swizzle(SWAP,1)
	ds_swizzle_b32 v102, v90 offset:swizzle(SWAP,1)
	v_mov_b32_e32 v105, v211
	v_lshlrev_b32_e32 v104, 11, v154
	s_waitcnt lgkmcnt(0)
	v_pk_add_f32 v[90:91], v[90:91], v[102:103]
	ds_swizzle_b32 v103, v91 offset:swizzle(SWAP,2)
	ds_swizzle_b32 v102, v90 offset:swizzle(SWAP,2)
	s_waitcnt lgkmcnt(0)
	v_pk_add_f32 v[90:91], v[90:91], v[102:103]
	ds_swizzle_b32 v103, v91 offset:swizzle(SWAP,4)
	ds_swizzle_b32 v102, v90 offset:swizzle(SWAP,4)
	s_waitcnt lgkmcnt(0)
	v_pk_add_f32 v[90:91], v[90:91], v[102:103]
	ds_swizzle_b32 v103, v91 offset:swizzle(SWAP,8)
	ds_swizzle_b32 v102, v90 offset:swizzle(SWAP,8)
	s_waitcnt lgkmcnt(0)
	v_pk_add_f32 v[90:91], v[90:91], v[102:103]
	s_nop 0
	v_pk_fma_f32 v[90:91], v[90:91], s[6:7], v[116:117] op_sel_hi:[1,0,0]
	s_waitcnt vmcnt(51)
	v_mov_b32_e32 v146, v194
	v_mov_b32_e32 v213, v211
	v_or_b32_e32 v212, s3, v97
	v_lshlrev_b64 v[214:215], 12, v[212:213]
	v_lshl_add_u64 v[216:217], s[58:59], 0, v[214:215]
	v_lshl_add_u64 v[218:219], v[216:217], 0, v[110:111]
	global_load_ushort v194, v[218:219], off offset:3424
	v_lshlrev_b32_e32 v144, 16, v146
	v_mul_f32_e32 v102, 0x4b800000, v91
	v_cmp_gt_f32_e64 s[48:49], s96, v91
	s_nop 1
	v_cndmask_b32_e64 v91, v91, v102, s[48:49]
	v_mul_f32_e32 v102, 0xbfb8aa3b, v144
	v_exp_f32_e32 v145, v102
	v_rsq_f32_e32 v91, v91
	v_lshl_add_u64 v[102:103], s[60:61], 0, v[104:105]
	v_lshl_add_u64 v[104:105], v[102:103], 0, v[110:111]
	v_add_f32_e32 v145, 1.0, v145
	v_rcp_f32_e32 v145, v145
	v_mul_f32_e32 v146, 0x45800000, v91
	v_cndmask_b32_e64 v91, v91, v146, s[48:49]
	v_mul_f32_e32 v98, v98, v91
	v_mul_f32_e32 v98, v115, v98
	v_mul_f32_e32 v144, v145, v144
	v_mul_f32_e32 v98, v144, v98
	v_cvt_pk_bf16_f32 v98, v98, s0
	global_store_short v[104:105], v98, off offset:1536
	v_mul_f32_e32 v92, v92, v91
	v_mul_f32_e32 v92, v161, v92
	v_mul_f32_e32 v84, v84, v91
	v_mul_f32_e32 v84, v160, v84
	v_mul_f32_e32 v80, v80, v91
	v_mul_f32_e32 v80, v159, v80
	v_lshl_add_u64 v[102:103], v[102:103], 0, v[112:113]
	v_cmp_gt_f32_e64 s[48:49], s96, v90
	s_waitcnt vmcnt(52)
	v_mov_b32_e32 v98, v195
	global_load_ushort v195, v[218:219], off offset:3456
	v_lshlrev_b32_e32 v98, 16, v98
	v_mul_f32_e32 v144, 0xbfb8aa3b, v98
	v_exp_f32_e32 v144, v144
	s_nop 0
	v_add_f32_e32 v144, 1.0, v144
	v_rcp_f32_e32 v144, v144
	s_nop 0
	v_mul_f32_e32 v98, v144, v98
	v_mul_f32_e32 v92, v98, v92
	v_cvt_pk_bf16_f32 v92, v92, s0
	global_store_short v[104:105], v92, off offset:1568
	s_waitcnt vmcnt(53)
	v_mov_b32_e32 v92, v196
	global_load_ushort v196, v[218:219], off offset:3488
	v_lshlrev_b32_e32 v92, 16, v92
	v_mul_f32_e32 v98, 0xbfb8aa3b, v92
	v_exp_f32_e32 v98, v98
	s_nop 0
	v_add_f32_e32 v98, 1.0, v98
	v_rcp_f32_e32 v98, v98
	s_nop 0
	v_mul_f32_e32 v92, v98, v92
	v_mul_f32_e32 v84, v84, v92
	v_cvt_pk_bf16_f32 v84, v84, s0
	global_store_short v[104:105], v84, off offset:1600
	v_or_b32_e32 v92, 1, v154
	v_mov_b32_e32 v89, v211
	s_waitcnt vmcnt(54)
; __device__ __forceinline__ unsigned cvtpk(float lo, float hi) { f32x2_t v = {lo, hi}; bf16x2_t b = __builtin_convertvector(v, bf16x2_t); return __builtin_bit_cast(unsigned, b); }
; template <int X> __device__ __forceinline__ float swz_xor(float v) { return __int_as_float(__builtin_amdgcn_ds_swizzle(__float_as_int(v), (X << 10) | 0x1F)); }
; __device__ __forceinline__ float silu_f(float g) { return g * __builtin_amdgcn_rcpf(1.0f + __expf(-g)); }
; template <bool GLA>
; __device__ __forceinline__ void chunk_pass_c(const ChunkIn& ci, const float* wgl, int unit, unsigned char* wl, int lane, const float* Sb, const float* ng, bf16_t* omix) {
;     ...
;         f32x4 o[4]; float ss[4] = {0.f, 0.f, 0.f, 0.f};
; #pragma unroll
;         for (int et = 0; et < 4; ++et) {
;             f32x4 acc = {0.f, 0.f, 0.f, 0.f};
;             acc = __builtin_amdgcn_mfma_f32_16x16x32_bf16(af[0], vfr[et][0], acc, 0, 0, 0);
;             acc = __builtin_amdgcn_mfma_f32_16x16x32_bf16(af[1], vfr[et][1], acc, 0, 0, 0);
;             acc = __builtin_amdgcn_mfma_f32_16x16x32_bf16(qf[it], sfr[et], acc, 0, 0, 0);
;             o[et] = acc;
; #pragma unroll
;             for (int r = 0; r < 4; ++r) ss[r] += acc[r] * acc[r];
;         }
; #pragma unroll
;         for (int r = 0; r < 4; ++r) {
;             ss[r] += swz_xor<1>(ss[r]); ss[r] += swz_xor<2>(ss[r]); ss[r] += swz_xor<4>(ss[r]); ss[r] += swz_xor<8>(ss[r]);
;             const float rs = rsqrtf(ss[r] * (1.0f / 64.0f) + EPS);
;             const int t = t0 + 16 * it + 4 * kq + r;
; #pragma unroll
;             for (int et = 0; et < 4; ++et) {
;                 const int e = 16 * et + row;
;                 const float gt = __uint_as_float((unsigned)ci.proj[(size_t)t * DINP + gcol + e] << 16);
;                 const float val = o[et][r] * rs * gn[et] * pg8::silu_f(gt);
;                 omix[(size_t)t * 1024 + ocol + e] = (bf16_t)(cvtpk(val, 0.f) & 0xffffu);
;             }
;         }
	v_mov_b32_e32 v84, v197
	v_lshlrev_b32_e32 v212, 1, v177
	v_mov_b32_e32 v213, v211
	v_mov_b32_e32 v215, v211
	v_or_b32_e32 v214, s3, v97
	v_lshlrev_b64 v[216:217], 12, v[214:215]
	v_lshl_add_u64 v[218:219], s[58:59], 0, v[216:217]
	v_lshl_add_u64 v[218:219], v[218:219], 0, v[212:213]
	global_load_ushort v197, v[218:219], off offset:3424
	v_lshlrev_b32_e32 v84, 16, v84
	v_mul_f32_e32 v88, 0xbfb8aa3b, v84
	v_exp_f32_e32 v98, v88
	v_lshlrev_b32_e32 v88, 12, v92
	v_lshl_add_u64 v[88:89], s[58:59], 0, v[88:89]
	v_lshl_add_u64 v[104:105], v[88:89], 0, v[110:111]
	v_add_f32_e32 v98, 1.0, v98
	v_rcp_f32_e32 v98, v98
	v_lshl_add_u64 v[88:89], v[88:89], 0, v[112:113]
	v_mul_f32_e32 v84, v98, v84
	v_mul_f32_e32 v80, v80, v84
	v_cvt_pk_bf16_f32 v80, v80, s0
	global_store_short v[102:103], v80, off offset:1536
	v_mul_f32_e32 v84, 0x4b800000, v90
	v_cndmask_b32_e64 v84, v90, v84, s[48:49]
	v_lshlrev_b32_e32 v102, 11, v92
	v_rsq_f32_e32 v84, v84
	v_mov_b32_e32 v103, v211
	v_mul_f32_e32 v98, 0x45800000, v84
	v_cndmask_b32_e64 v98, v84, v98, s[48:49]
	v_mul_f32_e32 v84, v99, v98
	v_mul_f32_e32 v84, v115, v84
	v_mul_f32_e32 v85, v85, v98
	v_mul_f32_e32 v85, v160, v85
	v_mul_f32_e32 v81, v81, v98
	v_mul_f32_e32 v81, v159, v81
	v_mov_b32_e32 v99, v83
	s_waitcnt vmcnt(55)
	v_mov_b32_e32 v80, v198
	v_or_b32_e32 v212, s3, v97
	v_mov_b32_e32 v215, v211
	v_or_b32_e32 v214, 1, v212
	v_lshlrev_b64 v[216:217], 12, v[214:215]
	v_lshl_add_u64 v[216:217], s[58:59], 0, v[216:217]
	v_lshl_add_u64 v[218:219], v[216:217], 0, v[110:111]
	global_load_ushort v198, v[218:219], off offset:3424
	v_lshlrev_b32_e32 v80, 16, v80
	v_mul_f32_e32 v90, 0xbfb8aa3b, v80
	v_exp_f32_e32 v92, v90
	v_lshl_add_u64 v[90:91], s[60:61], 0, v[102:103]
	v_lshl_add_u64 v[102:103], v[90:91], 0, v[110:111]
	v_add_f32_e32 v92, 1.0, v92
	v_rcp_f32_e32 v92, v92
	s_nop 0
	v_mul_f32_e32 v80, v92, v80
	v_mul_f32_e32 v80, v80, v84
	v_cvt_pk_bf16_f32 v80, v80, s0
	global_store_short v[102:103], v80, off offset:1536
	v_mul_f32_e32 v92, v93, v98
	v_mul_f32_e32 v92, v161, v92
	v_mov_b32_e32 v93, v82
	v_mov_b32_e32 v98, v87
	v_pk_mul_f32 v[98:99], v[98:99], v[98:99]
	s_waitcnt vmcnt(56)
	v_mov_b32_e32 v80, v199
	global_load_ushort v199, v[218:219], off offset:3456
	v_lshlrev_b32_e32 v80, 16, v80
	v_mul_f32_e32 v84, 0xbfb8aa3b, v80
	v_exp_f32_e32 v84, v84
	s_nop 0
	v_add_f32_e32 v84, 1.0, v84
	v_rcp_f32_e32 v84, v84
	s_nop 0
	v_mul_f32_e32 v80, v84, v80
	v_mul_f32_e32 v80, v92, v80
	v_cvt_pk_bf16_f32 v80, v80, s0
	global_store_short v[102:103], v80, off offset:1568
	v_or_b32_e32 v104, 2, v154
	s_waitcnt vmcnt(57)
	v_mov_b32_e32 v80, v200
	global_load_ushort v200, v[218:219], off offset:3488
	v_lshlrev_b32_e32 v80, 16, v80
	v_mul_f32_e32 v84, 0xbfb8aa3b, v80
	v_exp_f32_e32 v84, v84
	s_nop 0
	v_add_f32_e32 v84, 1.0, v84
	v_rcp_f32_e32 v84, v84
	s_nop 0
	v_mul_f32_e32 v80, v84, v80
	v_mul_f32_e32 v80, v85, v80
	v_cvt_pk_bf16_f32 v80, v80, s0
	global_store_short v[102:103], v80, off offset:1600
	v_lshl_add_u64 v[88:89], v[90:91], 0, v[112:113]
	v_mov_b32_e32 v85, v211
	s_waitcnt vmcnt(58)
	v_mov_b32_e32 v80, v201
	v_lshlrev_b32_e32 v212, 1, v177
	v_mov_b32_e32 v213, v211
	v_or_b32_e32 v214, s3, v97
	v_mov_b32_e32 v217, v211
	v_or_b32_e32 v216, 1, v214
	v_lshlrev_b64 v[218:219], 12, v[216:217]
	v_lshl_add_u64 v[218:219], s[58:59], 0, v[218:219]
	v_lshl_add_u64 v[220:221], v[218:219], 0, v[212:213]
	global_load_ushort v201, v[220:221], off offset:3424
	v_lshlrev_b32_e32 v80, 16, v80
	v_mul_f32_e32 v84, 0xbfb8aa3b, v80
	v_exp_f32_e32 v92, v84
	v_lshlrev_b32_e32 v84, 12, v104
	v_lshl_add_u64 v[84:85], s[58:59], 0, v[84:85]
	v_add_f32_e32 v90, 1.0, v92
	v_rcp_f32_e32 v92, v90
	v_lshl_add_u64 v[90:91], v[84:85], 0, v[110:111]
	v_lshl_add_u64 v[84:85], v[84:85], 0, v[112:113]
	v_mul_f32_e32 v80, v92, v80
	v_mul_f32_e32 v80, v81, v80
	v_cvt_pk_bf16_f32 v80, v80, s0
	global_store_short v[88:89], v80, off offset:1536
	v_mov_b32_e32 v80, v100
	v_mov_b32_e32 v81, v94
	v_mov_b32_e32 v88, v101
	v_mov_b32_e32 v89, v95
	v_mov_b32_e32 v92, v86
	v_pk_mul_f32 v[80:81], v[80:81], v[80:81]
	v_pk_mul_f32 v[88:89], v[88:89], v[88:89]
	v_pk_mul_f32 v[92:93], v[92:93], v[92:93]
	v_mov_b32_e32 v102, v88
	v_mov_b32_e32 v103, v80
	v_mov_b32_e32 v80, v89
	v_mov_b32_e32 v88, v98
	v_mov_b32_e32 v89, v92
	v_pk_add_f32 v[80:81], v[102:103], v[80:81]
	v_mov_b32_e32 v92, v99
	v_pk_add_f32 v[80:81], v[80:81], v[88:89]
	v_and_b32_e32 v103, 0xffff0000, v129
	v_pk_add_f32 v[80:81], v[80:81], v[92:93]
	ds_swizzle_b32 v89, v81 offset:swizzle(SWAP,1)
	ds_swizzle_b32 v88, v80 offset:swizzle(SWAP,1)
	v_mov_b32_e32 v93, v211
	v_lshlrev_b32_e32 v92, 11, v104
	s_waitcnt lgkmcnt(0)
	v_pk_add_f32 v[80:81], v[80:81], v[88:89]
	ds_swizzle_b32 v89, v81 offset:swizzle(SWAP,2)
	ds_swizzle_b32 v88, v80 offset:swizzle(SWAP,2)
	s_waitcnt lgkmcnt(0)
	v_pk_add_f32 v[80:81], v[80:81], v[88:89]
	ds_swizzle_b32 v89, v81 offset:swizzle(SWAP,4)
	ds_swizzle_b32 v88, v80 offset:swizzle(SWAP,4)
	s_waitcnt lgkmcnt(0)
	v_pk_add_f32 v[80:81], v[80:81], v[88:89]
	ds_swizzle_b32 v89, v81 offset:swizzle(SWAP,8)
	ds_swizzle_b32 v88, v80 offset:swizzle(SWAP,8)
	s_waitcnt lgkmcnt(0)
	v_pk_add_f32 v[80:81], v[80:81], v[88:89]
	s_nop 0
	v_pk_fma_f32 v[80:81], v[80:81], s[6:7], v[116:117] op_sel_hi:[1,0,0]
	s_waitcnt vmcnt(59)
; template <bool GLA>
; __device__ __forceinline__ void chunk_pass_c(const ChunkIn& ci, const float* wgl, int unit, unsigned char* wl, int lane, const float* Sb, const float* ng, bf16_t* omix) {
;     ...
;     for (int it = 0; it < 4; ++it) {
;         f32x4 st[4];
; #pragma unroll
;         for (int jt = 0; jt < 4; ++jt) {
;             const f32x4 z = {0.f, 0.f, 0.f, 0.f};
;             if (jt < it) st[jt] = __builtin_amdgcn_mfma_f32_16x16x32_bf16(kf[jt], qf[it], z, 0, 0, 0);
;             else if (jt > it) st[jt] = __builtin_amdgcn_mfma_f32_16x16x32_bf16(kb[jt], qb[it], z, 0, 0, 0);
;             else {
;                 const f32x4 lo = __builtin_amdgcn_mfma_f32_16x16x32_bf16(kf[jt], qf[it], z, 0, 0, 0), up = __builtin_amdgcn_mfma_f32_16x16x32_bf16(kb[jt], qb[it], z, 0, 0, 0);
; #pragma unroll
;                 for (int r = 0; r < 4; ++r) st[jt][r] = (4 * kq + r <= row) ? lo[r] : up[r];
;             }
;         }
;         bf16x8 af[2];
; #pragma unroll
;         for (int p = 0; p < 2; ++p)
;             af[p] = __builtin_bit_cast(bf16x8, (u32x4){cvtpk(st[2 * p][0], st[2 * p][1]), cvtpk(st[2 * p][2], st[2 * p][3]), cvtpk(st[2 * p + 1][0], st[2 * p + 1][1]), cvtpk(st[2 * p + 1][2], st[2 * p + 1][3])});
;         f32x4 o[4]; float ss[4] = {0.f, 0.f, 0.f, 0.f};
; #pragma unroll
;         for (int et = 0; et < 4; ++et) {
;             f32x4 acc = {0.f, 0.f, 0.f, 0.f};
;             acc = __builtin_amdgcn_mfma_f32_16x16x32_bf16(af[0], vfr[et][0], acc, 0, 0, 0);
;             acc = __builtin_amdgcn_mfma_f32_16x16x32_bf16(af[1], vfr[et][1], acc, 0, 0, 0);
;             acc = __builtin_amdgcn_mfma_f32_16x16x32_bf16(qf[it], sfr[et], acc, 0, 0, 0);
;             o[et] = acc;
; #pragma unroll
;             for (int r = 0; r < 4; ++r) ss[r] += acc[r] * acc[r];
;         }
; #pragma unroll
;         for (int r = 0; r < 4; ++r) {
;             ss[r] += swz_xor<1>(ss[r]); ss[r] += swz_xor<2>(ss[r]); ss[r] += swz_xor<4>(ss[r]); ss[r] += swz_xor<8>(ss[r]);
;             const float rs = rsqrtf(ss[r] * (1.0f / 64.0f) + EPS);
;             const int t = t0 + 16 * it + 4 * kq + r;
; #pragma unroll
;             for (int et = 0; et < 4; ++et) {
;                 const int e = 16 * et + row;
;                 const float gt = __uint_as_float((unsigned)ci.proj[(size_t)t * DINP + gcol + e] << 16);
;                 const float val = o[et][r] * rs * gn[et] * pg8::silu_f(gt);
	v_mov_b32_e32 v105, v202
	v_or_b32_e32 v212, s3, v97
	v_mov_b32_e32 v215, v211
	v_or_b32_e32 v214, 2, v212
	v_lshlrev_b64 v[216:217], 12, v[214:215]
	v_lshl_add_u64 v[216:217], s[58:59], 0, v[216:217]
	v_lshl_add_u64 v[218:219], v[216:217], 0, v[110:111]
	global_load_ushort v202, v[218:219], off offset:3424
	v_lshlrev_b32_e32 v98, 16, v105
	v_mul_f32_e32 v88, 0x4b800000, v81
	v_cmp_gt_f32_e64 s[48:49], s96, v81
	s_nop 1
	v_cndmask_b32_e64 v81, v81, v88, s[48:49]
	v_mul_f32_e32 v88, 0xbfb8aa3b, v98
	v_exp_f32_e32 v99, v88
	v_rsq_f32_e32 v81, v81
	v_lshl_add_u64 v[88:89], s[60:61], 0, v[92:93]
	v_lshl_add_u64 v[92:93], v[88:89], 0, v[110:111]
	v_add_f32_e32 v99, 1.0, v99
	v_rcp_f32_e32 v99, v99
	v_mul_f32_e32 v102, 0x45800000, v81
	v_cndmask_b32_e64 v81, v81, v102, s[48:49]
	v_mul_f32_e32 v100, v100, v81
	v_mul_f32_e32 v100, v115, v100
	v_mul_f32_e32 v98, v99, v98
	v_mul_f32_e32 v98, v98, v100
	v_cvt_pk_bf16_f32 v98, v98, s0
	global_store_short v[92:93], v98, off offset:1536
	v_mul_f32_e32 v94, v94, v81
	v_mul_f32_e32 v94, v161, v94
	v_mul_f32_e32 v86, v86, v81
	v_mul_f32_e32 v86, v160, v86
	v_mul_f32_e32 v81, v82, v81
	v_mul_f32_e32 v81, v159, v81
	v_lshl_add_u64 v[88:89], v[88:89], 0, v[112:113]
	v_lshlrev_b32_e32 v102, 16, v129
	v_cmp_gt_f32_e64 s[48:49], s96, v80
	s_waitcnt vmcnt(60)
	v_mov_b32_e32 v98, v203
	global_load_ushort v203, v[218:219], off offset:3456
	v_lshlrev_b32_e32 v98, 16, v98
	v_mul_f32_e32 v99, 0xbfb8aa3b, v98
	v_exp_f32_e32 v99, v99
	s_nop 0
	v_add_f32_e32 v99, 1.0, v99
	v_rcp_f32_e32 v99, v99
	s_nop 0
	v_mul_f32_e32 v98, v99, v98
	v_mul_f32_e32 v94, v94, v98
	v_cvt_pk_bf16_f32 v94, v94, s0
	global_store_short v[92:93], v94, off offset:1568
	v_lshlrev_b32_e32 v98, 16, v131
	v_and_b32_e32 v99, 0xffff0000, v131
	s_waitcnt vmcnt(61)
	v_mov_b32_e32 v90, v204
	global_load_ushort v204, v[218:219], off offset:3488
	v_lshlrev_b32_e32 v90, 16, v90
	v_mul_f32_e32 v91, 0xbfb8aa3b, v90
	v_exp_f32_e32 v91, v91
	s_nop 0
	v_add_f32_e32 v91, 1.0, v91
	v_rcp_f32_e32 v91, v91
	s_nop 0
	v_mul_f32_e32 v90, v91, v90
	v_mul_f32_e32 v86, v86, v90
	v_cvt_pk_bf16_f32 v86, v86, s0
	global_store_short v[92:93], v86, off offset:1600
	v_or_b32_e32 v86, 3, v154
	v_mov_b32_e32 v85, v211
	s_waitcnt vmcnt(62)
	v_mov_b32_e32 v84, v205
	v_lshlrev_b32_e32 v212, 1, v177
	v_mov_b32_e32 v213, v211
	v_or_b32_e32 v214, s3, v97
	v_mov_b32_e32 v217, v211
	v_or_b32_e32 v216, 2, v214
	v_lshlrev_b64 v[218:219], 12, v[216:217]
	v_lshl_add_u64 v[218:219], s[58:59], 0, v[218:219]
	v_lshl_add_u64 v[218:219], v[218:219], 0, v[212:213]
	global_load_ushort v205, v[218:219], off offset:3424
	v_lshlrev_b32_e32 v90, 16, v84
	v_mul_f32_e32 v84, 0xbfb8aa3b, v90
	v_exp_f32_e32 v91, v84
	v_lshlrev_b32_e32 v84, 12, v86
	v_lshl_add_u64 v[84:85], s[58:59], 0, v[84:85]
	v_lshl_add_u64 v[92:93], v[84:85], 0, v[110:111]
	v_add_f32_e32 v91, 1.0, v91
	v_rcp_f32_e32 v91, v91
	s_nop 0
	v_mul_f32_e32 v82, v91, v90
	v_mul_f32_e32 v81, v81, v82
	v_cvt_pk_bf16_f32 v81, v81, s0
	global_store_short v[88:89], v81, off offset:1536
	v_mov_b32_e32 v89, v211
	v_lshlrev_b32_e32 v88, 11, v86
	v_mul_f32_e32 v82, 0xbfb8aa3b, v163
	v_lshl_add_u64 v[142:143], s[60:61], 0, v[88:89]
	v_exp_f32_e32 v82, v82
	v_lshlrev_b32_e32 v88, 16, v130
	v_and_b32_e32 v89, 0xffff0000, v130
	v_lshlrev_b32_e32 v90, 16, v128
	v_and_b32_e32 v91, 0xffff0000, v128
	v_pk_mul_f32 v[104:105], v[68:69], v[88:89]
	v_pk_mul_f32 v[68:69], v[68:69], v[90:91]
	v_pk_mul_f32 v[128:129], v[70:71], v[98:99]
	v_pk_mul_f32 v[70:71], v[70:71], v[102:103]
	v_pk_fma_f32 v[90:91], v[64:65], v[90:91], v[104:105]
	v_pk_fma_f32 v[64:65], v[64:65], v[88:89], v[68:69] neg_lo:[0,0,1] neg_hi:[0,0,1]
	v_pk_fma_f32 v[68:69], v[66:67], v[102:103], v[128:129]
	v_pk_fma_f32 v[66:67], v[66:67], v[98:99], v[70:71] neg_lo:[0,0,1] neg_hi:[0,0,1]
	v_pk_mul_f32 v[70:71], v[90:91], s[8:9] op_sel_hi:[1,0]
	v_pk_mul_f32 v[64:65], v[64:65], s[8:9] op_sel_hi:[1,0]
	v_pk_mul_f32 v[68:69], v[68:69], s[8:9] op_sel_hi:[1,0]
	v_pk_mul_f32 v[66:67], v[66:67], s[8:9] op_sel_hi:[1,0]
	v_pk_mul_f32 v[88:89], v[82:83], v[136:137] op_sel_hi:[0,1]
	v_pk_mul_f32 v[98:99], v[82:83], v[134:135] op_sel_hi:[0,1]
	v_pk_mul_f32 v[102:103], v[82:83], v[140:141] op_sel_hi:[0,1]
	v_pk_mul_f32 v[104:105], v[82:83], v[138:139] op_sel_hi:[0,1]
	v_pk_mul_f32 v[128:129], v[82:83], v[64:65] op_sel_hi:[0,1]
	v_pk_mul_f32 v[134:135], v[82:83], v[70:71] op_sel_hi:[0,1]
	v_pk_mul_f32 v[136:137], v[82:83], v[66:67] op_sel_hi:[0,1]
	v_pk_mul_f32 v[138:139], v[82:83], v[68:69] op_sel_hi:[0,1]
	v_mul_f32_e32 v82, 0x4b800000, v80
	v_cndmask_b32_e64 v80, v80, v82, s[48:49]
	v_rsq_f32_e32 v80, v80
	v_pk_mul_f32 v[90:91], v[132:133], v[64:65] op_sel_hi:[0,1]
	v_pk_mul_f32 v[130:131], v[132:133], v[70:71] op_sel_hi:[0,1]
	v_pk_mul_f32 v[70:71], v[132:133], v[66:67] op_sel_hi:[0,1]
	v_mul_f32_e32 v86, 0x45800000, v80
	v_pk_mul_f32 v[66:67], v[132:133], v[68:69] op_sel_hi:[0,1]
	v_cndmask_b32_e64 v132, v80, v86, s[48:49]
	v_mul_f32_e32 v80, v101, v132
	v_mul_f32_e32 v80, v115, v80
	v_lshl_add_u64 v[144:145], v[142:143], 0, v[110:111]
	v_cvt_pk_bf16_f32 v64, v88, v89
	v_cvt_pk_bf16_f32 v69, v70, v71
	v_cvt_pk_bf16_f32 v71, v66, v67
	v_cvt_pk_bf16_f32 v65, v102, v103
	v_cvt_pk_bf16_f32 v66, v98, v99
	v_cvt_pk_bf16_f32 v67, v104, v105
	v_cvt_pk_bf16_f32 v68, v90, v91
	v_cvt_pk_bf16_f32 v70, v130, v131
	v_cvt_pk_bf16_f32 v128, v128, v129
	v_cvt_pk_bf16_f32 v129, v136, v137
	v_cvt_pk_bf16_f32 v130, v134, v135
	v_cvt_pk_bf16_f32 v131, v138, v139
	v_mfma_f32_16x16x32_bf16 v[134:137], v[64:67], v[68:71], 0
	v_mul_f32_e32 v83, v83, v132
	v_mul_f32_e32 v83, v159, v83
	s_waitcnt vmcnt(63)
; template <bool GLA>
; __device__ __forceinline__ void chunk_pass_c(const ChunkIn& ci, const float* wgl, int unit, unsigned char* wl, int lane, const float* Sb, const float* ng, bf16_t* omix) {
;     ...
;     for (int it = 0; it < 4; ++it) {
;         f32x4 st[4];
; #pragma unroll
;         for (int jt = 0; jt < 4; ++jt) {
;             const f32x4 z = {0.f, 0.f, 0.f, 0.f};
;             if (jt < it) st[jt] = __builtin_amdgcn_mfma_f32_16x16x32_bf16(kf[jt], qf[it], z, 0, 0, 0);
;             else if (jt > it) st[jt] = __builtin_amdgcn_mfma_f32_16x16x32_bf16(kb[jt], qb[it], z, 0, 0, 0);
;             else {
;                 const f32x4 lo = __builtin_amdgcn_mfma_f32_16x16x32_bf16(kf[jt], qf[it], z, 0, 0, 0), up = __builtin_amdgcn_mfma_f32_16x16x32_bf16(kb[jt], qb[it], z, 0, 0, 0);
; #pragma unroll
;                 for (int r = 0; r < 4; ++r) st[jt][r] = (4 * kq + r <= row) ? lo[r] : up[r];
;             }
;         }
;         bf16x8 af[2];
; #pragma unroll
;         for (int p = 0; p < 2; ++p)
;             af[p] = __builtin_bit_cast(bf16x8, (u32x4){cvtpk(st[2 * p][0], st[2 * p][1]), cvtpk(st[2 * p][2], st[2 * p][3]), cvtpk(st[2 * p + 1][0], st[2 * p + 1][1]), cvtpk(st[2 * p + 1][2], st[2 * p + 1][3])});
;         f32x4 o[4]; float ss[4] = {0.f, 0.f, 0.f, 0.f};
; #pragma unroll
;         for (int et = 0; et < 4; ++et) {
;             f32x4 acc = {0.f, 0.f, 0.f, 0.f};
;             acc = __builtin_amdgcn_mfma_f32_16x16x32_bf16(af[0], vfr[et][0], acc, 0, 0, 0);
;             acc = __builtin_amdgcn_mfma_f32_16x16x32_bf16(af[1], vfr[et][1], acc, 0, 0, 0);
;             acc = __builtin_amdgcn_mfma_f32_16x16x32_bf16(qf[it], sfr[et], acc, 0, 0, 0);
;             o[et] = acc;
; #pragma unroll
;             for (int r = 0; r < 4; ++r) ss[r] += acc[r] * acc[r];
;         }
; #pragma unroll
;         for (int r = 0; r < 4; ++r) {
;             ss[r] += swz_xor<1>(ss[r]); ss[r] += swz_xor<2>(ss[r]); ss[r] += swz_xor<4>(ss[r]); ss[r] += swz_xor<8>(ss[r]);
;             const float rs = rsqrtf(ss[r] * (1.0f / 64.0f) + EPS);
;             const int t = t0 + 16 * it + 4 * kq + r;
; #pragma unroll
;             for (int et = 0; et < 4; ++et) {
;                 const int e = 16 * et + row;
;                 const float gt = __uint_as_float((unsigned)ci.proj[(size_t)t * DINP + gcol + e] << 16);
;                 const float val = o[et][r] * rs * gn[et] * pg8::silu_f(gt);
	v_mov_b32_e32 v81, v206
	v_or_b32_e32 v212, s3, v97
	v_mov_b32_e32 v215, v211
	v_or_b32_e32 v214, 3, v212
	v_lshlrev_b64 v[216:217], 12, v[214:215]
	v_lshl_add_u64 v[216:217], s[58:59], 0, v[216:217]
	v_lshl_add_u64 v[218:219], v[216:217], 0, v[110:111]
	global_load_ushort v206, v[218:219], off offset:3424
	v_lshlrev_b32_e32 v81, 16, v81
	v_mul_f32_e32 v82, 0xbfb8aa3b, v81
	v_exp_f32_e32 v82, v82
	v_mfma_f32_16x16x32_bf16 v[72:75], v[72:75], v[128:131], 0
	v_add_f32_e32 v82, 1.0, v82
	v_rcp_f32_e32 v82, v82
	v_mfma_f32_16x16x32_bf16 v[98:101], v[12:15], v[128:131], 0
	s_nop 4
	v_cndmask_b32_e64 v86, v136, v74, s[44:45]
	v_cndmask_b32_e64 v129, v137, v75, s[46:47]
	v_mul_f32_e32 v81, v82, v81
	v_mul_f32_e32 v80, v81, v80
	v_cvt_pk_bf16_f32 v80, v80, s0
	global_store_short v[144:145], v80, off offset:1536
	v_mul_f32_e32 v82, v95, v132
	v_mul_f32_e32 v82, v161, v82
	v_cvt_pk_bf16_f32 v129, v86, v129
	v_mfma_f32_16x16x32_bf16 v[88:91], v[8:11], v[68:71], 0
	v_cvt_pk_bf16_f32 v130, v98, v99
	v_cvt_pk_bf16_f32 v131, v100, v101
	s_waitcnt vmcnt(63)
	v_mov_b32_e32 v80, v207
	global_load_ushort v207, v[218:219], off offset:3456
	v_lshlrev_b32_e32 v80, 16, v80
	v_mul_f32_e32 v81, 0xbfb8aa3b, v80
	v_exp_f32_e32 v81, v81
	v_mfma_f32_16x16x32_bf16 v[102:105], v[76:79], v[68:71], 0
	s_nop 0
	v_cvt_pk_bf16_f32 v88, v88, v89
	v_cvt_pk_bf16_f32 v89, v90, v91
	v_add_f32_e32 v81, 1.0, v81
	v_rcp_f32_e32 v81, v81
	s_nop 0
	v_mul_f32_e32 v80, v81, v80
	v_mul_f32_e32 v80, v82, v80
	v_cvt_pk_bf16_f32 v80, v80, s0
	global_store_short v[144:145], v80, off offset:1568
	v_cndmask_b32_e32 v81, v134, v72, vcc
	v_cndmask_b32_e64 v82, v73, v135, s[42:43]
	v_cvt_pk_bf16_f32 v128, v81, v82
	v_cvt_pk_bf16_f32 v90, v102, v103
	v_cvt_pk_bf16_f32 v91, v104, v105
	s_waitcnt vmcnt(63)
	v_mov_b32_e32 v80, v208
	global_load_ushort v208, v[218:219], off offset:3488
	v_lshlrev_b32_e32 v82, 16, v80
	v_mul_f32_e32 v80, 0xbfb8aa3b, v82
	v_exp_f32_e32 v86, v80
	v_lshl_add_u64 v[80:81], v[84:85], 0, v[112:113]
	v_mul_f32_e32 v85, v87, v132
	v_mul_f32_e32 v85, v160, v85
	v_add_f32_e32 v84, 1.0, v86
	v_rcp_f32_e32 v84, v84
	v_mfma_f32_16x16x32_bf16 v[102:105], v[88:91], v[28:31], 0
	v_mul_f32_e32 v82, v84, v82
	v_mul_f32_e32 v82, v85, v82
	v_cvt_pk_bf16_f32 v82, v82, s0
	global_store_short v[144:145], v82, off offset:1600
	v_mfma_f32_16x16x32_bf16 v[92:95], v[88:91], v[44:47], 0
	v_mov_b32_e32 v81, v211
	s_waitcnt vmcnt(63)
	v_mov_b32_e32 v82, v209
	v_lshlrev_b32_e32 v212, 1, v177
	v_mov_b32_e32 v213, v211
	v_or_b32_e32 v214, s3, v97
	v_mov_b32_e32 v217, v211
	v_or_b32_e32 v216, 3, v214
	v_lshlrev_b64 v[218:219], 12, v[216:217]
	v_lshl_add_u64 v[218:219], s[58:59], 0, v[218:219]
	v_lshl_add_u64 v[216:217], v[218:219], 0, v[212:213]
	global_load_ushort v209, v[216:217], off offset:3424
	v_lshlrev_b32_e32 v82, 16, v82
	v_mfma_f32_16x16x32_bf16 v[72:75], v[88:91], v[56:59], 0
	v_mul_f32_e32 v84, 0xbfb8aa3b, v82
	v_mfma_f32_16x16x32_bf16 v[88:91], v[88:91], v[60:63], 0
	v_mfma_f32_16x16x32_bf16 v[98:101], v[128:131], v[20:23], v[102:105]
	v_mfma_f32_16x16x32_bf16 v[92:95], v[128:131], v[32:35], v[92:95]
	v_mfma_f32_16x16x32_bf16 v[102:105], v[128:131], v[48:51], v[88:91]
	v_mfma_f32_16x16x32_bf16 v[88:91], v[68:71], v[24:27], v[98:101]
	s_nop 4
	v_exp_f32_e32 v100, v84
	v_mfma_f32_16x16x32_bf16 v[84:87], v[68:71], v[16:19], v[92:95]
	s_nop 2
	v_add_f32_e32 v94, 1.0, v100
	v_rcp_f32_e32 v94, v94
	v_mfma_f32_16x16x32_bf16 v[72:75], v[128:131], v[52:55], v[72:75]
	v_or_b32_e32 v128, s4, v97
	v_lshlrev_b32_e32 v80, 12, v128
	v_mul_f32_e32 v82, v94, v82
	v_mul_f32_e32 v82, v83, v82
	v_lshl_add_u64 v[80:81], s[58:59], 0, v[80:81]
	v_lshl_add_u64 v[92:93], v[142:143], 0, v[112:113]
	v_cvt_pk_bf16_f32 v82, v82, s0
	v_lshl_add_u64 v[98:99], v[80:81], 0, v[110:111]
	global_store_short v[92:93], v82, off offset:1536
	v_mfma_f32_16x16x32_bf16 v[72:75], v[68:71], v[36:39], v[72:75]
	v_mov_b32_e32 v82, v88
	v_mov_b32_e32 v83, v84
	v_mov_b32_e32 v92, v89
	v_mfma_f32_16x16x32_bf16 v[68:71], v[68:71], v[40:43], v[102:105]
	v_mov_b32_e32 v93, v85
	s_nop 2
	v_mov_b32_e32 v94, v72
	v_mov_b32_e32 v100, v73
	v_pk_mul_f32 v[82:83], v[82:83], v[82:83]
	v_pk_mul_f32 v[92:93], v[92:93], v[92:93]
	v_mov_b32_e32 v95, v68
	v_mov_b32_e32 v101, v69
	v_pk_mul_f32 v[94:95], v[94:95], v[94:95]
	v_pk_mul_f32 v[100:101], v[100:101], v[100:101]
	v_mov_b32_e32 v102, v92
	v_mov_b32_e32 v103, v82
	v_mov_b32_e32 v82, v93
	v_mov_b32_e32 v92, v100
	v_mov_b32_e32 v93, v94
	v_pk_add_f32 v[82:83], v[102:103], v[82:83]
	v_mov_b32_e32 v94, v101
	v_pk_add_f32 v[82:83], v[82:83], v[92:93]
	v_lshl_add_u64 v[80:81], v[80:81], 0, v[112:113]
	v_pk_add_f32 v[82:83], v[82:83], v[94:95]
	ds_swizzle_b32 v93, v83 offset:swizzle(SWAP,1)
	ds_swizzle_b32 v92, v82 offset:swizzle(SWAP,1)
	v_mov_b32_e32 v95, v211
	v_lshlrev_b32_e32 v94, 11, v128
	s_waitcnt lgkmcnt(0)
	v_pk_add_f32 v[82:83], v[82:83], v[92:93]
	ds_swizzle_b32 v93, v83 offset:swizzle(SWAP,2)
	ds_swizzle_b32 v92, v82 offset:swizzle(SWAP,2)
	s_waitcnt lgkmcnt(0)
	v_pk_add_f32 v[82:83], v[82:83], v[92:93]
	ds_swizzle_b32 v93, v83 offset:swizzle(SWAP,4)
	ds_swizzle_b32 v92, v82 offset:swizzle(SWAP,4)
	s_waitcnt lgkmcnt(0)
	v_pk_add_f32 v[82:83], v[82:83], v[92:93]
	ds_swizzle_b32 v93, v83 offset:swizzle(SWAP,8)
	ds_swizzle_b32 v92, v82 offset:swizzle(SWAP,8)
	s_waitcnt lgkmcnt(0)
	v_pk_add_f32 v[82:83], v[82:83], v[92:93]
	s_nop 0
	v_pk_fma_f32 v[82:83], v[82:83], s[6:7], v[116:117] op_sel_hi:[1,0,0]
	s_waitcnt vmcnt(63)
; __device__ __forceinline__ unsigned cvtpk(float lo, float hi) { f32x2_t v = {lo, hi}; bf16x2_t b = __builtin_convertvector(v, bf16x2_t); return __builtin_bit_cast(unsigned, b); }
; template <int X> __device__ __forceinline__ float swz_xor(float v) { return __int_as_float(__builtin_amdgcn_ds_swizzle(__float_as_int(v), (X << 10) | 0x1F)); }
; __device__ __forceinline__ float silu_f(float g) { return g * __builtin_amdgcn_rcpf(1.0f + __expf(-g)); }
; template <bool GLA>
; __device__ __forceinline__ void chunk_pass_c(const ChunkIn& ci, const float* wgl, int unit, unsigned char* wl, int lane, const float* Sb, const float* ng, bf16_t* omix) {
;     ...
;         f32x4 o[4]; float ss[4] = {0.f, 0.f, 0.f, 0.f};
; #pragma unroll
;         for (int et = 0; et < 4; ++et) {
;             f32x4 acc = {0.f, 0.f, 0.f, 0.f};
;             acc = __builtin_amdgcn_mfma_f32_16x16x32_bf16(af[0], vfr[et][0], acc, 0, 0, 0);
;             acc = __builtin_amdgcn_mfma_f32_16x16x32_bf16(af[1], vfr[et][1], acc, 0, 0, 0);
;             acc = __builtin_amdgcn_mfma_f32_16x16x32_bf16(qf[it], sfr[et], acc, 0, 0, 0);
;             o[et] = acc;
; #pragma unroll
;             for (int r = 0; r < 4; ++r) ss[r] += acc[r] * acc[r];
;         }
; #pragma unroll
;         for (int r = 0; r < 4; ++r) {
;             ss[r] += swz_xor<1>(ss[r]); ss[r] += swz_xor<2>(ss[r]); ss[r] += swz_xor<4>(ss[r]); ss[r] += swz_xor<8>(ss[r]);
;             const float rs = rsqrtf(ss[r] * (1.0f / 64.0f) + EPS);
;             const int t = t0 + 16 * it + 4 * kq + r;
; #pragma unroll
;             for (int et = 0; et < 4; ++et) {
;                 const int e = 16 * et + row;
;                 const float gt = __uint_as_float((unsigned)ci.proj[(size_t)t * DINP + gcol + e] << 16);
;                 const float val = o[et][r] * rs * gn[et] * pg8::silu_f(gt);
;                 omix[(size_t)t * 1024 + ocol + e] = (bf16_t)(cvtpk(val, 0.f) & 0xffffu);
;             }
;         }
	v_mov_b32_e32 v129, v178
	v_lshlrev_b32_e32 v100, 16, v129
	v_mul_f32_e32 v92, 0x4b800000, v83
	v_cmp_gt_f32_e64 s[48:49], s96, v83
	s_nop 1
	v_cndmask_b32_e64 v83, v83, v92, s[48:49]
	v_mul_f32_e32 v92, 0xbfb8aa3b, v100
	v_exp_f32_e32 v101, v92
	v_rsq_f32_e32 v83, v83
	v_lshl_add_u64 v[92:93], s[60:61], 0, v[94:95]
	v_lshl_add_u64 v[94:95], v[92:93], 0, v[110:111]
	v_add_f32_e32 v101, 1.0, v101
	v_rcp_f32_e32 v101, v101
	v_mul_f32_e32 v102, 0x45800000, v83
	v_cndmask_b32_e64 v83, v83, v102, s[48:49]
	v_mul_f32_e32 v88, v88, v83
	v_mul_f32_e32 v88, v115, v88
	v_mul_f32_e32 v100, v101, v100
	v_mul_f32_e32 v88, v100, v88
	v_cvt_pk_bf16_f32 v88, v88, s0
	global_store_short v[94:95], v88, off offset:1536
	v_mul_f32_e32 v84, v84, v83
	v_mul_f32_e32 v84, v161, v84
	v_mul_f32_e32 v72, v72, v83
	v_mul_f32_e32 v72, v160, v72
	v_mul_f32_e32 v68, v68, v83
	v_mul_f32_e32 v68, v159, v68
	v_lshl_add_u64 v[92:93], v[92:93], 0, v[112:113]
	v_cmp_gt_f32_e64 s[48:49], s96, v82
	s_waitcnt vmcnt(62)
	v_mov_b32_e32 v88, v179
	v_lshlrev_b32_e32 v88, 16, v88
	v_mul_f32_e32 v100, 0xbfb8aa3b, v88
	v_exp_f32_e32 v100, v100
	s_nop 0
	v_add_f32_e32 v100, 1.0, v100
	v_rcp_f32_e32 v100, v100
	s_nop 0
	v_mul_f32_e32 v88, v100, v88
	v_mul_f32_e32 v84, v88, v84
	v_cvt_pk_bf16_f32 v84, v84, s0
	global_store_short v[94:95], v84, off offset:1568
	s_waitcnt vmcnt(61)
	v_mov_b32_e32 v84, v180
	v_lshlrev_b32_e32 v84, 16, v84
	v_mul_f32_e32 v88, 0xbfb8aa3b, v84
	v_exp_f32_e32 v88, v88
	s_nop 0
	v_add_f32_e32 v88, 1.0, v88
	v_rcp_f32_e32 v88, v88
	s_nop 0
	v_mul_f32_e32 v84, v88, v84
	v_mul_f32_e32 v72, v72, v84
	v_cvt_pk_bf16_f32 v72, v72, s0
	global_store_short v[94:95], v72, off offset:1600
	v_or_b32_e32 v84, 1, v128
	v_mov_b32_e32 v81, v211
	s_waitcnt vmcnt(60)
	v_mov_b32_e32 v72, v181
	v_lshlrev_b32_e32 v72, 16, v72
	v_mul_f32_e32 v80, 0xbfb8aa3b, v72
	v_exp_f32_e32 v88, v80
	v_lshlrev_b32_e32 v80, 12, v84
	v_lshl_add_u64 v[80:81], s[58:59], 0, v[80:81]
	v_lshl_add_u64 v[94:95], v[80:81], 0, v[110:111]
	v_add_f32_e32 v88, 1.0, v88
	v_rcp_f32_e32 v88, v88
	v_lshl_add_u64 v[80:81], v[80:81], 0, v[112:113]
	v_mul_f32_e32 v72, v88, v72
	v_mul_f32_e32 v68, v68, v72
	v_cvt_pk_bf16_f32 v68, v68, s0
	global_store_short v[92:93], v68, off offset:1536
	v_mul_f32_e32 v72, 0x4b800000, v82
	v_cndmask_b32_e64 v72, v82, v72, s[48:49]
	v_lshlrev_b32_e32 v92, 11, v84
	v_rsq_f32_e32 v72, v72
	v_mov_b32_e32 v93, v211
	v_mul_f32_e32 v88, 0x45800000, v72
	v_cndmask_b32_e64 v88, v72, v88, s[48:49]
	v_mul_f32_e32 v72, v89, v88
	v_mul_f32_e32 v72, v115, v72
	v_mul_f32_e32 v73, v73, v88
	v_mul_f32_e32 v73, v160, v73
	v_mul_f32_e32 v69, v69, v88
	v_mul_f32_e32 v69, v159, v69
	v_mov_b32_e32 v89, v71
	s_waitcnt vmcnt(59)
	v_mov_b32_e32 v68, v182
	v_lshlrev_b32_e32 v68, 16, v68
	v_mul_f32_e32 v82, 0xbfb8aa3b, v68
	v_exp_f32_e32 v84, v82
	v_lshl_add_u64 v[82:83], s[60:61], 0, v[92:93]
	v_lshl_add_u64 v[92:93], v[82:83], 0, v[110:111]
	v_add_f32_e32 v84, 1.0, v84
	v_rcp_f32_e32 v84, v84
	s_nop 0
	v_mul_f32_e32 v68, v84, v68
	v_mul_f32_e32 v68, v68, v72
	v_cvt_pk_bf16_f32 v68, v68, s0
	global_store_short v[92:93], v68, off offset:1536
	v_mul_f32_e32 v84, v85, v88
	v_mul_f32_e32 v84, v161, v84
	v_mov_b32_e32 v85, v70
	v_mov_b32_e32 v88, v75
	v_pk_mul_f32 v[88:89], v[88:89], v[88:89]
	s_waitcnt vmcnt(58)
	v_mov_b32_e32 v68, v183
	v_lshlrev_b32_e32 v68, 16, v68
	v_mul_f32_e32 v72, 0xbfb8aa3b, v68
	v_exp_f32_e32 v72, v72
	s_nop 0
	v_add_f32_e32 v72, 1.0, v72
	v_rcp_f32_e32 v72, v72
	s_nop 0
	v_mul_f32_e32 v68, v72, v68
	v_mul_f32_e32 v68, v84, v68
	v_cvt_pk_bf16_f32 v68, v68, s0
	global_store_short v[92:93], v68, off offset:1568
	v_or_b32_e32 v94, 2, v128
	s_waitcnt vmcnt(57)
	v_mov_b32_e32 v68, v184
	v_lshlrev_b32_e32 v68, 16, v68
	v_mul_f32_e32 v72, 0xbfb8aa3b, v68
	v_exp_f32_e32 v72, v72
	s_nop 0
	v_add_f32_e32 v72, 1.0, v72
	v_rcp_f32_e32 v72, v72
	s_nop 0
	v_mul_f32_e32 v68, v72, v68
	v_mul_f32_e32 v68, v73, v68
	v_cvt_pk_bf16_f32 v68, v68, s0
	global_store_short v[92:93], v68, off offset:1600
	v_lshl_add_u64 v[80:81], v[82:83], 0, v[112:113]
	v_mov_b32_e32 v73, v211
	s_waitcnt vmcnt(56)
	v_mov_b32_e32 v68, v185
	v_lshlrev_b32_e32 v68, 16, v68
	v_mul_f32_e32 v72, 0xbfb8aa3b, v68
	v_exp_f32_e32 v84, v72
	v_lshlrev_b32_e32 v72, 12, v94
	v_lshl_add_u64 v[72:73], s[58:59], 0, v[72:73]
	v_add_f32_e32 v82, 1.0, v84
	v_rcp_f32_e32 v84, v82
	v_lshl_add_u64 v[82:83], v[72:73], 0, v[110:111]
	v_lshl_add_u64 v[72:73], v[72:73], 0, v[112:113]
	v_mul_f32_e32 v68, v84, v68
	v_mul_f32_e32 v68, v69, v68
	v_cvt_pk_bf16_f32 v68, v68, s0
	global_store_short v[80:81], v68, off offset:1536
	v_mov_b32_e32 v68, v90
	v_mov_b32_e32 v69, v86
	v_mov_b32_e32 v80, v91
	v_mov_b32_e32 v81, v87
	v_mov_b32_e32 v84, v74
	v_pk_mul_f32 v[68:69], v[68:69], v[68:69]
	v_pk_mul_f32 v[80:81], v[80:81], v[80:81]
	v_pk_mul_f32 v[84:85], v[84:85], v[84:85]
	v_mov_b32_e32 v92, v80
	v_mov_b32_e32 v93, v68
	v_mov_b32_e32 v68, v81
	v_mov_b32_e32 v80, v88
	v_mov_b32_e32 v81, v84
	v_pk_add_f32 v[68:69], v[92:93], v[68:69]
	v_mov_b32_e32 v84, v89
	v_pk_add_f32 v[68:69], v[68:69], v[80:81]
	v_and_b32_e32 v93, 0xffff0000, v107
	v_pk_add_f32 v[68:69], v[68:69], v[84:85]
	ds_swizzle_b32 v81, v69 offset:swizzle(SWAP,1)
	ds_swizzle_b32 v80, v68 offset:swizzle(SWAP,1)
	v_mov_b32_e32 v85, v211
	v_lshlrev_b32_e32 v84, 11, v94
	s_waitcnt lgkmcnt(0)
	v_pk_add_f32 v[68:69], v[68:69], v[80:81]
	ds_swizzle_b32 v81, v69 offset:swizzle(SWAP,2)
	ds_swizzle_b32 v80, v68 offset:swizzle(SWAP,2)
	s_waitcnt lgkmcnt(0)
	v_pk_add_f32 v[68:69], v[68:69], v[80:81]
	ds_swizzle_b32 v81, v69 offset:swizzle(SWAP,4)
	ds_swizzle_b32 v80, v68 offset:swizzle(SWAP,4)
	s_waitcnt lgkmcnt(0)
; template <bool GLA>
; __device__ __forceinline__ void chunk_pass_c(const ChunkIn& ci, const float* wgl, int unit, unsigned char* wl, int lane, const float* Sb, const float* ng, bf16_t* omix) {
;     ...
;     for (int it = 0; it < 4; ++it) {
;         f32x4 st[4];
; #pragma unroll
;         for (int jt = 0; jt < 4; ++jt) {
;             const f32x4 z = {0.f, 0.f, 0.f, 0.f};
;             if (jt < it) st[jt] = __builtin_amdgcn_mfma_f32_16x16x32_bf16(kf[jt], qf[it], z, 0, 0, 0);
;             else if (jt > it) st[jt] = __builtin_amdgcn_mfma_f32_16x16x32_bf16(kb[jt], qb[it], z, 0, 0, 0);
;             else {
;                 const f32x4 lo = __builtin_amdgcn_mfma_f32_16x16x32_bf16(kf[jt], qf[it], z, 0, 0, 0), up = __builtin_amdgcn_mfma_f32_16x16x32_bf16(kb[jt], qb[it], z, 0, 0, 0);
; #pragma unroll
;                 for (int r = 0; r < 4; ++r) st[jt][r] = (4 * kq + r <= row) ? lo[r] : up[r];
;             }
;         }
;         bf16x8 af[2];
; #pragma unroll
;         for (int p = 0; p < 2; ++p)
;             af[p] = __builtin_bit_cast(bf16x8, (u32x4){cvtpk(st[2 * p][0], st[2 * p][1]), cvtpk(st[2 * p][2], st[2 * p][3]), cvtpk(st[2 * p + 1][0], st[2 * p + 1][1]), cvtpk(st[2 * p + 1][2], st[2 * p + 1][3])});
;         f32x4 o[4]; float ss[4] = {0.f, 0.f, 0.f, 0.f};
; #pragma unroll
;         for (int et = 0; et < 4; ++et) {
;             f32x4 acc = {0.f, 0.f, 0.f, 0.f};
;             acc = __builtin_amdgcn_mfma_f32_16x16x32_bf16(af[0], vfr[et][0], acc, 0, 0, 0);
;             acc = __builtin_amdgcn_mfma_f32_16x16x32_bf16(af[1], vfr[et][1], acc, 0, 0, 0);
;             acc = __builtin_amdgcn_mfma_f32_16x16x32_bf16(qf[it], sfr[et], acc, 0, 0, 0);
;             o[et] = acc;
; #pragma unroll
;             for (int r = 0; r < 4; ++r) ss[r] += acc[r] * acc[r];
;         }
; #pragma unroll
;         for (int r = 0; r < 4; ++r) {
;             ss[r] += swz_xor<1>(ss[r]); ss[r] += swz_xor<2>(ss[r]); ss[r] += swz_xor<4>(ss[r]); ss[r] += swz_xor<8>(ss[r]);
;             const float rs = rsqrtf(ss[r] * (1.0f / 64.0f) + EPS);
;             const int t = t0 + 16 * it + 4 * kq + r;
; #pragma unroll
;             for (int et = 0; et < 4; ++et) {
;                 const int e = 16 * et + row;
;                 const float gt = __uint_as_float((unsigned)ci.proj[(size_t)t * DINP + gcol + e] << 16);
;                 const float val = o[et][r] * rs * gn[et] * pg8::silu_f(gt);
	v_pk_add_f32 v[68:69], v[68:69], v[80:81]
	ds_swizzle_b32 v81, v69 offset:swizzle(SWAP,8)
	ds_swizzle_b32 v80, v68 offset:swizzle(SWAP,8)
	s_waitcnt lgkmcnt(0)
	v_pk_add_f32 v[68:69], v[68:69], v[80:81]
	s_nop 0
	v_pk_fma_f32 v[68:69], v[68:69], s[6:7], v[116:117] op_sel_hi:[1,0,0]
	s_waitcnt vmcnt(55)
	v_mov_b32_e32 v95, v186
	v_lshlrev_b32_e32 v88, 16, v95
	v_mul_f32_e32 v80, 0x4b800000, v69
	v_cmp_gt_f32_e64 s[48:49], s96, v69
	s_nop 1
	v_cndmask_b32_e64 v69, v69, v80, s[48:49]
	v_mul_f32_e32 v80, 0xbfb8aa3b, v88
	v_exp_f32_e32 v89, v80
	v_rsq_f32_e32 v69, v69
	v_lshl_add_u64 v[80:81], s[60:61], 0, v[84:85]
	v_lshl_add_u64 v[84:85], v[80:81], 0, v[110:111]
	v_add_f32_e32 v89, 1.0, v89
	v_rcp_f32_e32 v89, v89
	v_mul_f32_e32 v92, 0x45800000, v69
	v_cndmask_b32_e64 v69, v69, v92, s[48:49]
	v_mul_f32_e32 v90, v90, v69
	v_mul_f32_e32 v90, v115, v90
	v_mul_f32_e32 v88, v89, v88
	v_mul_f32_e32 v88, v88, v90
	v_cvt_pk_bf16_f32 v88, v88, s0
	global_store_short v[84:85], v88, off offset:1536
	v_mul_f32_e32 v86, v86, v69
	v_mul_f32_e32 v86, v161, v86
	v_mul_f32_e32 v74, v74, v69
	v_mul_f32_e32 v74, v160, v74
	v_mul_f32_e32 v69, v70, v69
	v_mul_f32_e32 v69, v159, v69
	v_lshl_add_u64 v[80:81], v[80:81], 0, v[112:113]
	v_cmp_gt_f32_e64 s[48:49], s96, v68
	v_lshlrev_b32_e32 v90, 16, v109
	v_lshlrev_b32_e32 v92, 16, v107
	s_waitcnt vmcnt(54)
	v_mov_b32_e32 v88, v187
	v_lshlrev_b32_e32 v88, 16, v88
	v_mul_f32_e32 v89, 0xbfb8aa3b, v88
	v_exp_f32_e32 v89, v89
	s_nop 0
	v_add_f32_e32 v89, 1.0, v89
	v_rcp_f32_e32 v89, v89
	s_nop 0
	v_mul_f32_e32 v88, v89, v88
	v_mul_f32_e32 v86, v86, v88
	v_cvt_pk_bf16_f32 v86, v86, s0
	global_store_short v[84:85], v86, off offset:1568
	s_waitcnt vmcnt(53)
	v_mov_b32_e32 v82, v188
	v_lshlrev_b32_e32 v82, 16, v82
	v_mul_f32_e32 v83, 0xbfb8aa3b, v82
	v_exp_f32_e32 v83, v83
	s_nop 0
	v_add_f32_e32 v83, 1.0, v83
	v_rcp_f32_e32 v83, v83
	s_nop 0
	v_mul_f32_e32 v82, v83, v82
	v_mul_f32_e32 v74, v74, v82
	v_cvt_pk_bf16_f32 v74, v74, s0
	global_store_short v[84:85], v74, off offset:1600
	v_or_b32_e32 v74, 3, v128
	v_mov_b32_e32 v73, v211
	s_waitcnt vmcnt(52)
	v_mov_b32_e32 v72, v189
	v_lshlrev_b32_e32 v82, 16, v72
	v_mul_f32_e32 v72, 0xbfb8aa3b, v82
	v_exp_f32_e32 v83, v72
	v_lshlrev_b32_e32 v72, 12, v74
	v_lshl_add_u64 v[72:73], s[58:59], 0, v[72:73]
	v_lshl_add_u64 v[84:85], v[72:73], 0, v[110:111]
	v_add_f32_e32 v83, 1.0, v83
	v_rcp_f32_e32 v83, v83
	s_nop 0
	v_mul_f32_e32 v70, v83, v82
	v_mul_f32_e32 v69, v69, v70
	v_cvt_pk_bf16_f32 v69, v69, s0
	global_store_short v[80:81], v69, off offset:1536
	v_mul_f32_e32 v70, 0x4b800000, v68
	v_lshlrev_b32_e32 v80, 11, v74
	v_cndmask_b32_e64 v68, v68, v70, s[48:49]
	v_rsq_f32_e32 v70, v68
	v_mov_b32_e32 v81, v211
	v_and_b32_e32 v83, 0xffff0000, v106
	s_waitcnt vmcnt(51)
	v_mov_b32_e32 v69, v190
	v_lshlrev_b32_e32 v74, 16, v69
	v_mul_f32_e32 v68, 0xbfb8aa3b, v74
	v_exp_f32_e32 v82, v68
	v_lshl_add_u64 v[68:69], s[60:61], 0, v[80:81]
	v_mul_f32_e32 v80, 0x45800000, v70
	v_cndmask_b32_e64 v86, v70, v80, s[48:49]
	v_add_f32_e32 v81, 1.0, v82
	v_rcp_f32_e32 v81, v81
	v_mul_f32_e32 v70, v91, v86
	v_mul_f32_e32 v70, v115, v70
	v_lshl_add_u64 v[88:89], v[68:69], 0, v[110:111]
	v_mul_f32_e32 v74, v81, v74
	v_mul_f32_e32 v70, v74, v70
	v_cvt_pk_bf16_f32 v70, v70, s0
	global_store_short v[88:89], v70, off offset:1536
	v_lshlrev_b32_e32 v80, 16, v108
	v_and_b32_e32 v81, 0xffff0000, v108
	v_lshlrev_b32_e32 v82, 16, v106
	v_and_b32_e32 v91, 0xffff0000, v109
	v_pk_mul_f32 v[94:95], v[4:5], v[80:81]
	v_pk_mul_f32 v[4:5], v[4:5], v[82:83]
	v_pk_mul_f32 v[98:99], v[6:7], v[90:91]
	v_pk_mul_f32 v[6:7], v[6:7], v[92:93]
	v_pk_fma_f32 v[82:83], v[0:1], v[82:83], v[94:95]
	v_pk_fma_f32 v[0:1], v[0:1], v[80:81], v[4:5] neg_lo:[0,0,1] neg_hi:[0,0,1]
	v_pk_fma_f32 v[4:5], v[2:3], v[92:93], v[98:99]
	v_pk_fma_f32 v[2:3], v[2:3], v[90:91], v[6:7] neg_lo:[0,0,1] neg_hi:[0,0,1]
	v_mul_f32_e32 v70, 0xbfb8aa3b, v162
	v_pk_mul_f32 v[80:81], v[82:83], s[8:9] op_sel_hi:[1,0]
	v_pk_mul_f32 v[82:83], v[0:1], s[8:9] op_sel_hi:[1,0]
	v_pk_mul_f32 v[94:95], v[4:5], s[8:9] op_sel_hi:[1,0]
	v_pk_mul_f32 v[98:99], v[2:3], s[8:9] op_sel_hi:[1,0]
	v_exp_f32_e32 v70, v70
	v_pk_mul_f32 v[0:1], v[118:119], v[82:83] op_sel_hi:[0,1]
	v_pk_mul_f32 v[2:3], v[118:119], v[80:81] op_sel_hi:[0,1]
	v_pk_mul_f32 v[4:5], v[118:119], v[98:99] op_sel_hi:[0,1]
	v_pk_mul_f32 v[6:7], v[118:119], v[94:95] op_sel_hi:[0,1]
	v_cvt_pk_bf16_f32 v0, v0, v1
	v_cvt_pk_bf16_f32 v1, v4, v5
	v_cvt_pk_bf16_f32 v2, v2, v3
	v_cvt_pk_bf16_f32 v3, v6, v7
	v_pk_mul_f32 v[90:91], v[70:71], v[122:123] op_sel_hi:[0,1]
	v_pk_mul_f32 v[92:93], v[70:71], v[120:121] op_sel_hi:[0,1]
	v_mfma_f32_16x16x32_bf16 v[4:7], v[8:11], v[0:3], 0
	v_mul_f32_e64 v100, v70, v126
	v_mul_f32_e64 v101, v70, v127
	v_pk_mul_f32 v[102:103], v[70:71], v[124:125] op_sel_hi:[0,1]
	v_pk_mul_f32 v[82:83], v[70:71], v[82:83] op_sel_hi:[0,1]
	v_pk_mul_f32 v[104:105], v[70:71], v[80:81] op_sel_hi:[0,1]
	v_cvt_pk_bf16_f32 v8, v90, v91
	v_cvt_pk_bf16_f32 v10, v92, v93
	v_pk_mul_f32 v[90:91], v[70:71], v[98:99] op_sel_hi:[0,1]
	v_pk_mul_f32 v[92:93], v[70:71], v[94:95] op_sel_hi:[0,1]
	v_cvt_pk_bf16_f32 v4, v4, v5
	v_cvt_pk_bf16_f32 v5, v6, v7
	v_mfma_f32_16x16x32_bf16 v[76:79], v[76:79], v[0:3], 0
	v_cvt_pk_bf16_f32 v9, v100, v101
	v_cvt_pk_bf16_f32 v11, v102, v103
	v_cvt_pk_bf16_f32 v80, v82, v83
	v_cvt_pk_bf16_f32 v81, v90, v91
	v_cvt_pk_bf16_f32 v82, v104, v105
	s_nop 2
	v_cvt_pk_bf16_f32 v6, v76, v77
	v_mul_f32_e32 v76, v87, v86
	v_mul_f32_e32 v76, v161, v76
	v_cvt_pk_bf16_f32 v83, v92, v93
	v_mfma_f32_16x16x32_bf16 v[8:11], v[8:11], v[0:3], 0
	s_waitcnt vmcnt(50)
; template <bool GLA>
; __device__ __forceinline__ void chunk_pass_c(const ChunkIn& ci, const float* wgl, int unit, unsigned char* wl, int lane, const float* Sb, const float* ng, bf16_t* omix) {
;     ...
;     for (int it = 0; it < 4; ++it) {
;         f32x4 st[4];
; #pragma unroll
;         for (int jt = 0; jt < 4; ++jt) {
;             const f32x4 z = {0.f, 0.f, 0.f, 0.f};
;             if (jt < it) st[jt] = __builtin_amdgcn_mfma_f32_16x16x32_bf16(kf[jt], qf[it], z, 0, 0, 0);
;             else if (jt > it) st[jt] = __builtin_amdgcn_mfma_f32_16x16x32_bf16(kb[jt], qb[it], z, 0, 0, 0);
;             else {
;                 const f32x4 lo = __builtin_amdgcn_mfma_f32_16x16x32_bf16(kf[jt], qf[it], z, 0, 0, 0), up = __builtin_amdgcn_mfma_f32_16x16x32_bf16(kb[jt], qb[it], z, 0, 0, 0);
; #pragma unroll
;                 for (int r = 0; r < 4; ++r) st[jt][r] = (4 * kq + r <= row) ? lo[r] : up[r];
;             }
;         }
;         bf16x8 af[2];
; #pragma unroll
;         for (int p = 0; p < 2; ++p)
;             af[p] = __builtin_bit_cast(bf16x8, (u32x4){cvtpk(st[2 * p][0], st[2 * p][1]), cvtpk(st[2 * p][2], st[2 * p][3]), cvtpk(st[2 * p + 1][0], st[2 * p + 1][1]), cvtpk(st[2 * p + 1][2], st[2 * p + 1][3])});
;         f32x4 o[4]; float ss[4] = {0.f, 0.f, 0.f, 0.f};
; #pragma unroll
;         for (int et = 0; et < 4; ++et) {
;             f32x4 acc = {0.f, 0.f, 0.f, 0.f};
;             acc = __builtin_amdgcn_mfma_f32_16x16x32_bf16(af[0], vfr[et][0], acc, 0, 0, 0);
;             acc = __builtin_amdgcn_mfma_f32_16x16x32_bf16(af[1], vfr[et][1], acc, 0, 0, 0);
;             acc = __builtin_amdgcn_mfma_f32_16x16x32_bf16(qf[it], sfr[et], acc, 0, 0, 0);
;             o[et] = acc;
; #pragma unroll
;             for (int r = 0; r < 4; ++r) ss[r] += acc[r] * acc[r];
;         }
; #pragma unroll
;         for (int r = 0; r < 4; ++r) {
;             ss[r] += swz_xor<1>(ss[r]); ss[r] += swz_xor<2>(ss[r]); ss[r] += swz_xor<4>(ss[r]); ss[r] += swz_xor<8>(ss[r]);
;             const float rs = rsqrtf(ss[r] * (1.0f / 64.0f) + EPS);
;             const int t = t0 + 16 * it + 4 * kq + r;
; #pragma unroll
;             for (int et = 0; et < 4; ++et) {
;                 const int e = 16 * et + row;
;                 const float gt = __uint_as_float((unsigned)ci.proj[(size_t)t * DINP + gcol + e] << 16);
;                 const float val = o[et][r] * rs * gn[et] * pg8::silu_f(gt);
	v_mov_b32_e32 v74, v191
	v_lshlrev_b32_e32 v70, 16, v74
	v_mul_f32_e32 v7, 0xbfb8aa3b, v70
	v_exp_f32_e32 v74, v7
	v_mfma_f32_16x16x32_bf16 v[12:15], v[12:15], v[80:83], 0
	v_cvt_pk_bf16_f32 v7, v78, v79
	v_add_f32_e32 v74, 1.0, v74
	v_rcp_f32_e32 v74, v74
	v_mfma_f32_16x16x32_bf16 v[64:67], v[64:67], v[0:3], 0
	s_nop 3
	v_cndmask_b32_e64 v15, v11, v15, s[46:47]
	v_cndmask_b32_e64 v77, v10, v14, s[44:45]
	v_mul_f32_e32 v70, v74, v70
	v_mul_f32_e32 v70, v76, v70
	v_cvt_pk_bf16_f32 v70, v70, s0
	global_store_short v[88:89], v70, off offset:1568
	v_cndmask_b32_e32 v74, v8, v12, vcc
	v_cndmask_b32_e64 v76, v13, v9, s[42:43]
	v_cvt_pk_bf16_f32 v12, v64, v65
	v_cvt_pk_bf16_f32 v13, v66, v67
	v_cvt_pk_bf16_f32 v14, v74, v76
	v_cvt_pk_bf16_f32 v15, v77, v15
	v_mfma_f32_16x16x32_bf16 v[28:31], v[4:7], v[28:31], 0
	s_nop 0
	v_mfma_f32_16x16x32_bf16 v[28:31], v[12:15], v[20:23], v[28:31]
	s_waitcnt vmcnt(49)
	v_mov_b32_e32 v70, v192
	v_lshlrev_b32_e32 v22, 16, v70
	v_mul_f32_e32 v20, 0xbfb8aa3b, v22
	v_exp_f32_e32 v23, v20
	v_mfma_f32_16x16x32_bf16 v[44:47], v[4:7], v[44:47], 0
	v_lshl_add_u64 v[20:21], v[72:73], 0, v[112:113]
	v_add_f32_e32 v23, 1.0, v23
	v_mfma_f32_16x16x32_bf16 v[8:11], v[4:7], v[56:59], 0
	v_rcp_f32_e32 v23, v23
	v_mfma_f32_16x16x32_bf16 v[32:35], v[12:15], v[32:35], v[44:47]
	v_mfma_f32_16x16x32_bf16 v[44:47], v[12:15], v[52:55], v[8:11]
	s_nop 4
	v_mul_f32_e32 v8, v75, v86
	v_mul_f32_e32 v8, v160, v8
	v_mul_f32_e32 v9, v23, v22
	v_mul_f32_e32 v8, v8, v9
	v_cvt_pk_bf16_f32 v8, v8, s0
	global_store_short v[88:89], v8, off offset:1600
	v_mfma_f32_16x16x32_bf16 v[4:7], v[4:7], v[60:63], 0
	v_mov_b32_e32 v21, v211
	v_or_b32_e32 v20, s3, v97
	v_mfma_f32_16x16x32_bf16 v[48:51], v[12:15], v[48:51], v[4:7]
	v_mfma_f32_16x16x32_bf16 v[12:15], v[0:3], v[24:27], v[28:31]
	s_nop 3
	v_lshlrev_b64 v[4:5], 12, v[20:21]
	v_lshl_add_u64 v[22:23], s[58:59], 0, v[4:5]
	v_lshl_add_u64 v[24:25], v[22:23], 0, v[110:111]
	v_lshl_add_u64 v[22:23], v[22:23], 0, v[112:113]
	s_waitcnt vmcnt(48)
	v_mov_b32_e32 v8, v193
	v_lshlrev_b32_e32 v26, 16, v8
	v_mul_f32_e32 v4, 0xbfb8aa3b, v26
	v_exp_f32_e32 v4, v4
	v_mfma_f32_16x16x32_bf16 v[8:11], v[0:3], v[16:19], v[32:35]
	v_mul_f32_e32 v19, v71, v86
	v_mul_f32_e32 v19, v159, v19
	v_add_f32_e32 v4, 1.0, v4
	v_rcp_f32_e32 v18, v4
	v_lshl_add_u64 v[16:17], v[68:69], 0, v[112:113]
	v_mfma_f32_16x16x32_bf16 v[4:7], v[0:3], v[36:39], v[44:47]
	v_mul_f32_e32 v18, v18, v26
	v_mul_f32_e32 v18, v19, v18
	v_cvt_pk_bf16_f32 v18, v18, s0
	global_store_short v[16:17], v18, off offset:1536
	v_mfma_f32_16x16x32_bf16 v[0:3], v[0:3], v[40:43], v[48:51]
	v_mov_b32_e32 v16, v12
	v_mov_b32_e32 v17, v8
	v_mov_b32_e32 v18, v13
	v_mov_b32_e32 v19, v9
	v_mov_b32_e32 v26, v4
	s_nop 2
	v_mov_b32_e32 v27, v0
	v_mov_b32_e32 v28, v5
	v_mov_b32_e32 v29, v1
	v_pk_mul_f32 v[16:17], v[16:17], v[16:17]
	v_pk_mul_f32 v[18:19], v[18:19], v[18:19]
	v_pk_mul_f32 v[26:27], v[26:27], v[26:27]
	v_pk_mul_f32 v[28:29], v[28:29], v[28:29]
	v_mov_b32_e32 v30, v18
	v_mov_b32_e32 v31, v16
	v_mov_b32_e32 v16, v19
	v_mov_b32_e32 v18, v28
	v_mov_b32_e32 v19, v26
	v_pk_add_f32 v[16:17], v[30:31], v[16:17]
	v_mov_b32_e32 v26, v29
	v_pk_add_f32 v[16:17], v[16:17], v[18:19]
	s_nop 0
	v_pk_add_f32 v[16:17], v[16:17], v[26:27]
	ds_swizzle_b32 v19, v17 offset:swizzle(SWAP,1)
	ds_swizzle_b32 v18, v16 offset:swizzle(SWAP,1)
	v_lshlrev_b64 v[26:27], 11, v[20:21]
	s_waitcnt lgkmcnt(0)
	v_pk_add_f32 v[16:17], v[16:17], v[18:19]
	ds_swizzle_b32 v19, v17 offset:swizzle(SWAP,2)
	ds_swizzle_b32 v18, v16 offset:swizzle(SWAP,2)
	s_waitcnt lgkmcnt(0)
	v_pk_add_f32 v[16:17], v[16:17], v[18:19]
	ds_swizzle_b32 v19, v17 offset:swizzle(SWAP,4)
	ds_swizzle_b32 v18, v16 offset:swizzle(SWAP,4)
	s_waitcnt lgkmcnt(0)
	v_pk_add_f32 v[16:17], v[16:17], v[18:19]
	ds_swizzle_b32 v19, v17 offset:swizzle(SWAP,8)
	ds_swizzle_b32 v18, v16 offset:swizzle(SWAP,8)
	s_waitcnt lgkmcnt(0)
	v_pk_add_f32 v[16:17], v[16:17], v[18:19]
	s_nop 0
	v_pk_fma_f32 v[16:17], v[16:17], s[6:7], v[116:117] op_sel_hi:[1,0,0]
	s_waitcnt vmcnt(47)
	v_mov_b32_e32 v32, v194
	v_lshlrev_b32_e32 v21, 16, v32
	v_mul_f32_e32 v18, 0x4b800000, v17
	v_cmp_gt_f32_e32 vcc, s96, v17
	s_nop 1
	v_cndmask_b32_e32 v17, v17, v18, vcc
	v_mul_f32_e32 v18, 0xbfb8aa3b, v21
	v_exp_f32_e32 v28, v18
	v_rsq_f32_e32 v17, v17
	v_lshl_add_u64 v[18:19], s[60:61], 0, v[26:27]
	v_lshl_add_u64 v[26:27], v[18:19], 0, v[110:111]
	v_add_f32_e32 v28, 1.0, v28
	v_rcp_f32_e32 v28, v28
	v_mul_f32_e32 v29, 0x45800000, v17
	v_cndmask_b32_e32 v17, v17, v29, vcc
	v_mul_f32_e32 v12, v12, v17
	v_mul_f32_e32 v12, v115, v12
	v_mul_f32_e32 v21, v28, v21
	v_mul_f32_e32 v12, v21, v12
	v_cvt_pk_bf16_f32 v12, v12, s0
	global_store_short v[26:27], v12, off offset:1536
	v_mul_f32_e32 v8, v8, v17
	v_mul_f32_e32 v8, v161, v8
	v_mul_f32_e32 v4, v4, v17
	v_mul_f32_e32 v4, v160, v4
	v_mul_f32_e32 v0, v0, v17
	v_mul_f32_e32 v0, v159, v0
	v_lshl_add_u64 v[18:19], v[18:19], 0, v[112:113]
	v_cmp_gt_f32_e32 vcc, s96, v16
	s_waitcnt vmcnt(46)
	v_mov_b32_e32 v12, v195
	v_lshlrev_b32_e32 v12, 16, v12
	v_mul_f32_e32 v21, 0xbfb8aa3b, v12
	v_exp_f32_e32 v21, v21
	s_nop 0
	v_add_f32_e32 v21, 1.0, v21
	v_rcp_f32_e32 v21, v21
	s_nop 0
	v_mul_f32_e32 v12, v21, v12
	v_mul_f32_e32 v8, v12, v8
	v_cvt_pk_bf16_f32 v8, v8, s0
	global_store_short v[26:27], v8, off offset:1568
	s_waitcnt vmcnt(45)
	v_mov_b32_e32 v8, v196
	v_lshlrev_b32_e32 v8, 16, v8
	v_mul_f32_e32 v12, 0xbfb8aa3b, v8
	v_exp_f32_e32 v12, v12
	s_nop 0
	v_add_f32_e32 v12, 1.0, v12
	v_rcp_f32_e32 v12, v12
	s_nop 0
	v_mul_f32_e32 v8, v12, v8
	v_mul_f32_e32 v4, v4, v8
	v_cvt_pk_bf16_f32 v4, v4, s0
	global_store_short v[26:27], v4, off offset:1600
	v_mov_b32_e32 v23, v211
	v_or_b32_e32 v22, 1, v20
	v_lshlrev_b64 v[24:25], 12, v[22:23]
	v_lshl_add_u64 v[24:25], s[58:59], 0, v[24:25]
	v_lshl_add_u64 v[26:27], v[24:25], 0, v[110:111]
	s_waitcnt vmcnt(44)
; __device__ __forceinline__ unsigned cvtpk(float lo, float hi) { f32x2_t v = {lo, hi}; bf16x2_t b = __builtin_convertvector(v, bf16x2_t); return __builtin_bit_cast(unsigned, b); }
; template <int X> __device__ __forceinline__ float swz_xor(float v) { return __int_as_float(__builtin_amdgcn_ds_swizzle(__float_as_int(v), (X << 10) | 0x1F)); }
; __device__ __forceinline__ float silu_f(float g) { return g * __builtin_amdgcn_rcpf(1.0f + __expf(-g)); }
; template <bool GLA>
; __device__ __forceinline__ void chunk_pass_c(const ChunkIn& ci, const float* wgl, int unit, unsigned char* wl, int lane, const float* Sb, const float* ng, bf16_t* omix) {
;     ...
; #pragma unroll
;         for (int r = 0; r < 4; ++r) {
;             ss[r] += swz_xor<1>(ss[r]); ss[r] += swz_xor<2>(ss[r]); ss[r] += swz_xor<4>(ss[r]); ss[r] += swz_xor<8>(ss[r]);
;             const float rs = rsqrtf(ss[r] * (1.0f / 64.0f) + EPS);
;             const int t = t0 + 16 * it + 4 * kq + r;
; #pragma unroll
;             for (int et = 0; et < 4; ++et) {
;                 const int e = 16 * et + row;
;                 const float gt = __uint_as_float((unsigned)ci.proj[(size_t)t * DINP + gcol + e] << 16);
;                 const float val = o[et][r] * rs * gn[et] * pg8::silu_f(gt);
;                 omix[(size_t)t * 1024 + ocol + e] = (bf16_t)(cvtpk(val, 0.f) & 0xffffu);
;             }
;         }
	v_mov_b32_e32 v4, v197
	v_lshlrev_b32_e32 v4, 16, v4
	v_mul_f32_e32 v8, 0xbfb8aa3b, v4
	v_exp_f32_e32 v8, v8
	s_nop 0
	v_add_f32_e32 v8, 1.0, v8
	v_rcp_f32_e32 v8, v8
	s_nop 0
	v_mul_f32_e32 v4, v8, v4
	v_mul_f32_e32 v0, v0, v4
	v_cvt_pk_bf16_f32 v0, v0, s0
	global_store_short v[18:19], v0, off offset:1536
	v_mul_f32_e32 v4, 0x4b800000, v16
	v_cndmask_b32_e32 v4, v16, v4, vcc
	v_rsq_f32_e32 v4, v4
	v_lshlrev_b64 v[18:19], 11, v[22:23]
	v_lshl_add_u64 v[16:17], s[60:61], 0, v[18:19]
	v_lshl_add_u64 v[18:19], v[16:17], 0, v[110:111]
	v_mul_f32_e32 v12, 0x45800000, v4
	v_cndmask_b32_e32 v21, v4, v12, vcc
	v_mul_f32_e32 v4, v13, v21
	v_mul_f32_e32 v4, v115, v4
	v_mul_f32_e32 v5, v5, v21
	v_mul_f32_e32 v5, v160, v5
	v_lshl_add_u64 v[12:13], v[16:17], 0, v[112:113]
	v_mul_f32_e32 v1, v1, v21
	v_mul_f32_e32 v1, v159, v1
	v_mov_b32_e32 v22, v7
	v_mov_b32_e32 v23, v3
	v_pk_mul_f32 v[22:23], v[22:23], v[22:23]
	s_waitcnt vmcnt(43)
	v_mov_b32_e32 v0, v198
	v_lshlrev_b32_e32 v0, 16, v0
	v_mul_f32_e32 v8, 0xbfb8aa3b, v0
	v_exp_f32_e32 v8, v8
	s_nop 0
	v_add_f32_e32 v8, 1.0, v8
	v_rcp_f32_e32 v8, v8
	s_nop 0
	v_mul_f32_e32 v0, v8, v0
	v_mul_f32_e32 v0, v0, v4
	v_cvt_pk_bf16_f32 v0, v0, s0
	global_store_short v[18:19], v0, off offset:1536
	v_mul_f32_e32 v8, v9, v21
	v_mul_f32_e32 v8, v161, v8
	s_waitcnt vmcnt(42)
	v_mov_b32_e32 v0, v199
	v_lshlrev_b32_e32 v0, 16, v0
	v_mul_f32_e32 v4, 0xbfb8aa3b, v0
	v_exp_f32_e32 v4, v4
	s_nop 0
	v_add_f32_e32 v4, 1.0, v4
	v_rcp_f32_e32 v4, v4
	s_nop 0
	v_mul_f32_e32 v0, v4, v0
	v_mul_f32_e32 v0, v8, v0
	v_cvt_pk_bf16_f32 v0, v0, s0
	global_store_short v[18:19], v0, off offset:1568
	v_lshl_add_u64 v[8:9], v[24:25], 0, v[112:113]
	s_waitcnt vmcnt(41)
	v_mov_b32_e32 v0, v200
	v_lshlrev_b32_e32 v0, 16, v0
	v_mul_f32_e32 v4, 0xbfb8aa3b, v0
	v_exp_f32_e32 v4, v4
	s_nop 0
	v_add_f32_e32 v4, 1.0, v4
	v_rcp_f32_e32 v4, v4
	s_nop 0
	v_mul_f32_e32 v0, v4, v0
	v_mul_f32_e32 v0, v5, v0
	v_cvt_pk_bf16_f32 v0, v0, s0
	global_store_short v[18:19], v0, off offset:1600
	v_mov_b32_e32 v5, v211
	v_or_b32_e32 v4, 2, v20
	v_mov_b32_e32 v19, v2
	s_waitcnt vmcnt(40)
	v_mov_b32_e32 v0, v201
	v_lshlrev_b32_e32 v0, 16, v0
	v_mul_f32_e32 v8, 0xbfb8aa3b, v0
	v_exp_f32_e32 v18, v8
	v_lshlrev_b64 v[8:9], 12, v[4:5]
	v_lshl_add_u64 v[8:9], s[58:59], 0, v[8:9]
	v_lshlrev_b64 v[4:5], 11, v[4:5]
	v_add_f32_e32 v16, 1.0, v18
	v_rcp_f32_e32 v18, v16
	v_lshl_add_u64 v[16:17], v[8:9], 0, v[110:111]
	v_lshl_add_u64 v[4:5], s[60:61], 0, v[4:5]
	v_lshl_add_u64 v[8:9], v[8:9], 0, v[112:113]
	v_mul_f32_e32 v0, v18, v0
	v_mul_f32_e32 v0, v1, v0
	v_cvt_pk_bf16_f32 v0, v0, s0
	global_store_short v[12:13], v0, off offset:1536
	v_mov_b32_e32 v0, v14
	v_mov_b32_e32 v1, v10
	v_mov_b32_e32 v12, v15
	v_mov_b32_e32 v13, v11
	v_mov_b32_e32 v18, v6
	v_pk_mul_f32 v[0:1], v[0:1], v[0:1]
	v_pk_mul_f32 v[12:13], v[12:13], v[12:13]
	v_pk_mul_f32 v[18:19], v[18:19], v[18:19]
	v_mov_b32_e32 v24, v12
	v_mov_b32_e32 v25, v0
	v_mov_b32_e32 v0, v13
	v_mov_b32_e32 v12, v22
	v_mov_b32_e32 v13, v18
	v_pk_add_f32 v[0:1], v[24:25], v[0:1]
	v_mov_b32_e32 v18, v23
	v_pk_add_f32 v[0:1], v[0:1], v[12:13]
	s_nop 0
	v_pk_add_f32 v[0:1], v[0:1], v[18:19]
	ds_swizzle_b32 v13, v1 offset:swizzle(SWAP,1)
	ds_swizzle_b32 v12, v0 offset:swizzle(SWAP,1)
	s_waitcnt lgkmcnt(0)
	v_pk_add_f32 v[0:1], v[0:1], v[12:13]
	ds_swizzle_b32 v13, v1 offset:swizzle(SWAP,2)
	ds_swizzle_b32 v12, v0 offset:swizzle(SWAP,2)
	s_waitcnt lgkmcnt(0)
	v_pk_add_f32 v[0:1], v[0:1], v[12:13]
	ds_swizzle_b32 v13, v1 offset:swizzle(SWAP,4)
	ds_swizzle_b32 v12, v0 offset:swizzle(SWAP,4)
	s_waitcnt lgkmcnt(0)
	v_pk_add_f32 v[0:1], v[0:1], v[12:13]
	ds_swizzle_b32 v13, v1 offset:swizzle(SWAP,8)
	ds_swizzle_b32 v12, v0 offset:swizzle(SWAP,8)
	s_waitcnt lgkmcnt(0)
	v_pk_add_f32 v[0:1], v[0:1], v[12:13]
	s_nop 0
	v_pk_fma_f32 v[0:1], v[0:1], s[6:7], v[116:117] op_sel_hi:[1,0,0]
	s_mov_b64 s[6:7], 0
	v_mul_f32_e32 v12, 0x4b800000, v1
	v_cmp_gt_f32_e32 vcc, s96, v1
	s_waitcnt vmcnt(39)
; __device__ __forceinline__ unsigned cvtpk(float lo, float hi) { f32x2_t v = {lo, hi}; bf16x2_t b = __builtin_convertvector(v, bf16x2_t); return __builtin_bit_cast(unsigned, b); }
; template <int X> __device__ __forceinline__ float swz_xor(float v) { return __int_as_float(__builtin_amdgcn_ds_swizzle(__float_as_int(v), (X << 10) | 0x1F)); }
; __device__ __forceinline__ float silu_f(float g) { return g * __builtin_amdgcn_rcpf(1.0f + __expf(-g)); }
; template <bool GLA>
; __device__ __forceinline__ void chunk_pass_c(const ChunkIn& ci, const float* wgl, int unit, unsigned char* wl, int lane, const float* Sb, const float* ng, bf16_t* omix) {
;     ...
; #pragma unroll
;         for (int r = 0; r < 4; ++r) {
;             ss[r] += swz_xor<1>(ss[r]); ss[r] += swz_xor<2>(ss[r]); ss[r] += swz_xor<4>(ss[r]); ss[r] += swz_xor<8>(ss[r]);
;             const float rs = rsqrtf(ss[r] * (1.0f / 64.0f) + EPS);
;             const int t = t0 + 16 * it + 4 * kq + r;
; #pragma unroll
;             for (int et = 0; et < 4; ++et) {
;                 const int e = 16 * et + row;
;                 const float gt = __uint_as_float((unsigned)ci.proj[(size_t)t * DINP + gcol + e] << 16);
;                 const float val = o[et][r] * rs * gn[et] * pg8::silu_f(gt);
;                 omix[(size_t)t * 1024 + ocol + e] = (bf16_t)(cvtpk(val, 0.f) & 0xffffu);
;             }
;         }
;     }
;     __builtin_amdgcn_s_waitcnt(0); asm volatile("" ::: "memory");
	v_mov_b32_e32 v21, v202
	v_lshlrev_b32_e32 v18, 16, v21
	v_cndmask_b32_e32 v1, v1, v12, vcc
	v_mul_f32_e32 v12, 0xbfb8aa3b, v18
	v_exp_f32_e32 v19, v12
	v_rsq_f32_e32 v1, v1
	v_lshl_add_u64 v[12:13], v[4:5], 0, v[110:111]
	v_lshl_add_u64 v[4:5], v[4:5], 0, v[112:113]
	v_add_f32_e32 v19, 1.0, v19
	v_rcp_f32_e32 v19, v19
	v_mul_f32_e32 v21, 0x45800000, v1
	v_cndmask_b32_e32 v1, v1, v21, vcc
	v_mul_f32_e32 v14, v14, v1
	v_mul_f32_e32 v14, v115, v14
	v_mul_f32_e32 v18, v19, v18
	v_mul_f32_e32 v14, v18, v14
	v_cvt_pk_bf16_f32 v14, v14, s0
	global_store_short v[12:13], v14, off offset:1536
	v_mul_f32_e32 v10, v10, v1
	v_mul_f32_e32 v10, v161, v10
	v_mul_f32_e32 v6, v6, v1
	v_mul_f32_e32 v6, v160, v6
	v_mul_f32_e32 v1, v2, v1
	v_mul_f32_e32 v1, v159, v1
	v_cmp_gt_f32_e32 vcc, s96, v0
	s_waitcnt vmcnt(38)
	v_mov_b32_e32 v14, v203
	v_lshlrev_b32_e32 v14, 16, v14
	v_mul_f32_e32 v18, 0xbfb8aa3b, v14
	v_exp_f32_e32 v18, v18
	s_nop 0
	v_add_f32_e32 v18, 1.0, v18
	v_rcp_f32_e32 v18, v18
	s_nop 0
	v_mul_f32_e32 v14, v18, v14
	v_mul_f32_e32 v10, v10, v14
	v_cvt_pk_bf16_f32 v10, v10, s0
	global_store_short v[12:13], v10, off offset:1568
	s_waitcnt vmcnt(37)
	v_mov_b32_e32 v10, v204
	v_lshlrev_b32_e32 v10, 16, v10
	v_mul_f32_e32 v14, 0xbfb8aa3b, v10
	v_exp_f32_e32 v14, v14
	s_nop 0
	v_add_f32_e32 v14, 1.0, v14
	v_rcp_f32_e32 v14, v14
	s_nop 0
	v_mul_f32_e32 v10, v14, v10
	v_mul_f32_e32 v6, v6, v10
	v_cvt_pk_bf16_f32 v6, v6, s0
	global_store_short v[12:13], v6, off offset:1600
	v_mov_b32_e32 v9, v211
	v_or_b32_e32 v8, 3, v20
	v_lshlrev_b64 v[12:13], 12, v[8:9]
	v_lshl_add_u64 v[12:13], s[58:59], 0, v[12:13]
	v_lshl_add_u64 v[16:17], v[12:13], 0, v[110:111]
	s_waitcnt vmcnt(36)
	v_mov_b32_e32 v6, v205
	v_lshlrev_b32_e32 v6, 16, v6
	v_mul_f32_e32 v10, 0xbfb8aa3b, v6
	v_exp_f32_e32 v10, v10
	s_nop 0
	v_add_f32_e32 v10, 1.0, v10
	v_rcp_f32_e32 v10, v10
	s_nop 0
	v_mul_f32_e32 v2, v10, v6
	v_mul_f32_e32 v1, v1, v2
	v_cvt_pk_bf16_f32 v1, v1, s0
	global_store_short v[4:5], v1, off offset:1536
	v_mul_f32_e32 v2, 0x4b800000, v0
	v_cndmask_b32_e32 v0, v0, v2, vcc
	v_rsq_f32_e32 v2, v0
	v_lshlrev_b64 v[4:5], 11, v[8:9]
	v_mul_f32_e32 v9, 0x45800000, v2
	v_cndmask_b32_e32 v2, v2, v9, vcc
	v_mul_f32_e32 v9, v15, v2
	v_mul_f32_e32 v9, v115, v9
	v_mul_f32_e32 v7, v7, v2
	v_mul_f32_e32 v7, v160, v7
	s_waitcnt vmcnt(35)
	v_mov_b32_e32 v1, v206
	v_lshlrev_b32_e32 v6, 16, v1
	v_mul_f32_e32 v0, 0xbfb8aa3b, v6
	v_exp_f32_e32 v8, v0
	v_lshl_add_u64 v[0:1], s[60:61], 0, v[4:5]
	v_lshl_add_u64 v[4:5], v[0:1], 0, v[110:111]
	v_lshl_add_u64 v[0:1], v[0:1], 0, v[112:113]
	v_add_f32_e32 v8, 1.0, v8
	v_rcp_f32_e32 v8, v8
	s_nop 0
	v_mul_f32_e32 v6, v8, v6
	v_mul_f32_e32 v6, v6, v9
	v_cvt_pk_bf16_f32 v6, v6, s0
	global_store_short v[4:5], v6, off offset:1536
	v_mul_f32_e32 v9, v11, v2
	v_mul_f32_e32 v9, v161, v9
	v_mul_f32_e32 v2, v3, v2
	v_mul_f32_e32 v2, v159, v2
	s_waitcnt vmcnt(34)
	v_mov_b32_e32 v6, v207
	v_lshlrev_b32_e32 v6, 16, v6
	v_mul_f32_e32 v8, 0xbfb8aa3b, v6
	v_exp_f32_e32 v8, v8
	s_nop 0
	v_add_f32_e32 v8, 1.0, v8
	v_rcp_f32_e32 v8, v8
	s_nop 0
	v_mul_f32_e32 v6, v8, v6
	v_mul_f32_e32 v6, v9, v6
	v_cvt_pk_bf16_f32 v6, v6, s0
	global_store_short v[4:5], v6, off offset:1568
	s_waitcnt vmcnt(33)
	v_mov_b32_e32 v6, v208
	v_lshlrev_b32_e32 v6, 16, v6
	v_mul_f32_e32 v8, 0xbfb8aa3b, v6
	v_exp_f32_e32 v8, v8
	s_nop 0
	v_add_f32_e32 v8, 1.0, v8
	v_rcp_f32_e32 v10, v8
	v_lshl_add_u64 v[8:9], v[12:13], 0, v[112:113]
	v_mul_f32_e32 v6, v10, v6
	v_mul_f32_e32 v6, v7, v6
	v_cvt_pk_bf16_f32 v6, v6, s0
	global_store_short v[4:5], v6, off offset:1600
	s_waitcnt vmcnt(32)
	v_mov_b32_e32 v4, v209
	v_lshlrev_b32_e32 v4, 16, v4
	v_mul_f32_e32 v5, 0xbfb8aa3b, v4
	v_exp_f32_e32 v5, v5
	s_nop 0
	v_add_f32_e32 v5, 1.0, v5
	v_rcp_f32_e32 v5, v5
	s_nop 0
	v_mul_f32_e32 v3, v5, v4
	v_mul_f32_e32 v2, v2, v3
	v_cvt_pk_bf16_f32 v2, v2, s0
	global_store_short v[0:1], v2, off offset:1536
	s_waitcnt lgkmcnt(0)
